# final-norm loop: hoist loop-invariant gain loads out of the row loop, no per-chunk waits; retout state staging loop fully unrolled with all loads in flight
# speedup vs baseline: 1.0406x; 1.0006x over previous
; __device__ __forceinline__ unsigned short f2bf(float f) { return (unsigned short)(cvt_pk_bf16(f, 0.f) & 0xffffu); }
; __device__ __forceinline__ void retout_item(PRef p, int layer, int item, unsigned char* shm) {
;     ...
;     { const float* SF = (const float*)(p.ws + O_RETST) + ((size_t)((b * 8 + h) * 2 + 0) * 34 + cidx) * 8192;
;       const float* SB = (const float*)(p.ws + O_RETST) + ((size_t)((b * 8 + h) * 2 + 1) * 34 + cidx) * 8192;
; #pragma unroll 4
;       for (int i = 0; i < 16; ++i) { const int idx = tid + 512 * i, d = idx >> 7, e = idx & 127;
;           sTf[e * 72 + d] = f2bf(SF[idx]); sTb[e * 72 + d] = f2bf(SB[idx]); } }
.LBB0_408:
	v_add_u32_e32 v3, s12, v8
	v_add_co_u32_e32 v4, vcc, 0x110000, v0
	v_add_u32_e32 v6, 0x400, v3
	s_nop 0
	v_addc_co_u32_e32 v5, vcc, 0, v1, vcc
	v_add_u32_e32 v14, 0x600, v3
	v_ashrrev_i32_e32 v7, 31, v6
	global_load_dword v9, v[0:1], off
	global_load_dword v10, v[0:1], off offset:2048
	global_load_dword v13, v[4:5], off
	global_load_dword v22, v[4:5], off offset:2048
	v_ashrrev_i32_e32 v15, 31, v14
	v_lshlrev_b64 v[4:5], 2, v[6:7]
	v_lshlrev_b64 v[16:17], 2, v[14:15]
	v_lshl_add_u64 v[18:19], s[4:5], 0, v[4:5]
	v_lshl_add_u64 v[4:5], s[44:45], 0, v[4:5]
	v_lshl_add_u64 v[20:21], s[4:5], 0, v[16:17]
	v_lshl_add_u64 v[16:17], s[44:45], 0, v[16:17]
	global_load_dword v7, v[18:19], off
	s_nop 0
	global_load_dword v4, v[4:5], off
	s_nop 0
	global_load_dword v5, v[20:21], off
	global_load_dword v15, v[16:17], off
	v_ashrrev_i32_e32 v16, 7, v3
	v_add_u32_e32 v3, 0x200, v3
	v_add_u32_e32 v16, v16, v2
	v_ashrrev_i32_e32 v3, 7, v3
	v_ashrrev_i32_e32 v6, 7, v6
	v_lshl_add_u32 v16, v16, 1, 0
	v_add_u32_e32 v3, v3, v2
	s_addk_i32 s12, 0x800
	v_ashrrev_i32_e32 v14, 7, v14
	v_add_u32_e32 v6, v6, v2
	v_lshl_add_u32 v3, v3, 1, 0
	v_lshl_add_u64 v[0:1], v[0:1], 0, s[24:25]
	v_add_u32_e32 v14, v14, v2
	v_lshl_add_u32 v6, v6, 1, 0
	v_lshl_add_u32 v14, v14, 1, 0
	v_add_u32_e32 v149, s12, v8
	v_add_co_u32_e32 v150, vcc, 0x110000, v0
	v_add_u32_e32 v152, 0x400, v149
	s_nop 0
	v_addc_co_u32_e32 v151, vcc, 0, v1, vcc
	v_add_u32_e32 v160, 0x600, v149
	v_ashrrev_i32_e32 v153, 31, v152
	global_load_dword v155, v[0:1], off
	global_load_dword v156, v[0:1], off offset:2048
	global_load_dword v159, v[150:151], off
	global_load_dword v168, v[150:151], off offset:2048
	v_ashrrev_i32_e32 v161, 31, v160
	v_lshlrev_b64 v[150:151], 2, v[152:153]
	v_lshlrev_b64 v[162:163], 2, v[160:161]
	v_lshl_add_u64 v[164:165], s[4:5], 0, v[150:151]
	v_lshl_add_u64 v[150:151], s[44:45], 0, v[150:151]
	v_lshl_add_u64 v[166:167], s[4:5], 0, v[162:163]
	v_lshl_add_u64 v[162:163], s[44:45], 0, v[162:163]
	global_load_dword v153, v[164:165], off
	s_nop 0
	global_load_dword v150, v[150:151], off
	s_nop 0
	global_load_dword v151, v[166:167], off
	global_load_dword v161, v[162:163], off
	v_ashrrev_i32_e32 v162, 7, v149
	v_add_u32_e32 v149, 0x200, v149
	v_add_u32_e32 v162, v162, v2
	v_ashrrev_i32_e32 v149, 7, v149
	v_ashrrev_i32_e32 v152, 7, v152
	v_lshl_add_u32 v162, v162, 1, 0
	v_add_u32_e32 v149, v149, v2
	s_addk_i32 s12, 0x800
	v_ashrrev_i32_e32 v160, 7, v160
	v_add_u32_e32 v152, v152, v2
	v_lshl_add_u32 v149, v149, 1, 0
	v_lshl_add_u64 v[0:1], v[0:1], 0, s[24:25]
	v_add_u32_e32 v160, v160, v2
	v_lshl_add_u32 v152, v152, 1, 0
	v_lshl_add_u32 v160, v160, 1, 0
	v_add_u32_e32 v173, s12, v8
	v_add_co_u32_e32 v174, vcc, 0x110000, v0
	v_add_u32_e32 v176, 0x400, v173
	s_nop 0
	v_addc_co_u32_e32 v175, vcc, 0, v1, vcc
	v_add_u32_e32 v184, 0x600, v173
	v_ashrrev_i32_e32 v177, 31, v176
	global_load_dword v179, v[0:1], off
	global_load_dword v180, v[0:1], off offset:2048
	global_load_dword v183, v[174:175], off
	global_load_dword v192, v[174:175], off offset:2048
	v_ashrrev_i32_e32 v185, 31, v184
	v_lshlrev_b64 v[174:175], 2, v[176:177]
	v_lshlrev_b64 v[186:187], 2, v[184:185]
	v_lshl_add_u64 v[188:189], s[4:5], 0, v[174:175]
	v_lshl_add_u64 v[174:175], s[44:45], 0, v[174:175]
	v_lshl_add_u64 v[190:191], s[4:5], 0, v[186:187]
	v_lshl_add_u64 v[186:187], s[44:45], 0, v[186:187]
	global_load_dword v177, v[188:189], off
	s_nop 0
	global_load_dword v174, v[174:175], off
	s_nop 0
	global_load_dword v175, v[190:191], off
	global_load_dword v185, v[186:187], off
	v_ashrrev_i32_e32 v186, 7, v173
	v_add_u32_e32 v173, 0x200, v173
	v_add_u32_e32 v186, v186, v2
	v_ashrrev_i32_e32 v173, 7, v173
	v_ashrrev_i32_e32 v176, 7, v176
	v_lshl_add_u32 v186, v186, 1, 0
	v_add_u32_e32 v173, v173, v2
	s_addk_i32 s12, 0x800
	v_ashrrev_i32_e32 v184, 7, v184
	v_add_u32_e32 v176, v176, v2
	v_lshl_add_u32 v173, v173, 1, 0
	v_lshl_add_u64 v[0:1], v[0:1], 0, s[24:25]
	v_add_u32_e32 v184, v184, v2
	v_lshl_add_u32 v176, v176, 1, 0
	v_lshl_add_u32 v184, v184, 1, 0
	v_add_u32_e32 v197, s12, v8
	v_add_co_u32_e32 v198, vcc, 0x110000, v0
	v_add_u32_e32 v200, 0x400, v197
	s_nop 0
	v_addc_co_u32_e32 v199, vcc, 0, v1, vcc
	v_add_u32_e32 v208, 0x600, v197
	v_ashrrev_i32_e32 v201, 31, v200
	global_load_dword v203, v[0:1], off
	global_load_dword v204, v[0:1], off offset:2048
	global_load_dword v207, v[198:199], off
	global_load_dword v216, v[198:199], off offset:2048
	v_ashrrev_i32_e32 v209, 31, v208
	v_lshlrev_b64 v[198:199], 2, v[200:201]
	v_lshlrev_b64 v[210:211], 2, v[208:209]
	v_lshl_add_u64 v[212:213], s[4:5], 0, v[198:199]
	v_lshl_add_u64 v[198:199], s[44:45], 0, v[198:199]
	v_lshl_add_u64 v[214:215], s[4:5], 0, v[210:211]
	v_lshl_add_u64 v[210:211], s[44:45], 0, v[210:211]
	global_load_dword v201, v[212:213], off
	s_nop 0
	global_load_dword v198, v[198:199], off
	s_nop 0
	global_load_dword v199, v[214:215], off
	global_load_dword v209, v[210:211], off
	v_ashrrev_i32_e32 v210, 7, v197
	v_add_u32_e32 v197, 0x200, v197
	v_add_u32_e32 v210, v210, v2
	v_ashrrev_i32_e32 v197, 7, v197
	v_ashrrev_i32_e32 v200, 7, v200
	v_lshl_add_u32 v210, v210, 1, 0
	v_add_u32_e32 v197, v197, v2
	s_addk_i32 s12, 0x800
	v_ashrrev_i32_e32 v208, 7, v208
	v_add_u32_e32 v200, v200, v2
	v_lshl_add_u32 v197, v197, 1, 0
	v_lshl_add_u64 v[0:1], v[0:1], 0, s[24:25]
	v_add_u32_e32 v208, v208, v2
	v_lshl_add_u32 v200, v200, 1, 0
	v_lshl_add_u32 v208, v208, 1, 0
	s_waitcnt vmcnt(31)
	v_cvt_pk_bf16_f32 v9, v9, v33
	ds_write_b16 v16, v9 offset:34816
	s_waitcnt vmcnt(29)
	v_cvt_pk_bf16_f32 v9, v13, v33
	v_cvt_pk_bf16_f32 v10, v10, v33
	s_waitcnt vmcnt(28)
; __device__ __forceinline__ unsigned short f2bf(float f) { return (unsigned short)(cvt_pk_bf16(f, 0.f) & 0xffffu); }
; __device__ __forceinline__ void retout_item(PRef p, int layer, int item, unsigned char* shm) {
;     ...
;     { const float* SF = (const float*)(p.ws + O_RETST) + ((size_t)((b * 8 + h) * 2 + 0) * 34 + cidx) * 8192;
;       const float* SB = (const float*)(p.ws + O_RETST) + ((size_t)((b * 8 + h) * 2 + 1) * 34 + cidx) * 8192;
; #pragma unroll 4
;       for (int i = 0; i < 16; ++i) { const int idx = tid + 512 * i, d = idx >> 7, e = idx & 127;
;           sTf[e * 72 + d] = f2bf(SF[idx]); sTb[e * 72 + d] = f2bf(SB[idx]); } }
;     __syncthreads();
;     bf16x8 qa[2];
; #pragma unroll
;     for (int kk = 0; kk < 2; ++kk) qa[kk] = *(const bf16x8*)(A + (size_t)(row0 + 16 * wave + fr) * NIN + C_Q + h * 64 + kk * 32 + fq * 8);
; #pragma unroll
;     for (int nt = 0; nt < 8; ++nt) { f32x4 s = (f32x4){0.f, 0.f, 0.f, 0.f};
; #pragma unroll
;         for (int kk = 0; kk < 2; ++kk) { const bf16x8 kb = *(const bf16x8*)(A + (size_t)(row0 + 16 * nt + fr) * NIN + C_K + h * 64 + kk * 32 + fq * 8);
;             s = __builtin_amdgcn_mfma_f32_16x16x32_bf16(qa[kk], kb, s, 0, 0, 0); }
;         const int m = 16 * nt + fr;
; #pragma unroll
;         for (int r = 0; r < 4; ++r) { const int c = 16 * wave + fq * 4 + r; const float dd = (float)(c - m);
;             const float dec = (m <= c) ? expf(dd * lgf) : expf(-dd * lgb);
;             Pw[(fq * 4 + r) * LDK + m] = f2bf(s[r] * 0.125f * dec); } }
	v_cvt_pk_bf16_f32 v13, v22, v33
	ds_write_b16 v16, v9 offset:53248
	ds_write_b16 v3, v10 offset:34816
	ds_write_b16 v3, v13 offset:53248
	s_waitcnt vmcnt(27)
	v_cvt_pk_bf16_f32 v3, v7, v33
	s_waitcnt vmcnt(26)
	v_cvt_pk_bf16_f32 v4, v4, v33
	s_waitcnt vmcnt(25)
	v_cvt_pk_bf16_f32 v5, v5, v33
	s_waitcnt vmcnt(24)
	v_cvt_pk_bf16_f32 v7, v15, v33
	ds_write_b16 v6, v3 offset:34816
	ds_write_b16 v6, v4 offset:53248
	ds_write_b16 v14, v5 offset:34816
	ds_write_b16 v14, v7 offset:53248
	s_waitcnt vmcnt(23)
	v_cvt_pk_bf16_f32 v155, v155, v33
	ds_write_b16 v162, v155 offset:34816
	s_waitcnt vmcnt(21)
	v_cvt_pk_bf16_f32 v155, v159, v33
	v_cvt_pk_bf16_f32 v156, v156, v33
	s_waitcnt vmcnt(20)
	v_cvt_pk_bf16_f32 v159, v168, v33
	ds_write_b16 v162, v155 offset:53248
	ds_write_b16 v149, v156 offset:34816
	ds_write_b16 v149, v159 offset:53248
	s_waitcnt vmcnt(19)
	v_cvt_pk_bf16_f32 v149, v153, v33
	s_waitcnt vmcnt(18)
	v_cvt_pk_bf16_f32 v150, v150, v33
	s_waitcnt vmcnt(17)
	v_cvt_pk_bf16_f32 v151, v151, v33
	s_waitcnt vmcnt(16)
	v_cvt_pk_bf16_f32 v153, v161, v33
	ds_write_b16 v152, v149 offset:34816
	ds_write_b16 v152, v150 offset:53248
	ds_write_b16 v160, v151 offset:34816
	ds_write_b16 v160, v153 offset:53248
	s_waitcnt vmcnt(15)
	v_cvt_pk_bf16_f32 v179, v179, v33
	ds_write_b16 v186, v179 offset:34816
	s_waitcnt vmcnt(13)
	v_cvt_pk_bf16_f32 v179, v183, v33
	v_cvt_pk_bf16_f32 v180, v180, v33
	s_waitcnt vmcnt(12)
	v_cvt_pk_bf16_f32 v183, v192, v33
	ds_write_b16 v186, v179 offset:53248
	ds_write_b16 v173, v180 offset:34816
	ds_write_b16 v173, v183 offset:53248
	s_waitcnt vmcnt(11)
	v_cvt_pk_bf16_f32 v173, v177, v33
	s_waitcnt vmcnt(10)
	v_cvt_pk_bf16_f32 v174, v174, v33
	s_waitcnt vmcnt(9)
	v_cvt_pk_bf16_f32 v175, v175, v33
	s_waitcnt vmcnt(8)
	v_cvt_pk_bf16_f32 v177, v185, v33
	ds_write_b16 v176, v173 offset:34816
	ds_write_b16 v176, v174 offset:53248
	ds_write_b16 v184, v175 offset:34816
	ds_write_b16 v184, v177 offset:53248
	s_waitcnt vmcnt(7)
	v_cvt_pk_bf16_f32 v203, v203, v33
	ds_write_b16 v210, v203 offset:34816
	s_waitcnt vmcnt(5)
	v_cvt_pk_bf16_f32 v203, v207, v33
	v_cvt_pk_bf16_f32 v204, v204, v33
	s_waitcnt vmcnt(4)
	v_cvt_pk_bf16_f32 v207, v216, v33
	ds_write_b16 v210, v203 offset:53248
	ds_write_b16 v197, v204 offset:34816
	ds_write_b16 v197, v207 offset:53248
	s_waitcnt vmcnt(3)
	v_cvt_pk_bf16_f32 v197, v201, v33
	s_waitcnt vmcnt(2)
	v_cvt_pk_bf16_f32 v198, v198, v33
	s_waitcnt vmcnt(1)
	v_cvt_pk_bf16_f32 v199, v199, v33
	s_waitcnt vmcnt(0)
	v_cvt_pk_bf16_f32 v201, v209, v33
	ds_write_b16 v200, v197 offset:34816
	ds_write_b16 v200, v198 offset:53248
	ds_write_b16 v208, v199 offset:34816
	ds_write_b16 v208, v201 offset:53248
	v_ashrrev_i32_e32 v10, 2, v8
	v_and_b32_e32 v9, 15, v8
	v_and_b32_e32 v14, -16, v10
	v_add_u32_e32 v15, s46, v9
	v_add_u32_e32 v0, v15, v14
	v_mov_b64_e32 v[36:37], s[16:17]
	v_bfe_u32 v13, v8, 4, 2
	v_mad_i64_i32 v[0:1], s[4:5], v0, s37, v[36:37]
	s_mov_b32 s3, s23
	v_lshl_add_u64 v[0:1], v[0:1], 0, s[2:3]
	v_lshlrev_b32_e32 v32, 4, v13
	v_lshl_add_u64 v[0:1], v[0:1], 0, v[32:33]
	s_waitcnt lgkmcnt(0)
	s_barrier
	global_load_dwordx4 v[4:7], v[0:1], off offset:3072
	v_mad_u64_u32 v[2:3], s[4:5], v15, s37, v[36:37]
	v_lshl_add_u64 v[2:3], v[2:3], 0, s[2:3]
	v_lshl_add_u64 v[16:17], v[2:3], 0, v[32:33]
	v_add_co_u32_e32 v2, vcc, s39, v16
	v_mul_lo_u32 v30, v14, s38
	s_nop 0
	v_addc_co_u32_e32 v3, vcc, 0, v17, vcc
	global_load_dwordx4 v[20:23], v[2:3], off
	s_nop 0
	global_load_dwordx4 v[0:3], v[0:1], off offset:3136
	v_lshl_add_u64 v[16:17], v[16:17], 0, s[26:27]
	global_load_dwordx4 v[24:27], v[16:17], off offset:64
	v_mul_f32_e32 v16, 0x3fb8aa3b, v11
	v_mul_f32_e32 v17, 0x3fb8aa3b, v12
	v_rndne_f32_e32 v18, v16
	v_fma_f32 v19, v11, s54, -v16
	v_rndne_f32_e32 v28, v17
	v_fma_f32 v29, v12, s54, -v17
	v_sub_f32_e32 v31, v16, v18
	v_fmac_f32_e32 v19, 0x32a5705f, v11
	v_sub_f32_e32 v17, v17, v28
	v_fmac_f32_e32 v29, 0x32a5705f, v12
	v_add_f32_e32 v19, v31, v19
	v_cvt_i32_f32_e32 v35, v18
	v_add_f32_e32 v17, v17, v29
	v_exp_f32_e32 v19, v19
	v_cvt_i32_f32_e32 v40, v28
	v_exp_f32_e32 v17, v17
	v_lshl_or_b32 v16, v13, 2, v14
	v_ldexp_f32 v19, v19, v35
	v_cmp_ngt_f32_e32 vcc, s55, v11
	v_add_u32_e32 v14, s57, v30
	v_sub_u32_e32 v30, v16, v9
	v_ldexp_f32 v17, v17, v40
	v_cndmask_b32_e32 v19, 0, v19, vcc
	v_cmp_ngt_f32_e32 vcc, s55, v12
	v_cvt_f32_i32_e32 v30, v30
	v_add_u32_e32 v28, 16, v15
	v_cndmask_b32_e32 v17, 0, v17, vcc
	v_cmp_nlt_f32_e32 vcc, s56, v11
	v_mad_u64_u32 v[28:29], s[4:5], v28, s37, v[36:37]
	s_nop 0
	v_cndmask_b32_e32 v11, v51, v19, vcc
	v_cmp_nlt_f32_e32 vcc, s56, v12
	v_lshl_add_u64 v[28:29], v[28:29], 0, s[2:3]
	v_lshl_add_u64 v[38:39], v[28:29], 0, v[32:33]
	v_cndmask_b32_e32 v12, v51, v17, vcc
	v_cmp_lt_i32_e32 vcc, v16, v9
	v_or_b32_e32 v18, 1, v16
	v_sub_u32_e32 v31, v18, v9
	v_cndmask_b32_e64 v17, -v12, v11, vcc
	v_mul_f32_e32 v17, v17, v30
	v_mul_f32_e32 v19, 0x3fb8aa3b, v17
	v_fma_f32 v28, v17, s54, -v19
	v_rndne_f32_e32 v29, v19
	v_fmac_f32_e32 v28, 0x32a5705f, v17
	v_sub_f32_e32 v19, v19, v29
	v_add_f32_e32 v19, v19, v28
	v_add_co_u32_e32 v28, vcc, s39, v38
	v_cvt_i32_f32_e32 v35, v29
	s_nop 0
	v_addc_co_u32_e32 v29, vcc, 0, v39, vcc
	v_cvt_f32_i32_e32 v41, v31
	global_load_dwordx4 v[28:31], v[28:29], off
	v_lshl_add_u64 v[38:39], v[38:39], 0, s[26:27]
	v_exp_f32_e32 v19, v19
	v_cmp_ngt_f32_e32 vcc, s55, v17
	v_lshlrev_b32_e32 v34, 1, v9
	v_mad_u32_u24 v63, v9, s38, v52
	v_ldexp_f32 v19, v19, v35
	v_cndmask_b32_e32 v19, 0, v19, vcc
	v_cmp_nlt_f32_e32 vcc, s56, v17
	s_waitcnt vmcnt(3)
	v_mfma_f32_16x16x32_bf16 v[20:23], v[4:7], v[20:23], 0
	v_cndmask_b32_e32 v17, v51, v19, vcc
	v_cmp_lt_i32_e32 vcc, v18, v9
	v_bitop3_b32 v103, v9, s59, v58 bitop3:0xc8
	s_waitcnt vmcnt(1)
; __device__ __forceinline__ unsigned short f2bf(float f) { return (unsigned short)(cvt_pk_bf16(f, 0.f) & 0xffffu); }
; __device__ __forceinline__ void retout_item(PRef p, int layer, int item, unsigned char* shm) {
;     ...
;     for (int nt = 0; nt < 8; ++nt) { f32x4 s = (f32x4){0.f, 0.f, 0.f, 0.f};
; #pragma unroll
;         for (int kk = 0; kk < 2; ++kk) { const bf16x8 kb = *(const bf16x8*)(A + (size_t)(row0 + 16 * nt + fr) * NIN + C_K + h * 64 + kk * 32 + fq * 8);
;             s = __builtin_amdgcn_mfma_f32_16x16x32_bf16(qa[kk], kb, s, 0, 0, 0); }
;         const int m = 16 * nt + fr;
; #pragma unroll
;         for (int r = 0; r < 4; ++r) { const int c = 16 * wave + fq * 4 + r; const float dd = (float)(c - m);
;             const float dec = (m <= c) ? expf(dd * lgf) : expf(-dd * lgb);
;             Pw[(fq * 4 + r) * LDK + m] = f2bf(s[r] * 0.125f * dec); } }
	v_mfma_f32_16x16x32_bf16 v[20:23], v[0:3], v[24:27], v[20:23]
	global_load_dwordx4 v[24:27], v[38:39], off offset:64
	v_cndmask_b32_e64 v19, -v12, v11, vcc
	v_mul_f32_e32 v19, v19, v41
	v_mul_f32_e32 v35, 0x3fb8aa3b, v19
	v_fma_f32 v40, v19, s54, -v35
	s_nop 2
	v_mul_f32_e32 v20, 0x3e000000, v20
	v_mul_f32_e32 v17, v17, v20
	v_cvt_pk_bf16_f32 v20, v17, v33
	v_rndne_f32_e32 v17, v35
	v_fmac_f32_e32 v40, 0x32a5705f, v19
	v_sub_f32_e32 v35, v35, v17
	v_add_f32_e32 v35, v35, v40
	v_exp_f32_e32 v35, v35
	v_cvt_i32_f32_e32 v38, v17
	v_mul_u32_u24_e32 v17, 0x440, v13
	v_add3_u32 v17, v14, v34, v17
	ds_write_b16 v17, v20
	v_ldexp_f32 v20, v35, v38
	v_cmp_ngt_f32_e32 vcc, s55, v19
	v_mul_f32_e32 v21, 0x3e000000, v21
	v_mul_f32_e32 v22, 0x3e000000, v22
	v_cndmask_b32_e32 v20, 0, v20, vcc
	v_cmp_nlt_f32_e32 vcc, s56, v19
	s_waitcnt vmcnt(1)
	v_mfma_f32_16x16x32_bf16 v[28:31], v[4:7], v[28:31], 0
	v_cndmask_b32_e32 v19, v51, v20, vcc
	v_or_b32_e32 v20, 2, v16
	v_sub_u32_e32 v35, v20, v9
	v_cvt_f32_i32_e32 v35, v35
	v_cmp_lt_i32_e32 vcc, v20, v9
	v_mul_f32_e32 v19, v19, v21
	v_cvt_pk_bf16_f32 v19, v19, v33
	ds_write_b16 v17, v19 offset:272
	v_cndmask_b32_e64 v38, -v12, v11, vcc
	v_mul_f32_e32 v35, v38, v35
	v_mul_f32_e32 v38, 0x3fb8aa3b, v35
	v_fma_f32 v39, v35, s54, -v38
	v_rndne_f32_e32 v40, v38
	v_fmac_f32_e32 v39, 0x32a5705f, v35
	v_sub_f32_e32 v38, v38, v40
	v_add_f32_e32 v38, v38, v39
	v_exp_f32_e32 v38, v38
	v_cvt_i32_f32_e32 v39, v40
	v_cmp_ngt_f32_e32 vcc, s55, v35
	v_lshlrev_b32_e32 v13, 3, v13
	v_bitop3_b32 v105, v9, s13, v60 bitop3:0xc8
	v_ldexp_f32 v19, v38, v39
	v_cndmask_b32_e32 v19, 0, v19, vcc
	v_cmp_nlt_f32_e32 vcc, s56, v35
	v_add_u32_e32 v88, v13, v103
	v_add_u32_e32 v92, v13, v105
	v_cndmask_b32_e32 v21, v51, v19, vcc
	v_or_b32_e32 v19, 3, v16
	v_sub_u32_e32 v35, v19, v9
	v_cvt_f32_i32_e32 v35, v35
	v_cmp_lt_i32_e32 vcc, v19, v9
	v_mul_f32_e32 v21, v21, v22
	v_cvt_pk_bf16_f32 v21, v21, v33
	ds_write_b16 v17, v21 offset:544
	v_cndmask_b32_e64 v38, -v12, v11, vcc
	v_mul_f32_e32 v35, v38, v35
	v_mul_f32_e32 v38, 0x3fb8aa3b, v35
	v_fma_f32 v39, v35, s54, -v38
	v_rndne_f32_e32 v40, v38
	v_fmac_f32_e32 v39, 0x32a5705f, v35
	v_sub_f32_e32 v38, v38, v40
	v_add_f32_e32 v38, v38, v39
	v_exp_f32_e32 v38, v38
	v_cvt_i32_f32_e32 v39, v40
	v_cmp_ngt_f32_e32 vcc, s55, v35
	v_mul_f32_e32 v22, 0x3e000000, v23
	v_bitop3_b32 v97, v9, 56, 48 bitop3:0xc8
	v_ldexp_f32 v21, v38, v39
	v_cndmask_b32_e32 v21, 0, v21, vcc
	v_cmp_nlt_f32_e32 vcc, s56, v35
	v_or_b32_e32 v35, 16, v9
	v_bitop3_b32 v99, v9, s52, 64 bitop3:0xc8
	v_cndmask_b32_e32 v21, v51, v21, vcc
	v_mul_f32_e32 v21, v21, v22
	v_sub_u32_e32 v22, v16, v35
	v_cvt_f32_i32_e32 v22, v22
	v_cmp_lt_i32_e32 vcc, v16, v35
	v_cvt_pk_bf16_f32 v21, v21, v33
	ds_write_b16 v17, v21 offset:816
	v_bitop3_b32 v101, v9, s58, v56 bitop3:0xc8
	v_cndmask_b32_e64 v23, -v12, v11, vcc
	v_mul_f32_e32 v38, v23, v22
	v_mul_f32_e32 v22, 0x3fb8aa3b, v38
	v_fma_f32 v23, v38, s54, -v22
	v_rndne_f32_e32 v39, v22
	v_fmac_f32_e32 v23, 0x32a5705f, v38
	v_sub_f32_e32 v22, v22, v39
	v_add_f32_e32 v22, v22, v23
	v_exp_f32_e32 v40, v22
	s_waitcnt vmcnt(0)
	v_mfma_f32_16x16x32_bf16 v[22:25], v[0:3], v[24:27], v[28:31]
	v_add_u32_e32 v26, 32, v15
	v_mad_u64_u32 v[26:27], s[4:5], v26, s37, v[36:37]
	v_lshl_add_u64 v[26:27], v[26:27], 0, s[2:3]
	v_lshl_add_u64 v[30:31], v[26:27], 0, v[32:33]
	v_add_co_u32_e32 v26, vcc, s39, v30
	v_cvt_i32_f32_e32 v39, v39
	s_nop 0
	v_addc_co_u32_e32 v27, vcc, 0, v31, vcc
	global_load_dwordx4 v[26:29], v[26:27], off
	v_ldexp_f32 v21, v40, v39
	v_cmp_ngt_f32_e32 vcc, s55, v38
	v_mul_f32_e32 v22, 0x3e000000, v22
	v_lshl_add_u64 v[30:31], v[30:31], 0, s[26:27]
	v_cndmask_b32_e32 v21, 0, v21, vcc
	v_cmp_nlt_f32_e32 vcc, s56, v38
	v_mul_f32_e32 v23, 0x3e000000, v23
	v_and_b32_e32 v88, 0x78, v88
	v_cndmask_b32_e32 v21, v51, v21, vcc
	v_mul_f32_e32 v21, v21, v22
	v_sub_u32_e32 v22, v18, v35
	v_cvt_f32_i32_e32 v22, v22
	v_cmp_lt_i32_e32 vcc, v18, v35
	v_cvt_pk_bf16_f32 v21, v21, v33
	ds_write_b16 v17, v21 offset:32
	v_and_b32_e32 v92, 0x78, v92
	v_cndmask_b32_e64 v38, -v12, v11, vcc
	v_mul_f32_e32 v22, v38, v22
	v_mul_f32_e32 v38, 0x3fb8aa3b, v22
	v_fma_f32 v39, v22, s54, -v38
	v_rndne_f32_e32 v40, v38
	v_fmac_f32_e32 v39, 0x32a5705f, v22
	v_sub_f32_e32 v38, v38, v40
	v_add_f32_e32 v38, v38, v39
	v_exp_f32_e32 v42, v38
	v_cvt_i32_f32_e32 v43, v40
	global_load_dwordx4 v[38:41], v[30:31], off offset:64
	v_cmp_ngt_f32_e32 vcc, s55, v22
	v_mad_u32_u24 v96, v9, s38, v53
	v_ldexp_f32 v21, v42, v43
	v_cndmask_b32_e32 v21, 0, v21, vcc
	v_cmp_nlt_f32_e32 vcc, s56, v22
	v_sub_u32_e32 v22, v20, v35
	v_cvt_f32_i32_e32 v22, v22
	v_cndmask_b32_e32 v21, v51, v21, vcc
	v_cmp_lt_i32_e32 vcc, v20, v35
	v_mul_f32_e32 v21, v21, v23
	v_cvt_pk_bf16_f32 v21, v21, v33
	ds_write_b16 v17, v21 offset:304
	v_cndmask_b32_e64 v30, -v12, v11, vcc
	v_mul_f32_e32 v22, v30, v22
	v_mul_f32_e32 v30, 0x3fb8aa3b, v22
	v_fma_f32 v31, v22, s54, -v30
	v_rndne_f32_e32 v42, v30
	v_fmac_f32_e32 v31, 0x32a5705f, v22
	v_sub_f32_e32 v30, v30, v42
	v_add_f32_e32 v30, v30, v31
	v_exp_f32_e32 v30, v30
	v_cvt_i32_f32_e32 v31, v42
	v_cmp_ngt_f32_e32 vcc, s55, v22
	v_mul_f32_e32 v23, 0x3e000000, v24
	v_lshlrev_b32_e32 v72, 1, v97
	v_ldexp_f32 v21, v30, v31
	v_cndmask_b32_e32 v21, 0, v21, vcc
	v_cmp_nlt_f32_e32 vcc, s56, v22
	v_sub_u32_e32 v22, v19, v35
	v_cvt_f32_i32_e32 v22, v22
	v_cndmask_b32_e32 v21, v51, v21, vcc
	v_cmp_lt_i32_e32 vcc, v19, v35
	v_mul_f32_e32 v21, v21, v23
	v_cvt_pk_bf16_f32 v21, v21, v33
	ds_write_b16 v17, v21 offset:576
	v_cndmask_b32_e64 v24, -v12, v11, vcc
	v_mul_f32_e32 v22, v24, v22
	v_mul_f32_e32 v24, 0x3fb8aa3b, v22
	v_fma_f32 v30, v22, s54, -v24
	v_rndne_f32_e32 v31, v24
	v_fmac_f32_e32 v30, 0x32a5705f, v22
	v_sub_f32_e32 v24, v24, v31
	v_add_f32_e32 v24, v24, v30
	v_exp_f32_e32 v24, v24
	v_cvt_i32_f32_e32 v30, v31
	v_cmp_ngt_f32_e32 vcc, s55, v22
	v_mad_u32_u24 v98, v9, s38, v54
	v_lshlrev_b32_e32 v80, 1, v99
	v_ldexp_f32 v21, v24, v30
	v_cndmask_b32_e32 v21, 0, v21, vcc
	v_cmp_nlt_f32_e32 vcc, s56, v22
	v_mul_f32_e32 v22, 0x3e000000, v25
	v_mad_u32_u24 v100, v9, s38, v55
	v_cndmask_b32_e32 v21, v51, v21, vcc
	v_mul_f32_e32 v21, v21, v22
	v_cvt_pk_bf16_f32 v21, v21, v33
	ds_write_b16 v17, v21 offset:848
	v_or_b32_e32 v21, 32, v9
	v_sub_u32_e32 v22, v16, v21
	v_cvt_f32_i32_e32 v30, v22
	v_cmp_lt_i32_e32 vcc, v16, v21
	s_waitcnt vmcnt(1)
; __device__ __forceinline__ unsigned short f2bf(float f) { return (unsigned short)(cvt_pk_bf16(f, 0.f) & 0xffffu); }
; __device__ __forceinline__ void retout_item(PRef p, int layer, int item, unsigned char* shm) {
;     ...
;     for (int nt = 0; nt < 8; ++nt) { f32x4 s = (f32x4){0.f, 0.f, 0.f, 0.f};
; #pragma unroll
;         for (int kk = 0; kk < 2; ++kk) { const bf16x8 kb = *(const bf16x8*)(A + (size_t)(row0 + 16 * nt + fr) * NIN + C_K + h * 64 + kk * 32 + fq * 8);
;             s = __builtin_amdgcn_mfma_f32_16x16x32_bf16(qa[kk], kb, s, 0, 0, 0); }
;         const int m = 16 * nt + fr;
; #pragma unroll
;         for (int r = 0; r < 4; ++r) { const int c = 16 * wave + fq * 4 + r; const float dd = (float)(c - m);
;             const float dec = (m <= c) ? expf(dd * lgf) : expf(-dd * lgb);
;             Pw[(fq * 4 + r) * LDK + m] = f2bf(s[r] * 0.125f * dec); } }
	v_mfma_f32_16x16x32_bf16 v[22:25], v[4:7], v[26:29], 0
	v_lshlrev_b32_e32 v84, 1, v101
	v_cndmask_b32_e64 v26, -v12, v11, vcc
	v_mul_f32_e32 v35, v26, v30
	v_mul_f32_e32 v26, 0x3fb8aa3b, v35
	v_fma_f32 v27, v35, s54, -v26
	v_rndne_f32_e32 v28, v26
	v_fmac_f32_e32 v27, 0x32a5705f, v35
	v_sub_f32_e32 v26, v26, v28
	v_add_f32_e32 v26, v26, v27
	v_exp_f32_e32 v42, v26
	v_add_u32_e32 v26, 48, v15
	v_mad_u64_u32 v[26:27], s[4:5], v26, s37, v[36:37]
	v_lshl_add_u64 v[26:27], v[26:27], 0, s[2:3]
	v_lshl_add_u64 v[30:31], v[26:27], 0, v[32:33]
	v_add_co_u32_e32 v26, vcc, s39, v30
	v_cvt_i32_f32_e32 v43, v28
	s_nop 0
	v_addc_co_u32_e32 v27, vcc, 0, v31, vcc
	global_load_dwordx4 v[26:29], v[26:27], off
	s_waitcnt vmcnt(1)
	v_mfma_f32_16x16x32_bf16 v[22:25], v[0:3], v[38:41], v[22:25]
	v_ldexp_f32 v38, v42, v43
	v_cmp_ngt_f32_e32 vcc, s55, v35
	v_lshl_add_u64 v[30:31], v[30:31], 0, s[26:27]
	v_mad_u32_u24 v102, v9, s38, v57
	v_cndmask_b32_e32 v38, 0, v38, vcc
	v_cmp_nlt_f32_e32 vcc, s56, v35
	s_nop 1
	v_mul_f32_e32 v22, 0x3e000000, v22
	v_mul_f32_e32 v23, 0x3e000000, v23
	v_cndmask_b32_e32 v35, v51, v38, vcc
	v_sub_u32_e32 v38, v18, v21
	v_cvt_f32_i32_e32 v38, v38
	v_cmp_lt_i32_e32 vcc, v18, v21
	v_mul_f32_e32 v22, v35, v22
	v_cvt_pk_bf16_f32 v22, v22, v33
	ds_write_b16 v17, v22 offset:64
	v_cndmask_b32_e64 v39, -v12, v11, vcc
	v_mul_f32_e32 v42, v39, v38
	global_load_dwordx4 v[38:41], v[30:31], off offset:64
	v_mul_f32_e32 v30, 0x3fb8aa3b, v42
	v_fma_f32 v31, v42, s54, -v30
	v_rndne_f32_e32 v43, v30
	v_fmac_f32_e32 v31, 0x32a5705f, v42
	v_sub_f32_e32 v30, v30, v43
	v_add_f32_e32 v30, v30, v31
	v_exp_f32_e32 v30, v30
	v_cvt_i32_f32_e32 v31, v43
	v_cmp_ngt_f32_e32 vcc, s55, v42
	v_mul_f32_e32 v24, 0x3e000000, v24
	v_lshlrev_b32_e32 v88, 1, v88
	v_ldexp_f32 v22, v30, v31
	v_sub_u32_e32 v30, v20, v21
	v_cvt_f32_i32_e32 v30, v30
	v_cndmask_b32_e32 v22, 0, v22, vcc
	v_cmp_nlt_f32_e32 vcc, s56, v42
	v_mad_u32_u24 v104, v9, s38, v59
	v_lshlrev_b32_e32 v92, 1, v92
	v_cndmask_b32_e32 v22, v51, v22, vcc
	v_cmp_lt_i32_e32 vcc, v20, v21
	v_mul_f32_e32 v22, v22, v23
	v_cvt_pk_bf16_f32 v22, v22, v33
	v_sub_u32_e32 v23, v19, v21
	v_cndmask_b32_e64 v31, -v12, v11, vcc
	v_mul_f32_e32 v30, v31, v30
	v_mul_f32_e32 v31, 0x3fb8aa3b, v30
	v_fma_f32 v35, v30, s54, -v31
	v_rndne_f32_e32 v42, v31
	v_fmac_f32_e32 v35, 0x32a5705f, v30
	v_sub_f32_e32 v31, v31, v42
	v_add_f32_e32 v31, v31, v35
	v_exp_f32_e32 v31, v31
	v_cvt_i32_f32_e32 v35, v42
	ds_write_b16 v17, v22 offset:336
	v_cmp_ngt_f32_e32 vcc, s55, v30
	v_cvt_f32_i32_e32 v23, v23
	v_ldexp_f32 v22, v31, v35
	v_cndmask_b32_e32 v22, 0, v22, vcc
	v_cmp_nlt_f32_e32 vcc, s56, v30
	v_or_b32_e32 v35, 48, v9
	v_mad_u32_u24 v106, v9, s38, v61
	v_cndmask_b32_e32 v22, v51, v22, vcc
	v_cmp_lt_i32_e32 vcc, v19, v21
	v_mul_f32_e32 v22, v22, v24
	v_cvt_pk_bf16_f32 v22, v22, v33
	ds_write_b16 v17, v22 offset:608
	v_cndmask_b32_e64 v21, -v12, v11, vcc
	v_mul_f32_e32 v21, v21, v23
	v_mul_f32_e32 v23, 0x3fb8aa3b, v21
	v_fma_f32 v30, v21, s54, -v23
	v_rndne_f32_e32 v31, v23
	v_fmac_f32_e32 v30, 0x32a5705f, v21
	v_sub_f32_e32 v23, v23, v31
	v_add_f32_e32 v23, v23, v30
	v_exp_f32_e32 v23, v23
	v_cvt_i32_f32_e32 v30, v31
	v_cmp_ngt_f32_e32 vcc, s55, v21
	v_add3_u32 v88, 0, v88, v104
	v_add3_u32 v92, 0, v92, v106
	v_ldexp_f32 v22, v23, v30
	v_cndmask_b32_e32 v22, 0, v22, vcc
	v_cmp_nlt_f32_e32 vcc, s56, v21
	s_lshl_b32 s22, s2, 1
	s_nop 0
	v_cndmask_b32_e32 v21, v51, v22, vcc
	v_mul_f32_e32 v22, 0x3e000000, v25
	v_mul_f32_e32 v21, v21, v22
	v_sub_u32_e32 v22, v16, v35
	v_cvt_f32_i32_e32 v30, v22
	v_cmp_lt_i32_e32 vcc, v16, v35
	s_waitcnt vmcnt(1)
	v_mfma_f32_16x16x32_bf16 v[22:25], v[4:7], v[26:29], 0
	v_cvt_pk_bf16_f32 v21, v21, v33
	ds_write_b16 v17, v21 offset:880
	v_cndmask_b32_e64 v26, -v12, v11, vcc
	v_mul_f32_e32 v42, v26, v30
	v_mul_f32_e32 v26, 0x3fb8aa3b, v42
	v_fma_f32 v27, v42, s54, -v26
	v_rndne_f32_e32 v28, v26
	v_fmac_f32_e32 v27, 0x32a5705f, v42
	v_sub_f32_e32 v26, v26, v28
	v_add_f32_e32 v26, v26, v27
	v_exp_f32_e32 v26, v26
	v_cvt_i32_f32_e32 v27, v28
	s_waitcnt vmcnt(0)
	v_mfma_f32_16x16x32_bf16 v[22:25], v[0:3], v[38:41], v[22:25]
	v_ldexp_f32 v21, v26, v27
	v_add_u32_e32 v26, 64, v15
	v_mad_u64_u32 v[26:27], s[4:5], v26, s37, v[36:37]
	v_lshl_add_u64 v[26:27], v[26:27], 0, s[2:3]
	v_lshl_add_u64 v[30:31], v[26:27], 0, v[32:33]
	v_add_co_u32_e32 v26, vcc, s39, v30
	s_nop 1
	v_mul_f32_e32 v22, 0x3e000000, v22
	v_addc_co_u32_e32 v27, vcc, 0, v31, vcc
	global_load_dwordx4 v[26:29], v[26:27], off
	v_cmp_ngt_f32_e32 vcc, s55, v42
	v_lshl_add_u64 v[30:31], v[30:31], 0, s[26:27]
	v_mul_f32_e32 v23, 0x3e000000, v23
	v_cndmask_b32_e32 v21, 0, v21, vcc
	v_cmp_nlt_f32_e32 vcc, s56, v42
	s_nop 1
	v_cndmask_b32_e32 v21, v51, v21, vcc
	v_mul_f32_e32 v21, v21, v22
	v_sub_u32_e32 v22, v18, v35
	v_cvt_f32_i32_e32 v22, v22
	v_cmp_lt_i32_e32 vcc, v18, v35
	v_cvt_pk_bf16_f32 v21, v21, v33
	ds_write_b16 v17, v21 offset:96
	s_nop 0
	v_cndmask_b32_e64 v38, -v12, v11, vcc
	v_mul_f32_e32 v22, v38, v22
	v_mul_f32_e32 v38, 0x3fb8aa3b, v22
	v_fma_f32 v39, v22, s54, -v38
	v_rndne_f32_e32 v40, v38
	v_fmac_f32_e32 v39, 0x32a5705f, v22
	v_sub_f32_e32 v38, v38, v40
	v_add_f32_e32 v38, v38, v39
	v_exp_f32_e32 v42, v38
	v_cvt_i32_f32_e32 v43, v40
	global_load_dwordx4 v[38:41], v[30:31], off offset:64
	v_cmp_ngt_f32_e32 vcc, s55, v22
	v_ldexp_f32 v21, v42, v43
	s_nop 0
	v_cndmask_b32_e32 v21, 0, v21, vcc
	v_cmp_nlt_f32_e32 vcc, s56, v22
	v_sub_u32_e32 v22, v20, v35
	v_cvt_f32_i32_e32 v22, v22
	v_cndmask_b32_e32 v21, v51, v21, vcc
	v_cmp_lt_i32_e32 vcc, v20, v35
	v_mul_f32_e32 v21, v21, v23
	v_cvt_pk_bf16_f32 v21, v21, v33
	ds_write_b16 v17, v21 offset:368
; __device__ __forceinline__ unsigned short f2bf(float f) { return (unsigned short)(cvt_pk_bf16(f, 0.f) & 0xffffu); }
; __device__ __forceinline__ void retout_item(PRef p, int layer, int item, unsigned char* shm) {
;     ...
;     for (int nt = 0; nt < 8; ++nt) { f32x4 s = (f32x4){0.f, 0.f, 0.f, 0.f};
; #pragma unroll
;         for (int kk = 0; kk < 2; ++kk) { const bf16x8 kb = *(const bf16x8*)(A + (size_t)(row0 + 16 * nt + fr) * NIN + C_K + h * 64 + kk * 32 + fq * 8);
;             s = __builtin_amdgcn_mfma_f32_16x16x32_bf16(qa[kk], kb, s, 0, 0, 0); }
;         const int m = 16 * nt + fr;
; #pragma unroll
;         for (int r = 0; r < 4; ++r) { const int c = 16 * wave + fq * 4 + r; const float dd = (float)(c - m);
;             const float dec = (m <= c) ? expf(dd * lgf) : expf(-dd * lgb);
;             Pw[(fq * 4 + r) * LDK + m] = f2bf(s[r] * 0.125f * dec); } }
	v_cndmask_b32_e64 v30, -v12, v11, vcc
	v_mul_f32_e32 v22, v30, v22
	v_mul_f32_e32 v30, 0x3fb8aa3b, v22
	v_fma_f32 v31, v22, s54, -v30
	v_rndne_f32_e32 v42, v30
	v_fmac_f32_e32 v31, 0x32a5705f, v22
	v_sub_f32_e32 v30, v30, v42
	v_add_f32_e32 v30, v30, v31
	v_exp_f32_e32 v30, v30
	v_cvt_i32_f32_e32 v31, v42
	v_cmp_ngt_f32_e32 vcc, s55, v22
	v_mul_f32_e32 v23, 0x3e000000, v24
	v_ldexp_f32 v21, v30, v31
	v_cndmask_b32_e32 v21, 0, v21, vcc
	v_cmp_nlt_f32_e32 vcc, s56, v22
	v_sub_u32_e32 v22, v19, v35
	v_cvt_f32_i32_e32 v22, v22
	v_cndmask_b32_e32 v21, v51, v21, vcc
	v_cmp_lt_i32_e32 vcc, v19, v35
	v_mul_f32_e32 v21, v21, v23
	v_cvt_pk_bf16_f32 v21, v21, v33
	ds_write_b16 v17, v21 offset:640
	v_cndmask_b32_e64 v24, -v12, v11, vcc
	v_mul_f32_e32 v22, v24, v22
	v_mul_f32_e32 v24, 0x3fb8aa3b, v22
	v_fma_f32 v30, v22, s54, -v24
	v_rndne_f32_e32 v31, v24
	v_fmac_f32_e32 v30, 0x32a5705f, v22
	v_sub_f32_e32 v24, v24, v31
	v_add_f32_e32 v24, v24, v30
	v_exp_f32_e32 v24, v24
	v_cvt_i32_f32_e32 v30, v31
	v_cmp_ngt_f32_e32 vcc, s55, v22
	v_ldexp_f32 v21, v24, v30
	s_nop 0
	v_cndmask_b32_e32 v21, 0, v21, vcc
	v_cmp_nlt_f32_e32 vcc, s56, v22
	v_mul_f32_e32 v22, 0x3e000000, v25
	s_nop 0
	v_cndmask_b32_e32 v21, v51, v21, vcc
	v_mul_f32_e32 v21, v21, v22
	v_cvt_pk_bf16_f32 v21, v21, v33
	ds_write_b16 v17, v21 offset:912
	v_or_b32_e32 v21, 64, v9
	v_sub_u32_e32 v22, v16, v21
	v_cvt_f32_i32_e32 v30, v22
	v_cmp_lt_i32_e32 vcc, v16, v21
	s_waitcnt vmcnt(1)
	v_mfma_f32_16x16x32_bf16 v[22:25], v[4:7], v[26:29], 0
	v_cndmask_b32_e64 v26, -v12, v11, vcc
	v_mul_f32_e32 v35, v26, v30
	v_mul_f32_e32 v26, 0x3fb8aa3b, v35
	v_fma_f32 v27, v35, s54, -v26
	v_rndne_f32_e32 v28, v26
	v_fmac_f32_e32 v27, 0x32a5705f, v35
	v_sub_f32_e32 v26, v26, v28
	v_add_f32_e32 v26, v26, v27
	v_exp_f32_e32 v42, v26
	v_add_u32_e32 v26, 0x50, v15
	v_mad_u64_u32 v[26:27], s[4:5], v26, s37, v[36:37]
	v_lshl_add_u64 v[26:27], v[26:27], 0, s[2:3]
	v_lshl_add_u64 v[30:31], v[26:27], 0, v[32:33]
	v_add_co_u32_e32 v26, vcc, s39, v30
	v_cvt_i32_f32_e32 v43, v28
	s_nop 0
	v_addc_co_u32_e32 v27, vcc, 0, v31, vcc
	global_load_dwordx4 v[26:29], v[26:27], off
	s_waitcnt vmcnt(1)
	v_mfma_f32_16x16x32_bf16 v[22:25], v[0:3], v[38:41], v[22:25]
	v_ldexp_f32 v38, v42, v43
	v_cmp_ngt_f32_e32 vcc, s55, v35
	v_lshl_add_u64 v[30:31], v[30:31], 0, s[26:27]
	s_nop 0
	v_cndmask_b32_e32 v38, 0, v38, vcc
	v_cmp_nlt_f32_e32 vcc, s56, v35
	s_nop 1
	v_mul_f32_e32 v22, 0x3e000000, v22
	v_mul_f32_e32 v23, 0x3e000000, v23
	v_cndmask_b32_e32 v35, v51, v38, vcc
	v_sub_u32_e32 v38, v18, v21
	v_cvt_f32_i32_e32 v38, v38
	v_cmp_lt_i32_e32 vcc, v18, v21
	v_mul_f32_e32 v22, v35, v22
	v_cvt_pk_bf16_f32 v22, v22, v33
	ds_write_b16 v17, v22 offset:128
	v_cndmask_b32_e64 v39, -v12, v11, vcc
	v_mul_f32_e32 v42, v39, v38
	global_load_dwordx4 v[38:41], v[30:31], off offset:64
	v_mul_f32_e32 v30, 0x3fb8aa3b, v42
	v_fma_f32 v31, v42, s54, -v30
	v_rndne_f32_e32 v43, v30
	v_fmac_f32_e32 v31, 0x32a5705f, v42
	v_sub_f32_e32 v30, v30, v43
	v_add_f32_e32 v30, v30, v31
	v_exp_f32_e32 v30, v30
	v_cvt_i32_f32_e32 v31, v43
	v_cmp_ngt_f32_e32 vcc, s55, v42
	v_mul_f32_e32 v24, 0x3e000000, v24
	v_ldexp_f32 v22, v30, v31
	v_sub_u32_e32 v30, v20, v21
	v_cvt_f32_i32_e32 v30, v30
	v_cndmask_b32_e32 v22, 0, v22, vcc
	v_cmp_nlt_f32_e32 vcc, s56, v42
	s_nop 1
	v_cndmask_b32_e32 v22, v51, v22, vcc
	v_cmp_lt_i32_e32 vcc, v20, v21
	v_mul_f32_e32 v22, v22, v23
	v_cvt_pk_bf16_f32 v22, v22, v33
	v_sub_u32_e32 v23, v19, v21
	v_cndmask_b32_e64 v31, -v12, v11, vcc
	v_mul_f32_e32 v30, v31, v30
	v_mul_f32_e32 v31, 0x3fb8aa3b, v30
	v_fma_f32 v35, v30, s54, -v31
	v_rndne_f32_e32 v42, v31
	v_fmac_f32_e32 v35, 0x32a5705f, v30
	v_sub_f32_e32 v31, v31, v42
	v_add_f32_e32 v31, v31, v35
	v_exp_f32_e32 v31, v31
	v_cvt_i32_f32_e32 v35, v42
	ds_write_b16 v17, v22 offset:400
	v_cmp_ngt_f32_e32 vcc, s55, v30
	v_cvt_f32_i32_e32 v23, v23
	v_ldexp_f32 v22, v31, v35
	v_cndmask_b32_e32 v22, 0, v22, vcc
	v_cmp_nlt_f32_e32 vcc, s56, v30
	v_or_b32_e32 v35, 0x50, v9
	s_nop 0
	v_cndmask_b32_e32 v22, v51, v22, vcc
	v_cmp_lt_i32_e32 vcc, v19, v21
	v_mul_f32_e32 v22, v22, v24
	v_cvt_pk_bf16_f32 v22, v22, v33
	ds_write_b16 v17, v22 offset:672
	v_cndmask_b32_e64 v21, -v12, v11, vcc
	v_mul_f32_e32 v21, v21, v23
	v_mul_f32_e32 v23, 0x3fb8aa3b, v21
	v_fma_f32 v30, v21, s54, -v23
	v_rndne_f32_e32 v31, v23
	v_fmac_f32_e32 v30, 0x32a5705f, v21
	v_sub_f32_e32 v23, v23, v31
	v_add_f32_e32 v23, v23, v30
	v_exp_f32_e32 v23, v23
	v_cvt_i32_f32_e32 v30, v31
	v_cmp_ngt_f32_e32 vcc, s55, v21
	v_ldexp_f32 v22, v23, v30
	s_nop 0
	v_cndmask_b32_e32 v22, 0, v22, vcc
	v_cmp_nlt_f32_e32 vcc, s56, v21
	s_nop 1
	v_cndmask_b32_e32 v21, v51, v22, vcc
	v_mul_f32_e32 v22, 0x3e000000, v25
	v_mul_f32_e32 v21, v21, v22
	v_sub_u32_e32 v22, v16, v35
	v_cvt_f32_i32_e32 v30, v22
	v_cmp_lt_i32_e32 vcc, v16, v35
	s_waitcnt vmcnt(1)
	v_mfma_f32_16x16x32_bf16 v[22:25], v[4:7], v[26:29], 0
	v_cvt_pk_bf16_f32 v21, v21, v33
	ds_write_b16 v17, v21 offset:944
	v_cndmask_b32_e64 v26, -v12, v11, vcc
	v_mul_f32_e32 v42, v26, v30
	v_mul_f32_e32 v26, 0x3fb8aa3b, v42
	v_fma_f32 v27, v42, s54, -v26
	v_rndne_f32_e32 v28, v26
	v_fmac_f32_e32 v27, 0x32a5705f, v42
	v_sub_f32_e32 v26, v26, v28
	v_add_f32_e32 v26, v26, v27
	v_exp_f32_e32 v26, v26
	v_cvt_i32_f32_e32 v27, v28
	s_waitcnt vmcnt(0)
; __device__ __forceinline__ unsigned short f2bf(float f) { return (unsigned short)(cvt_pk_bf16(f, 0.f) & 0xffffu); }
; __device__ __forceinline__ void retout_item(PRef p, int layer, int item, unsigned char* shm) {
;     ...
;     for (int nt = 0; nt < 8; ++nt) { f32x4 s = (f32x4){0.f, 0.f, 0.f, 0.f};
; #pragma unroll
;         for (int kk = 0; kk < 2; ++kk) { const bf16x8 kb = *(const bf16x8*)(A + (size_t)(row0 + 16 * nt + fr) * NIN + C_K + h * 64 + kk * 32 + fq * 8);
;             s = __builtin_amdgcn_mfma_f32_16x16x32_bf16(qa[kk], kb, s, 0, 0, 0); }
;         const int m = 16 * nt + fr;
; #pragma unroll
;         for (int r = 0; r < 4; ++r) { const int c = 16 * wave + fq * 4 + r; const float dd = (float)(c - m);
;             const float dec = (m <= c) ? expf(dd * lgf) : expf(-dd * lgb);
;             Pw[(fq * 4 + r) * LDK + m] = f2bf(s[r] * 0.125f * dec); } }
	v_mfma_f32_16x16x32_bf16 v[22:25], v[0:3], v[38:41], v[22:25]
	v_ldexp_f32 v21, v26, v27
	v_add_u32_e32 v26, 0x60, v15
	v_mad_u64_u32 v[26:27], s[4:5], v26, s37, v[36:37]
	v_lshl_add_u64 v[26:27], v[26:27], 0, s[2:3]
	v_lshl_add_u64 v[30:31], v[26:27], 0, v[32:33]
	v_add_co_u32_e32 v26, vcc, s39, v30
	s_nop 1
	v_mul_f32_e32 v22, 0x3e000000, v22
	v_addc_co_u32_e32 v27, vcc, 0, v31, vcc
	global_load_dwordx4 v[26:29], v[26:27], off
	v_cmp_ngt_f32_e32 vcc, s55, v42
	v_lshl_add_u64 v[30:31], v[30:31], 0, s[26:27]
	v_mul_f32_e32 v23, 0x3e000000, v23
	v_cndmask_b32_e32 v21, 0, v21, vcc
	v_cmp_nlt_f32_e32 vcc, s56, v42
	v_add_u32_e32 v15, 0x70, v15
	s_nop 0
	v_cndmask_b32_e32 v21, v51, v21, vcc
	v_mul_f32_e32 v21, v21, v22
	v_sub_u32_e32 v22, v18, v35
	v_cvt_f32_i32_e32 v22, v22
	v_cmp_lt_i32_e32 vcc, v18, v35
	v_cvt_pk_bf16_f32 v21, v21, v33
	ds_write_b16 v17, v21 offset:160
	s_nop 0
	v_cndmask_b32_e64 v38, -v12, v11, vcc
	v_mul_f32_e32 v22, v38, v22
	v_mul_f32_e32 v38, 0x3fb8aa3b, v22
	v_fma_f32 v39, v22, s54, -v38
	v_rndne_f32_e32 v40, v38
	v_fmac_f32_e32 v39, 0x32a5705f, v22
	v_sub_f32_e32 v38, v38, v40
	v_add_f32_e32 v38, v38, v39
	v_exp_f32_e32 v42, v38
	v_cvt_i32_f32_e32 v43, v40
	global_load_dwordx4 v[38:41], v[30:31], off offset:64
	v_cmp_ngt_f32_e32 vcc, s55, v22
	v_ldexp_f32 v21, v42, v43
	s_nop 0
	v_cndmask_b32_e32 v21, 0, v21, vcc
	v_cmp_nlt_f32_e32 vcc, s56, v22
	v_sub_u32_e32 v22, v20, v35
	v_cvt_f32_i32_e32 v22, v22
	v_cndmask_b32_e32 v21, v51, v21, vcc
	v_cmp_lt_i32_e32 vcc, v20, v35
	v_mul_f32_e32 v21, v21, v23
	v_cvt_pk_bf16_f32 v21, v21, v33
	ds_write_b16 v17, v21 offset:432
	v_cndmask_b32_e64 v30, -v12, v11, vcc
	v_mul_f32_e32 v22, v30, v22
	v_mul_f32_e32 v30, 0x3fb8aa3b, v22
	v_fma_f32 v31, v22, s54, -v30
	v_rndne_f32_e32 v42, v30
	v_fmac_f32_e32 v31, 0x32a5705f, v22
	v_sub_f32_e32 v30, v30, v42
	v_add_f32_e32 v30, v30, v31
	v_exp_f32_e32 v30, v30
	v_cvt_i32_f32_e32 v31, v42
	v_cmp_ngt_f32_e32 vcc, s55, v22
	v_mul_f32_e32 v23, 0x3e000000, v24
	v_ldexp_f32 v21, v30, v31
	v_cndmask_b32_e32 v21, 0, v21, vcc
	v_cmp_nlt_f32_e32 vcc, s56, v22
	v_sub_u32_e32 v22, v19, v35
	v_cvt_f32_i32_e32 v22, v22
	v_cndmask_b32_e32 v21, v51, v21, vcc
	v_cmp_lt_i32_e32 vcc, v19, v35
	v_mul_f32_e32 v21, v21, v23
	v_cvt_pk_bf16_f32 v21, v21, v33
	ds_write_b16 v17, v21 offset:704
	v_cndmask_b32_e64 v24, -v12, v11, vcc
	v_mul_f32_e32 v22, v24, v22
	v_mul_f32_e32 v24, 0x3fb8aa3b, v22
	v_fma_f32 v30, v22, s54, -v24
	v_rndne_f32_e32 v31, v24
	v_fmac_f32_e32 v30, 0x32a5705f, v22
	v_sub_f32_e32 v24, v24, v31
	v_add_f32_e32 v24, v24, v30
	v_exp_f32_e32 v24, v24
	v_cvt_i32_f32_e32 v30, v31
	v_cmp_ngt_f32_e32 vcc, s55, v22
	v_ldexp_f32 v21, v24, v30
	s_nop 0
	v_cndmask_b32_e32 v21, 0, v21, vcc
	v_cmp_nlt_f32_e32 vcc, s56, v22
	v_mul_f32_e32 v22, 0x3e000000, v25
	s_nop 0
	v_cndmask_b32_e32 v21, v51, v21, vcc
	v_mul_f32_e32 v21, v21, v22
	v_cvt_pk_bf16_f32 v21, v21, v33
	ds_write_b16 v17, v21 offset:976
	v_or_b32_e32 v21, 0x60, v9
	v_sub_u32_e32 v22, v16, v21
	v_cvt_f32_i32_e32 v30, v22
	v_cmp_lt_i32_e32 vcc, v16, v21
	s_waitcnt vmcnt(1)
	v_mfma_f32_16x16x32_bf16 v[22:25], v[4:7], v[26:29], 0
	v_cndmask_b32_e64 v26, -v12, v11, vcc
	v_mul_f32_e32 v35, v26, v30
	v_mul_f32_e32 v26, 0x3fb8aa3b, v35
	v_fma_f32 v27, v35, s54, -v26
	v_rndne_f32_e32 v28, v26
	v_fmac_f32_e32 v27, 0x32a5705f, v35
	v_sub_f32_e32 v26, v26, v28
	v_add_f32_e32 v26, v26, v27
	v_exp_f32_e32 v42, v26
	v_mad_u64_u32 v[26:27], s[4:5], v15, s37, v[36:37]
	v_lshl_add_u64 v[26:27], v[26:27], 0, s[2:3]
	v_lshl_add_u64 v[30:31], v[26:27], 0, v[32:33]
	v_add_co_u32_e32 v26, vcc, s39, v30
	v_cvt_i32_f32_e32 v43, v28
	s_nop 0
	v_addc_co_u32_e32 v27, vcc, 0, v31, vcc
	global_load_dwordx4 v[26:29], v[26:27], off
	v_ldexp_f32 v15, v42, v43
	v_cmp_ngt_f32_e32 vcc, s55, v35
	s_waitcnt vmcnt(1)
	v_mfma_f32_16x16x32_bf16 v[22:25], v[0:3], v[38:41], v[22:25]
	v_lshl_add_u64 v[30:31], v[30:31], 0, s[26:27]
	v_cndmask_b32_e32 v15, 0, v15, vcc
	v_cmp_nlt_f32_e32 vcc, s56, v35
	v_sub_u32_e32 v35, v18, v21
	v_cvt_f32_i32_e32 v35, v35
	v_cndmask_b32_e32 v15, v51, v15, vcc
	v_cmp_lt_i32_e32 vcc, v18, v21
	s_nop 0
	v_mul_f32_e32 v22, 0x3e000000, v22
	v_mul_f32_e32 v15, v15, v22
	v_cndmask_b32_e64 v38, -v12, v11, vcc
	v_mul_f32_e32 v35, v38, v35
	global_load_dwordx4 v[38:41], v[30:31], off offset:64
	v_mul_f32_e32 v30, 0x3fb8aa3b, v35
	v_fma_f32 v31, v35, s54, -v30
	v_rndne_f32_e32 v42, v30
	v_fmac_f32_e32 v31, 0x32a5705f, v35
	v_sub_f32_e32 v30, v30, v42
	v_add_f32_e32 v30, v30, v31
	v_exp_f32_e32 v30, v30
	v_cvt_i32_f32_e32 v31, v42
	v_cvt_pk_bf16_f32 v15, v15, v33
	v_sub_u32_e32 v22, v20, v21
	ds_write_b16 v17, v15 offset:192
	v_ldexp_f32 v15, v30, v31
	v_cmp_ngt_f32_e32 vcc, s55, v35
	v_cvt_f32_i32_e32 v22, v22
	v_mul_f32_e32 v23, 0x3e000000, v23
	v_cndmask_b32_e32 v15, 0, v15, vcc
	v_cmp_nlt_f32_e32 vcc, s56, v35
	s_nop 1
	v_cndmask_b32_e32 v15, v51, v15, vcc
	v_cmp_lt_i32_e32 vcc, v20, v21
	v_mul_f32_e32 v15, v15, v23
	v_cvt_pk_bf16_f32 v15, v15, v33
	ds_write_b16 v17, v15 offset:464
	v_cndmask_b32_e64 v30, -v12, v11, vcc
	v_mul_f32_e32 v22, v30, v22
	v_mul_f32_e32 v30, 0x3fb8aa3b, v22
	v_fma_f32 v31, v22, s54, -v30
	v_rndne_f32_e32 v35, v30
	v_fmac_f32_e32 v31, 0x32a5705f, v22
	v_sub_f32_e32 v30, v30, v35
	v_add_f32_e32 v30, v30, v31
	v_exp_f32_e32 v30, v30
	v_cvt_i32_f32_e32 v31, v35
	v_cmp_ngt_f32_e32 vcc, s55, v22
	v_mul_f32_e32 v23, 0x3e000000, v24
	v_ldexp_f32 v15, v30, v31
	v_cndmask_b32_e32 v15, 0, v15, vcc
	v_cmp_nlt_f32_e32 vcc, s56, v22
	v_sub_u32_e32 v22, v19, v21
	v_cvt_f32_i32_e32 v22, v22
	v_cndmask_b32_e32 v15, v51, v15, vcc
	v_cmp_lt_i32_e32 vcc, v19, v21
	v_mul_f32_e32 v15, v15, v23
	v_cvt_pk_bf16_f32 v15, v15, v33
	ds_write_b16 v17, v15 offset:736
	v_cndmask_b32_e64 v21, -v12, v11, vcc
	v_mul_f32_e32 v21, v21, v22
	v_mul_f32_e32 v22, 0x3fb8aa3b, v21
	v_fma_f32 v24, v21, s54, -v22
	v_rndne_f32_e32 v30, v22
	v_fmac_f32_e32 v24, 0x32a5705f, v21
	v_sub_f32_e32 v22, v22, v30
	v_add_f32_e32 v22, v22, v24
	v_exp_f32_e32 v22, v22
	v_cvt_i32_f32_e32 v24, v30
	v_cmp_ngt_f32_e32 vcc, s55, v21
	v_ldexp_f32 v15, v22, v24
	s_nop 0
	v_cndmask_b32_e32 v15, 0, v15, vcc
	v_cmp_nlt_f32_e32 vcc, s56, v21
	v_mul_f32_e32 v21, 0x3e000000, v25
	s_nop 0
	v_cndmask_b32_e32 v15, v51, v15, vcc
	v_mul_f32_e32 v15, v15, v21
	v_or_b32_e32 v21, 0x70, v9
	v_sub_u32_e32 v22, v16, v21
	v_cvt_f32_i32_e32 v30, v22
	v_cmp_lt_i32_e32 vcc, v16, v21
	s_waitcnt vmcnt(1)
; __device__ __forceinline__ unsigned short f2bf(float f) { return (unsigned short)(cvt_pk_bf16(f, 0.f) & 0xffffu); }
; __device__ __forceinline__ void retout_item(PRef p, int layer, int item, unsigned char* shm) {
;     ...
;         const int m = 16 * nt + fr;
; #pragma unroll
;         for (int r = 0; r < 4; ++r) { const int c = 16 * wave + fq * 4 + r; const float dd = (float)(c - m);
;             const float dec = (m <= c) ? expf(dd * lgf) : expf(-dd * lgb);
;             Pw[(fq * 4 + r) * LDK + m] = f2bf(s[r] * 0.125f * dec); } }
;     __syncthreads();
;     f32x4 acc[8];
; #pragma unroll
;     for (int et = 0; et < 8; ++et) acc[et] = (f32x4){0.f, 0.f, 0.f, 0.f};
; #pragma unroll
;     for (int kk = 0; kk < 4; ++kk) { const bf16x8 af = *(const bf16x8*)(Pw + fr * LDK + kk * 32 + fq * 8);
; #pragma unroll
;         for (int et = 0; et < 8; ++et) { const bf16x8 bf = *(const bf16x8*)(vT + tsw(16 * et + fr, kk * 32 + fq * 8));
;             acc[et] = __builtin_amdgcn_mfma_f32_16x16x32_bf16(af, bf, acc[et], 0, 0, 0); } }
	v_mfma_f32_16x16x32_bf16 v[22:25], v[4:7], v[26:29], 0
	v_cvt_pk_bf16_f32 v15, v15, v33
	ds_write_b16 v17, v15 offset:1008
	v_cndmask_b32_e64 v26, -v12, v11, vcc
	v_mul_f32_e32 v26, v26, v30
	v_mul_f32_e32 v27, 0x3fb8aa3b, v26
	v_fma_f32 v28, v26, s54, -v27
	v_rndne_f32_e32 v29, v27
	v_fmac_f32_e32 v28, 0x32a5705f, v26
	v_sub_f32_e32 v27, v27, v29
	v_add_f32_e32 v27, v27, v28
	v_exp_f32_e32 v27, v27
	v_cvt_i32_f32_e32 v28, v29
	v_cmp_ngt_f32_e32 vcc, s55, v26
	s_waitcnt vmcnt(0)
	v_mfma_f32_16x16x32_bf16 v[22:25], v[0:3], v[38:41], v[22:25]
	v_add_u32_e32 v30, 0, v32
	v_ldexp_f32 v15, v27, v28
	v_cndmask_b32_e32 v15, 0, v15, vcc
	v_cmp_nlt_f32_e32 vcc, s56, v26
	v_sub_u32_e32 v26, v18, v21
	v_cvt_f32_i32_e32 v26, v26
	v_cndmask_b32_e32 v15, v51, v15, vcc
	v_cmp_lt_i32_e32 vcc, v18, v21
	v_mul_f32_e32 v22, 0x3e000000, v22
	v_mul_f32_e32 v15, v15, v22
	v_cndmask_b32_e64 v18, -v12, v11, vcc
	v_mul_f32_e32 v18, v18, v26
	v_mul_f32_e32 v26, 0x3fb8aa3b, v18
	v_fma_f32 v27, v18, s54, -v26
	v_rndne_f32_e32 v28, v26
	v_fmac_f32_e32 v27, 0x32a5705f, v18
	v_sub_f32_e32 v26, v26, v28
	v_add_f32_e32 v26, v26, v27
	v_exp_f32_e32 v26, v26
	v_cvt_i32_f32_e32 v27, v28
	v_cvt_pk_bf16_f32 v15, v15, v33
	ds_write_b16 v17, v15 offset:224
	v_cmp_ngt_f32_e32 vcc, s55, v18
	v_ldexp_f32 v15, v26, v27
	v_mul_f32_e32 v22, 0x3e000000, v23
	v_cndmask_b32_e32 v15, 0, v15, vcc
	v_cmp_nlt_f32_e32 vcc, s56, v18
	v_sub_u32_e32 v18, v20, v21
	v_cvt_f32_i32_e32 v18, v18
	v_cndmask_b32_e32 v15, v51, v15, vcc
	v_cmp_lt_i32_e32 vcc, v20, v21
	v_mul_f32_e32 v15, v15, v22
	v_cvt_pk_bf16_f32 v15, v15, v33
	ds_write_b16 v17, v15 offset:496
	v_cndmask_b32_e64 v20, -v12, v11, vcc
	v_mul_f32_e32 v18, v20, v18
	v_mul_f32_e32 v20, 0x3fb8aa3b, v18
	v_fma_f32 v23, v18, s54, -v20
	v_rndne_f32_e32 v26, v20
	v_fmac_f32_e32 v23, 0x32a5705f, v18
	v_sub_f32_e32 v20, v20, v26
	v_add_f32_e32 v20, v20, v23
	v_exp_f32_e32 v20, v20
	v_cvt_i32_f32_e32 v23, v26
	v_cmp_ngt_f32_e32 vcc, s55, v18
	v_add3_u32 v76, v30, v72, v98
	v_add3_u32 v80, v30, v80, v100
	v_ldexp_f32 v15, v20, v23
	v_cndmask_b32_e32 v15, 0, v15, vcc
	v_cmp_nlt_f32_e32 vcc, s56, v18
	v_sub_u32_e32 v18, v19, v21
	v_cvt_f32_i32_e32 v18, v18
	v_cndmask_b32_e32 v15, v51, v15, vcc
	v_cmp_lt_i32_e32 vcc, v19, v21
	v_mul_f32_e32 v20, 0x3e000000, v24
	v_mul_f32_e32 v15, v15, v20
	v_cndmask_b32_e64 v19, -v12, v11, vcc
	v_mul_f32_e32 v18, v19, v18
	v_mul_f32_e32 v19, 0x3fb8aa3b, v18
	v_fma_f32 v21, v18, s54, -v19
	v_rndne_f32_e32 v22, v19
	v_fmac_f32_e32 v21, 0x32a5705f, v18
	v_sub_f32_e32 v19, v19, v22
	v_add_f32_e32 v19, v19, v21
	v_exp_f32_e32 v19, v19
	v_cvt_i32_f32_e32 v21, v22
	v_cvt_pk_bf16_f32 v15, v15, v33
	ds_write_b16 v17, v15 offset:768
	v_cmp_ngt_f32_e32 vcc, s55, v18
	v_ldexp_f32 v15, v19, v21
	v_add3_u32 v84, v30, v84, v102
	v_cndmask_b32_e32 v15, 0, v15, vcc
	v_cmp_nlt_f32_e32 vcc, s56, v18
	v_mul_f32_e32 v18, 0x3e000000, v25
	s_nop 0
	v_cndmask_b32_e32 v15, v51, v15, vcc
	v_mul_f32_e32 v15, v15, v18
	v_cvt_pk_bf16_f32 v15, v15, v33
	ds_write_b16 v17, v15 offset:1040
	v_mul_u32_u24_e32 v15, 0x110, v9
	v_add3_u32 v14, v14, v15, v32
	s_waitcnt lgkmcnt(0)
	s_barrier
	ds_read_b128 v[18:21], v14
	v_and_b32_e32 v17, 8, v8
	v_bitop3_b32 v32, v9, 24, 16 bitop3:0xc8
	v_lshlrev_b32_e32 v22, 1, v17
	v_lshlrev_b32_e32 v35, 1, v32
	v_add3_u32 v31, v30, v22, v15
	v_add3_u32 v35, v30, v35, v63
	ds_read_b128 v[22:25], v31
	ds_read_b128 v[26:29], v14 offset:64
	ds_read_b128 v[38:41], v31 offset:64
	ds_read_b128 v[42:45], v35
	ds_read_b128 v[46:49], v31 offset:128
	v_bitop3_b32 v31, v9, 40, 32 bitop3:0xc8
	v_lshlrev_b32_e32 v64, 1, v31
	v_add3_u32 v68, v30, v64, v96
	ds_read_b128 v[64:67], v68
	ds_read_b128 v[68:71], v68 offset:64
	ds_read_b128 v[72:75], v76
	ds_read_b128 v[76:79], v76 offset:64
	ds_read_b128 v[80:83], v80
	ds_read_b128 v[84:87], v84
	ds_read_b128 v[88:91], v88
	ds_read_b128 v[92:95], v92
	s_waitcnt lgkmcnt(12)
	v_mfma_f32_16x16x32_bf16 v[22:25], v[18:21], v[22:25], 0
	v_bfi_b32 v8, -16, v10, v8
	v_add_u32_e32 v10, 1, v8
	v_cvt_f32_i32_e32 v10, v10
	s_waitcnt lgkmcnt(9)
	v_mfma_f32_16x16x32_bf16 v[42:45], v[18:21], v[42:45], 0
	v_sub_u32_e32 v8, 0x80, v8
	v_cvt_f32_i32_e32 v8, v8
	v_mul_f32_e64 v10, v10, -v12
	s_waitcnt lgkmcnt(7)
	v_mfma_f32_16x16x32_bf16 v[64:67], v[18:21], v[64:67], 0
	v_mul_f32_e32 v12, 0x3fb8aa3b, v10
	v_mul_f32_e64 v8, v8, -v11
	v_mul_f32_e32 v11, 0x3fb8aa3b, v8
	s_waitcnt lgkmcnt(5)
	v_mfma_f32_16x16x32_bf16 v[72:75], v[18:21], v[72:75], 0
	v_cmp_ngt_f32_e32 vcc, s55, v10
	s_waitcnt lgkmcnt(3)
	v_mfma_f32_16x16x32_bf16 v[80:83], v[18:21], v[80:83], 0
	s_waitcnt lgkmcnt(2)
	v_mfma_f32_16x16x32_bf16 v[84:87], v[18:21], v[84:87], 0
	s_waitcnt lgkmcnt(1)
	v_mfma_f32_16x16x32_bf16 v[88:91], v[18:21], v[88:91], 0
	s_waitcnt lgkmcnt(0)
	v_mfma_f32_16x16x32_bf16 v[18:21], v[18:21], v[92:95], 0
	v_mfma_f32_16x16x32_bf16 v[22:25], v[26:29], v[38:41], v[22:25]
	ds_read_b128 v[38:41], v35 offset:64
	ds_read_b128 v[92:95], v35 offset:128
	v_or_b32_e32 v35, 32, v13
	s_waitcnt lgkmcnt(1)
	v_mfma_f32_16x16x32_bf16 v[38:41], v[26:29], v[38:41], v[42:45]
	v_mfma_f32_16x16x32_bf16 v[42:45], v[26:29], v[68:71], v[64:67]
	v_add_u32_e32 v68, v35, v99
	v_and_b32_e32 v68, 0x78, v68
	v_lshlrev_b32_e32 v68, 1, v68
	v_add3_u32 v68, 0, v68, v100
	ds_read_b128 v[68:71], v68
	v_mfma_f32_16x16x32_bf16 v[64:67], v[26:29], v[76:79], v[72:75]
	v_add_u32_e32 v76, v35, v103
	v_and_b32_e32 v76, 56, v76
	v_lshlrev_b32_e32 v76, 1, v76
	v_add_u32_e32 v72, v35, v101
	v_add_u32_e32 v35, v35, v105
	v_and_b32_e32 v72, 0x78, v72
	v_and_b32_e32 v35, 56, v35
	v_lshlrev_b32_e32 v72, 1, v72
	v_lshlrev_b32_e32 v35, 1, v35
	v_add3_u32 v72, 0, v72, v102
	v_add3_u32 v76, 0, v76, v104
	v_add3_u32 v35, 0, v35, v106
	ds_read_b128 v[72:75], v72
	ds_read_b128 v[76:79], v76
	s_waitcnt lgkmcnt(2)
; __device__ __forceinline__ unsigned cvt_pk_bf16(float lo, float hi) { unsigned r; asm("v_cvt_pk_bf16_f32 %0, %1, %2" : "=v"(r) : "v"(lo), "v"(hi)); return r; }
; __device__ __forceinline__ float bflo(unsigned w) { return __uint_as_float(w << 16); }
; __device__ __forceinline__ float bfhi(unsigned w) { return __uint_as_float(w & 0xffff0000u); }
; __device__ __forceinline__ bf16x8 scale8(bf16x8 q, float s) {
;     const u32x4 w = un8(q); u32x4 o;
;     o.x = cvt_pk_bf16(bflo(w.x) * s, bfhi(w.x) * s); o.y = cvt_pk_bf16(bflo(w.y) * s, bfhi(w.y) * s);
;     o.z = cvt_pk_bf16(bflo(w.z) * s, bfhi(w.z) * s); o.w = cvt_pk_bf16(bflo(w.w) * s, bfhi(w.w) * s);
;     return mk8(o);
; }
; __device__ __forceinline__ void retout_item(PRef p, int layer, int item, unsigned char* shm) {
;     ...
;     for (int kk = 0; kk < 4; ++kk) { const bf16x8 af = *(const bf16x8*)(Pw + fr * LDK + kk * 32 + fq * 8);
; #pragma unroll
;         for (int et = 0; et < 8; ++et) { const bf16x8 bf = *(const bf16x8*)(vT + tsw(16 * et + fr, kk * 32 + fq * 8));
;             acc[et] = __builtin_amdgcn_mfma_f32_16x16x32_bf16(af, bf, acc[et], 0, 0, 0); } }
;     { const int ca = 16 * wave + fr;
;       const float sf = expf((float)(ca + 1) * lgf), sb = expf((float)(128 - ca) * lgb);
; #pragma unroll
;       for (int kk = 0; kk < 2; ++kk) { const bf16x8 af = scale8(qa[kk], sf), ab = scale8(qa[kk], sb);
	v_mfma_f32_16x16x32_bf16 v[68:71], v[26:29], v[68:71], v[80:83]
	s_nop 2
	ds_read_b128 v[80:83], v35
	s_waitcnt lgkmcnt(2)
	v_mfma_f32_16x16x32_bf16 v[72:75], v[26:29], v[72:75], v[84:87]
	s_waitcnt lgkmcnt(1)
	v_mfma_f32_16x16x32_bf16 v[76:79], v[26:29], v[76:79], v[88:91]
	s_waitcnt lgkmcnt(0)
	v_mfma_f32_16x16x32_bf16 v[18:21], v[26:29], v[80:83], v[18:21]
	ds_read_b128 v[26:29], v14 offset:128
	ds_read_b128 v[80:83], v14 offset:192
	v_or_b32_e32 v14, 64, v13
	v_add_u32_e32 v35, v14, v31
	v_and_b32_e32 v35, 0x78, v35
	v_lshlrev_b32_e32 v35, 1, v35
	v_add3_u32 v35, 0, v35, v96
	s_waitcnt lgkmcnt(1)
	v_mfma_f32_16x16x32_bf16 v[22:25], v[26:29], v[46:49], v[22:25]
	ds_read_b128 v[46:49], v35
	v_add_u32_e32 v35, v14, v97
	v_and_b32_e32 v35, 0x78, v35
	v_lshlrev_b32_e32 v35, 1, v35
	v_add3_u32 v35, 0, v35, v98
	ds_read_b128 v[84:87], v35
	v_add_u32_e32 v35, v13, v99
	v_and_b32_e32 v35, 56, v35
	v_lshlrev_b32_e32 v35, 1, v35
	v_add3_u32 v35, 0, v35, v100
	s_waitcnt lgkmcnt(1)
	v_mfma_f32_16x16x32_bf16 v[42:45], v[26:29], v[46:49], v[42:45]
	s_waitcnt lgkmcnt(0)
	v_mfma_f32_16x16x32_bf16 v[46:49], v[26:29], v[84:87], v[64:67]
	s_nop 2
	ds_read_b128 v[64:67], v35
	v_add_u32_e32 v35, v13, v101
	v_and_b32_e32 v35, 56, v35
	v_lshlrev_b32_e32 v35, 1, v35
	v_add3_u32 v35, 0, v35, v102
	ds_read_b128 v[84:87], v35
	v_add_u32_e32 v35, v14, v103
	v_add_u32_e32 v14, v14, v105
	v_and_b32_e32 v35, 0x78, v35
	v_and_b32_e32 v14, 0x78, v14
	v_lshlrev_b32_e32 v35, 1, v35
	v_lshlrev_b32_e32 v14, 1, v14
	v_add3_u32 v35, 0, v35, v104
	v_add3_u32 v14, 0, v14, v106
	s_waitcnt lgkmcnt(1)
	v_mfma_f32_16x16x32_bf16 v[64:67], v[26:29], v[64:67], v[68:71]
	v_or_b32_e32 v13, 0x60, v13
	s_waitcnt lgkmcnt(0)
	v_mfma_f32_16x16x32_bf16 v[68:71], v[26:29], v[84:87], v[72:75]
	ds_read_b128 v[84:87], v14
	v_add_u32_e32 v14, v13, v17
	v_and_b32_e32 v14, 0x78, v14
	ds_read_b128 v[72:75], v35
	v_lshlrev_b32_e32 v14, 1, v14
	v_add3_u32 v14, 0, v14, v15
	v_mfma_f32_16x16x32_bf16 v[38:41], v[26:29], v[92:95], v[38:41]
	v_and_b32_e32 v35, 0xffff0000, v7
	s_waitcnt lgkmcnt(0)
	v_mfma_f32_16x16x32_bf16 v[72:75], v[26:29], v[72:75], v[76:79]
	v_mfma_f32_16x16x32_bf16 v[18:21], v[26:29], v[84:87], v[18:21]
	ds_read_b128 v[26:29], v14
	v_add_u32_e32 v14, v13, v32
	v_and_b32_e32 v14, 0x78, v14
	v_lshlrev_b32_e32 v14, 1, v14
	v_add3_u32 v14, 0, v14, v63
	ds_read_b128 v[76:79], v14
	v_add_u32_e32 v14, v13, v31
	v_and_b32_e32 v14, 56, v14
	v_lshlrev_b32_e32 v14, 1, v14
	v_add3_u32 v14, 0, v14, v96
	s_waitcnt lgkmcnt(1)
	v_mfma_f32_16x16x32_bf16 v[22:25], v[80:83], v[26:29], v[22:25]
	v_lshlrev_b32_e32 v32, 16, v7
	s_waitcnt lgkmcnt(0)
	v_mfma_f32_16x16x32_bf16 v[26:29], v[80:83], v[76:79], v[38:41]
	s_nop 2
	ds_read_b128 v[38:41], v14
	v_add_u32_e32 v14, v13, v97
	v_and_b32_e32 v14, 56, v14
	v_lshlrev_b32_e32 v14, 1, v14
	v_add3_u32 v14, 0, v14, v98
	ds_read_b128 v[76:79], v14
	v_add_u32_e32 v14, v13, v99
	v_and_b32_e32 v14, 0x78, v14
	v_lshlrev_b32_e32 v14, 1, v14
	v_add3_u32 v14, 0, v14, v100
	s_waitcnt lgkmcnt(1)
	v_mfma_f32_16x16x32_bf16 v[38:41], v[80:83], v[38:41], v[42:45]
	s_waitcnt lgkmcnt(0)
	v_mfma_f32_16x16x32_bf16 v[42:45], v[80:83], v[76:79], v[46:49]
	s_nop 2
	ds_read_b128 v[46:49], v14
	v_add_u32_e32 v14, v13, v101
	v_and_b32_e32 v14, 0x78, v14
	v_lshlrev_b32_e32 v14, 1, v14
	v_add3_u32 v14, 0, v14, v102
	ds_read_b128 v[76:79], v14
	v_add_u32_e32 v14, v13, v103
	v_add_u32_e32 v13, v13, v105
	v_and_b32_e32 v14, 0x78, v14
	v_and_b32_e32 v13, 0x78, v13
	v_lshlrev_b32_e32 v14, 1, v14
	v_lshlrev_b32_e32 v13, 1, v13
	v_add3_u32 v14, 0, v14, v104
	v_add3_u32 v13, 0, v13, v106
	s_waitcnt lgkmcnt(1)
	v_mfma_f32_16x16x32_bf16 v[46:49], v[80:83], v[46:49], v[64:67]
	s_waitcnt lgkmcnt(0)
	v_mfma_f32_16x16x32_bf16 v[64:67], v[80:83], v[76:79], v[68:71]
	ds_read_b128 v[76:79], v13
	v_fma_f32 v13, v10, s54, -v12
	v_fmac_f32_e32 v13, 0x32a5705f, v10
	ds_read_b128 v[68:71], v14
	v_rndne_f32_e32 v14, v12
	v_sub_f32_e32 v12, v12, v14
	v_add_f32_e32 v12, v12, v13
	v_exp_f32_e32 v17, v12
	v_cvt_i32_f32_e32 v31, v14
	s_waitcnt lgkmcnt(1)
	v_mfma_f32_16x16x32_bf16 v[12:15], v[80:83], v[76:79], v[18:21]
	v_ldexp_f32 v17, v17, v31
	s_nop 1
	v_fma_f32 v18, v8, s54, -v11
	v_rndne_f32_e32 v19, v11
	v_fmac_f32_e32 v18, 0x32a5705f, v8
	v_sub_f32_e32 v11, v11, v19
	v_add_f32_e32 v11, v11, v18
	v_exp_f32_e32 v11, v11
	v_cvt_i32_f32_e32 v18, v19
	v_cndmask_b32_e32 v17, 0, v17, vcc
	v_cmp_nlt_f32_e32 vcc, s56, v10
	v_and_b32_e32 v19, 0xffff0000, v5
	v_ldexp_f32 v10, v11, v18
	v_cndmask_b32_e32 v17, v51, v17, vcc
	v_cmp_ngt_f32_e32 vcc, s55, v8
	v_and_b32_e32 v11, 0xffff0000, v4
	v_and_b32_e32 v21, 0xffff0000, v6
	v_cndmask_b32_e32 v10, 0, v10, vcc
	v_cmp_nlt_f32_e32 vcc, s56, v8
	v_lshlrev_b32_e32 v8, 16, v4
	v_mul_f32_e32 v4, v17, v11
	v_cndmask_b32_e32 v31, v51, v10, vcc
	v_mul_u32_u24_e32 v10, 0x48, v9
	v_mul_f32_e32 v9, v17, v8
	v_cvt_pk_bf16_f32 v4, v9, v4
	v_lshlrev_b32_e32 v9, 16, v5
	v_mul_f32_e32 v18, v17, v9
	v_mul_f32_e32 v5, v17, v19
	v_cvt_pk_bf16_f32 v5, v18, v5
	v_lshlrev_b32_e32 v18, 16, v6
	v_mul_f32_e32 v20, v17, v18
	v_mul_f32_e32 v6, v17, v21
	v_mul_f32_e32 v8, v31, v8
	v_mul_f32_e32 v11, v31, v11
	v_cvt_pk_bf16_f32 v6, v20, v6
	v_mul_f32_e32 v20, v17, v32
	v_mul_f32_e32 v7, v17, v35
	v_cvt_pk_bf16_f32 v8, v8, v11
	v_mul_f32_e32 v9, v31, v9
	v_mul_f32_e32 v11, v31, v19
	v_lshl_add_u32 v30, v10, 1, v30
	v_cvt_pk_bf16_f32 v7, v20, v7
	v_cvt_pk_bf16_f32 v9, v9, v11
	v_mul_f32_e32 v11, v31, v18
	v_mul_f32_e32 v63, v31, v21
	ds_read_b128 v[18:21], v30 offset:34816
	s_waitcnt lgkmcnt(1)
; __device__ __forceinline__ float bf2f(unsigned short b) { return __uint_as_float(((unsigned)b) << 16); }
; __device__ __forceinline__ void retout_item(PRef p, int layer, int item, unsigned char* shm) {
;     ...
;     { const int ca = 16 * wave + fr;
;       const float sf = expf((float)(ca + 1) * lgf), sb = expf((float)(128 - ca) * lgb);
; #pragma unroll
;       for (int kk = 0; kk < 2; ++kk) { const bf16x8 af = scale8(qa[kk], sf), ab = scale8(qa[kk], sb);
; #pragma unroll
;           for (int et = 0; et < 8; ++et) { const bf16x8 b1 = *(const bf16x8*)(sTf + (16 * et + fr) * 72 + kk * 32 + fq * 8);
;               acc[et] = __builtin_amdgcn_mfma_f32_16x16x32_bf16(af, b1, acc[et], 0, 0, 0);
;               const bf16x8 b2 = *(const bf16x8*)(sTb + (16 * et + fr) * 72 + kk * 32 + fq * 8);
;               acc[et] = __builtin_amdgcn_mfma_f32_16x16x32_bf16(ab, b2, acc[et], 0, 0, 0); } } }
; #pragma unroll
;     for (int r = 0; r < 4; ++r) { float ss = 0.f;
; #pragma unroll
;         for (int et = 0; et < 8; ++et) ss += acc[et][r] * acc[et][r];
;         ss += __shfl_xor(ss, 1); ss += __shfl_xor(ss, 2); ss += __shfl_xor(ss, 4); ss += __shfl_xor(ss, 8);
;         const float rinv = rsqrtf(ss * (1.f / 128.f) + 1e-6f);
;         const size_t row = (size_t)(row0 + 16 * wave + fq * 4 + r);
; #pragma unroll
;         for (int et = 0; et < 8; ++et) { const int e = 16 * et + fr; const float gg = bf2f(A[row * NIN + C_G + h * 128 + e]);
	v_mfma_f32_16x16x32_bf16 v[68:71], v[80:83], v[68:71], v[72:75]
	s_nop 2
	ds_read_b128 v[72:75], v30 offset:53248
	ds_read_b128 v[76:79], v30 offset:34880
	v_cvt_pk_bf16_f32 v10, v11, v63
	v_mul_f32_e32 v11, v31, v32
	s_waitcnt lgkmcnt(2)
	v_mfma_f32_16x16x32_bf16 v[18:21], v[4:7], v[18:21], v[22:25]
	v_add_u32_e32 v32, 0x900, v30
	s_nop 1
	v_mul_f32_e32 v22, v31, v35
	v_cvt_pk_bf16_f32 v11, v11, v22
	ds_read_b128 v[22:25], v30 offset:53312
	s_waitcnt lgkmcnt(2)
	v_mfma_f32_16x16x32_bf16 v[18:21], v[8:11], v[72:75], v[18:21]
	ds_read_b128 v[72:75], v30 offset:37120
	ds_read_b128 v[80:83], v30 offset:37184
	v_mov_b32_e32 v35, v33
	s_waitcnt lgkmcnt(1)
	v_mfma_f32_16x16x32_bf16 v[26:29], v[4:7], v[72:75], v[26:29]
	ds_read_b128 v[72:75], v30 offset:55552
	ds_read_b128 v[84:87], v30 offset:55616
	s_waitcnt lgkmcnt(1)
	v_mfma_f32_16x16x32_bf16 v[72:75], v[8:11], v[72:75], v[26:29]
	s_nop 3
	ds_read_b128 v[26:29], v30 offset:39424
	ds_read_b128 v[88:91], v30 offset:39488
	s_waitcnt lgkmcnt(1)
	v_mfma_f32_16x16x32_bf16 v[26:29], v[4:7], v[26:29], v[38:41]
	s_nop 2
	ds_read_b128 v[38:41], v30 offset:57856
	ds_read_b128 v[92:95], v30 offset:57920
	s_waitcnt lgkmcnt(1)
	v_mfma_f32_16x16x32_bf16 v[38:41], v[8:11], v[38:41], v[26:29]
	s_nop 2
	ds_read_b128 v[26:29], v30 offset:41728
	ds_read_b128 v[96:99], v30 offset:41792
	s_waitcnt lgkmcnt(1)
	v_mfma_f32_16x16x32_bf16 v[26:29], v[4:7], v[26:29], v[42:45]
	s_nop 2
	ds_read_b128 v[42:45], v30 offset:60160
	ds_read_b128 v[100:103], v30 offset:60224
	s_waitcnt lgkmcnt(1)
	v_mfma_f32_16x16x32_bf16 v[42:45], v[8:11], v[42:45], v[26:29]
	s_nop 2
	ds_read_b128 v[26:29], v30 offset:44032
	ds_read_b128 v[104:107], v30 offset:44096
	s_waitcnt lgkmcnt(1)
	v_mfma_f32_16x16x32_bf16 v[26:29], v[4:7], v[26:29], v[46:49]
	s_nop 2
	ds_read_b128 v[46:49], v30 offset:62464
	ds_read_b128 v[108:111], v30 offset:62528
	s_waitcnt lgkmcnt(1)
	v_mfma_f32_16x16x32_bf16 v[46:49], v[8:11], v[46:49], v[26:29]
	s_nop 2
	ds_read_b128 v[26:29], v30 offset:46336
	ds_read_b128 v[112:115], v30 offset:46400
	s_waitcnt lgkmcnt(1)
	v_mfma_f32_16x16x32_bf16 v[26:29], v[4:7], v[26:29], v[64:67]
	s_nop 2
	ds_read_b128 v[64:67], v30 offset:64768
	ds_read_b128 v[116:119], v30 offset:64832
	ds_read_b128 v[120:123], v30 offset:48704
	s_waitcnt lgkmcnt(2)
	v_mfma_f32_16x16x32_bf16 v[64:67], v[8:11], v[64:67], v[26:29]
	s_nop 2
	ds_read_b128 v[26:29], v30 offset:48640
	s_waitcnt lgkmcnt(0)
	v_mfma_f32_16x16x32_bf16 v[26:29], v[4:7], v[26:29], v[68:71]
	s_nop 2
	ds_read_b128 v[68:71], v32 offset:64768
	ds_read_b128 v[124:127], v32 offset:64832
	v_add_u32_e32 v32, 0x1200, v30
	ds_read_b128 v[128:131], v30 offset:51008
	s_waitcnt lgkmcnt(2)
	v_mfma_f32_16x16x32_bf16 v[68:71], v[8:11], v[68:71], v[26:29]
	s_nop 2
	ds_read_b128 v[26:29], v30 offset:50944
	s_waitcnt lgkmcnt(0)
	v_mfma_f32_16x16x32_bf16 v[4:7], v[4:7], v[26:29], v[12:15]
	s_nop 2
	ds_read_b128 v[12:15], v32 offset:64768
	ds_read_b128 v[132:135], v32 offset:64832
	v_xor_b32_e32 v32, 1, v62
	s_waitcnt lgkmcnt(1)
	v_mfma_f32_16x16x32_bf16 v[136:139], v[8:11], v[12:15], v[4:7]
	v_and_b32_e32 v9, 0xffff0000, v3
	s_nop 1
	v_lshlrev_b32_e32 v4, 16, v0
	v_mul_f32_e32 v5, v17, v4
	v_and_b32_e32 v0, 0xffff0000, v0
	v_mul_f32_e32 v6, v17, v0
	v_cvt_pk_bf16_f32 v140, v5, v6
	v_lshlrev_b32_e32 v5, 16, v1
	v_mul_f32_e32 v6, v17, v5
	v_and_b32_e32 v1, 0xffff0000, v1
	v_mul_f32_e32 v7, v17, v1
	v_cvt_pk_bf16_f32 v141, v6, v7
	v_lshlrev_b32_e32 v6, 16, v2
	v_mul_f32_e32 v7, v17, v6
	v_and_b32_e32 v2, 0xffff0000, v2
	v_mul_f32_e32 v8, v17, v2
	v_cvt_pk_bf16_f32 v142, v7, v8
	v_lshlrev_b32_e32 v7, 16, v3
	v_mul_f32_e32 v3, v17, v9
	v_mul_f32_e32 v0, v31, v0
	v_mul_f32_e32 v8, v17, v7
	v_cvt_pk_bf16_f32 v143, v8, v3
	v_mul_f32_e32 v3, v31, v4
	v_cvt_pk_bf16_f32 v144, v3, v0
	v_mul_f32_e32 v0, v31, v5
	v_mul_f32_e32 v1, v31, v1
	v_cvt_pk_bf16_f32 v145, v0, v1
	v_mul_f32_e32 v0, v31, v6
	v_mul_f32_e32 v1, v31, v2
	v_cvt_pk_bf16_f32 v146, v0, v1
	v_mfma_f32_16x16x32_bf16 v[0:3], v[140:143], v[76:79], v[18:21]
	v_mul_f32_e32 v4, v31, v7
	v_mul_f32_e32 v5, v31, v9
	v_cvt_pk_bf16_f32 v147, v4, v5
	s_nop 0
	v_mfma_f32_16x16x32_bf16 v[28:31], v[144:147], v[22:25], v[0:3]
	v_mfma_f32_16x16x32_bf16 v[0:3], v[140:143], v[80:83], v[72:75]
	v_mfma_f32_16x16x32_bf16 v[24:27], v[144:147], v[84:87], v[0:3]
	v_mfma_f32_16x16x32_bf16 v[0:3], v[140:143], v[88:91], v[38:41]
	s_nop 2
	v_add_u32_e32 v38, s46, v16
	v_mad_i64_i32 v[16:17], s[2:3], v38, s37, v[36:37]
	v_lshl_add_u64 v[16:17], v[16:17], 0, s[22:23]
	v_mfma_f32_16x16x32_bf16 v[20:23], v[144:147], v[92:95], v[0:3]
	s_add_u32 s2, s29, s22
	s_addc_u32 s3, s30, 0
	v_mfma_f32_16x16x32_bf16 v[0:3], v[140:143], v[96:99], v[42:45]
	s_nop 2
	v_lshl_add_u64 v[44:45], v[16:17], 0, v[34:35]
	v_add_co_u32_e32 v16, vcc, s39, v44
	v_mfma_f32_16x16x32_bf16 v[12:15], v[144:147], v[100:103], v[0:3]
	s_nop 0
	v_addc_co_u32_e32 v17, vcc, 0, v45, vcc
	global_load_ushort v39, v[16:17], off offset:3072
	v_mfma_f32_16x16x32_bf16 v[0:3], v[140:143], v[104:107], v[46:49]
	v_mfma_f32_16x16x32_bf16 v[8:11], v[144:147], v[108:111], v[0:3]
	s_nop 1
	v_mul_f32_e32 v47, v24, v24
	v_fmac_f32_e32 v47, v28, v28
	v_xor_b32_e32 v49, 8, v62
	v_mfma_f32_16x16x32_bf16 v[0:3], v[140:143], v[112:115], v[64:67]
	v_mfma_f32_16x16x32_bf16 v[40:43], v[140:143], v[128:131], v[136:139]
	s_waitcnt vmcnt(0)
	s_nop 0
	v_lshlrev_b32_e32 v67, 16, v39
	v_mfma_f32_16x16x32_bf16 v[4:7], v[144:147], v[116:119], v[0:3]
	v_mul_f32_e32 v39, 0xbfb8aa3b, v67
	v_mfma_f32_16x16x32_bf16 v[0:3], v[140:143], v[120:123], v[68:71]
	s_waitcnt lgkmcnt(0)
; __device__ __forceinline__ float bf2f(unsigned short b) { return __uint_as_float(((unsigned)b) << 16); }
; __device__ __forceinline__ unsigned short f2bf(float f) { return (unsigned short)(cvt_pk_bf16(f, 0.f) & 0xffffu); }
; __device__ __forceinline__ float sigmoidf_(float x) { return 1.f / (1.f + __expf(-x)); }
; __device__ __forceinline__ void retout_item(PRef p, int layer, int item, unsigned char* shm) {
;     ...
; #pragma unroll
;     for (int r = 0; r < 4; ++r) { float ss = 0.f;
; #pragma unroll
;         for (int et = 0; et < 8; ++et) ss += acc[et][r] * acc[et][r];
;         ss += __shfl_xor(ss, 1); ss += __shfl_xor(ss, 2); ss += __shfl_xor(ss, 4); ss += __shfl_xor(ss, 8);
;         const float rinv = rsqrtf(ss * (1.f / 128.f) + 1e-6f);
;         const size_t row = (size_t)(row0 + 16 * wave + fq * 4 + r);
; #pragma unroll
;         for (int et = 0; et < 8; ++et) { const int e = 16 * et + fr; const float gg = bf2f(A[row * NIN + C_G + h * 128 + e]);
;             MIX[row * 2048 + 512 + h * 128 + e] = f2bf(acc[et][r] * rinv * gg * sigmoidf_(gg)); } }
	v_mfma_f32_16x16x32_bf16 v[16:19], v[144:147], v[132:135], v[40:43]
	s_nop 0
	v_exp_f32_e32 v68, v39
	v_ashrrev_i32_e32 v39, 31, v38
	v_and_b32_e32 v40, 64, v62
	v_add_u32_e32 v46, 64, v40
	v_lshl_add_u64 v[40:41], v[44:45], 0, s[40:41]
	v_mov_b32_e32 v42, v20
	v_mov_b32_e32 v43, v12
	global_load_ushort v48, v[40:41], off offset:32
	v_pk_mul_f32 v[42:43], v[42:43], v[42:43]
	v_mfma_f32_16x16x32_bf16 v[0:3], v[144:147], v[124:127], v[0:3]
	v_add_f32_e32 v42, v47, v42
	v_add_f32_e32 v44, v42, v43
	v_mov_b32_e32 v42, v8
	v_mov_b32_e32 v43, v4
	v_pk_mul_f32 v[42:43], v[42:43], v[42:43]
	v_cmp_lt_i32_e32 vcc, v32, v46
	v_add_f32_e32 v42, v44, v42
	v_add_f32_e32 v44, v42, v43
	v_mov_b32_e32 v42, v0
	v_mov_b32_e32 v43, v16
	v_pk_mul_f32 v[42:43], v[42:43], v[42:43]
	v_cndmask_b32_e32 v32, v62, v32, vcc
	v_add_f32_e32 v42, v44, v42
	v_lshlrev_b32_e32 v32, 2, v32
	v_add_f32_e32 v42, v42, v43
	ds_bpermute_b32 v43, v32, v42
	v_xor_b32_e32 v44, 2, v62
	v_cmp_lt_i32_e32 vcc, v44, v46
	v_xor_b32_e32 v45, 4, v62
	s_waitcnt lgkmcnt(0)
	v_add_f32_e32 v42, v42, v43
	v_cndmask_b32_e32 v44, v62, v44, vcc
	v_lshlrev_b32_e32 v44, 2, v44
	ds_bpermute_b32 v47, v44, v42
	global_load_ushort v43, v[40:41], off offset:64
	v_cmp_lt_i32_e32 vcc, v45, v46
	s_waitcnt lgkmcnt(0)
	v_add_f32_e32 v42, v42, v47
	v_cndmask_b32_e32 v45, v62, v45, vcc
	v_lshlrev_b32_e32 v45, 2, v45
	ds_bpermute_b32 v47, v45, v42
	v_cmp_lt_i32_e32 vcc, v49, v46
	s_waitcnt lgkmcnt(0)
	v_add_f32_e32 v42, v42, v47
	v_cndmask_b32_e32 v46, v62, v49, vcc
	v_lshlrev_b32_e32 v46, 2, v46
	ds_bpermute_b32 v47, v46, v42
	s_waitcnt lgkmcnt(0)
	v_add_f32_e32 v42, v42, v47
	v_fmamk_f32 v42, v42, 0x3c000000, v50
	v_mul_f32_e32 v47, 0x4b800000, v42
	v_cmp_gt_f32_e32 vcc, s60, v42
	s_nop 1
	v_cndmask_b32_e32 v42, v42, v47, vcc
	global_load_ushort v47, v[40:41], off offset:96
	global_load_ushort v63, v[40:41], off offset:128
	global_load_ushort v64, v[40:41], off offset:160
	global_load_ushort v65, v[40:41], off offset:192
	global_load_ushort v66, v[40:41], off offset:224
	v_rsq_f32_e32 v42, v42
	v_lshlrev_b64 v[40:41], 12, v[38:39]
	v_add_f32_e32 v39, 1.0, v68
	v_lshl_add_u64 v[40:41], s[2:3], 0, v[40:41]
	v_mul_f32_e32 v49, 0x45800000, v42
	v_cndmask_b32_e32 v69, v42, v49, vcc
	v_rcp_f32_e32 v39, v39
	v_mul_f32_e32 v28, v28, v69
	v_mul_f32_e32 v28, v28, v67
	v_lshl_add_u64 v[40:41], v[40:41], 0, v[34:35]
	v_mul_f32_e32 v28, v39, v28
	v_cvt_pk_bf16_f32 v28, v28, v33
	s_waitcnt vmcnt(6)
	v_lshlrev_b32_e32 v42, 16, v48
	v_mul_f32_e32 v48, 0xbfb8aa3b, v42
	v_exp_f32_e32 v48, v48
	global_store_short v[40:41], v28, off
	v_mul_f32_e32 v24, v24, v69
	v_mul_f32_e32 v24, v24, v42
	v_add_f32_e32 v39, 1.0, v48
	v_rcp_f32_e32 v28, v39
	v_mul_f32_e32 v20, v20, v69
	v_mul_f32_e32 v12, v12, v69
	v_mul_f32_e32 v8, v8, v69
	v_mul_f32_e32 v24, v24, v28
	v_cvt_pk_bf16_f32 v24, v24, v33
	global_store_short v[40:41], v24, off offset:32
	v_mul_f32_e32 v4, v4, v69
	s_waitcnt vmcnt(7)
	v_lshlrev_b32_e32 v42, 16, v43
	v_mul_f32_e32 v43, 0xbfb8aa3b, v42
	v_exp_f32_e32 v43, v43
	v_mul_f32_e32 v20, v20, v42
	v_mul_f32_e32 v0, v0, v69
	v_add_f32_e32 v28, 1.0, v43
	v_rcp_f32_e32 v24, v28
	s_nop 0
	v_mul_f32_e32 v20, v20, v24
	v_cvt_pk_bf16_f32 v20, v20, v33
	global_store_short v[40:41], v20, off offset:64
	s_waitcnt vmcnt(7)
	v_lshlrev_b32_e32 v39, 16, v47
	v_mul_f32_e32 v42, 0xbfb8aa3b, v39
	v_exp_f32_e32 v42, v42
	v_mul_f32_e32 v12, v12, v39
	v_add_f32_e32 v24, 1.0, v42
	v_rcp_f32_e32 v20, v24
	s_nop 0
	s_waitcnt vmcnt(6)
	v_lshlrev_b32_e32 v28, 16, v63
	v_mul_f32_e32 v39, 0xbfb8aa3b, v28
	v_exp_f32_e32 v39, v39
	v_mul_f32_e32 v12, v12, v20
	v_cvt_pk_bf16_f32 v12, v12, v33
	v_add_f32_e32 v20, 1.0, v39
	v_rcp_f32_e32 v39, v20
	global_store_short v[40:41], v12, off offset:96
	v_mul_f32_e32 v8, v8, v28
	s_waitcnt vmcnt(6)
	v_lshlrev_b32_e32 v24, 16, v64
	v_mul_f32_e32 v28, 0xbfb8aa3b, v24
	v_exp_f32_e32 v28, v28
	v_mov_b32_e32 v12, v39
	v_mul_f32_e32 v8, v8, v12
	v_cvt_pk_bf16_f32 v8, v8, v33
	v_add_f32_e32 v12, 1.0, v28
	v_rcp_f32_e32 v28, v12
	global_store_short v[40:41], v8, off offset:128
	v_mul_f32_e32 v4, v4, v24
	v_add_u32_e32 v42, 1, v38
	s_waitcnt vmcnt(6)
	v_lshlrev_b32_e32 v20, 16, v65
	v_mul_f32_e32 v24, 0xbfb8aa3b, v20
	v_mad_i64_i32 v[48:49], s[4:5], v42, s37, v[36:37]
	v_exp_f32_e32 v24, v24
	v_lshl_add_u64 v[48:49], v[48:49], 0, s[22:23]
	v_lshl_add_u64 v[48:49], v[48:49], 0, v[34:35]
	v_add_co_u32_e32 v64, vcc, s39, v48
	v_mov_b32_e32 v8, v28
	s_nop 0
	v_addc_co_u32_e32 v65, vcc, 0, v49, vcc
	v_mul_f32_e32 v4, v4, v8
	v_add_f32_e32 v8, 1.0, v24
	global_load_ushort v24, v[64:65], off offset:3072
	v_rcp_f32_e32 v28, v8
	v_cvt_pk_bf16_f32 v4, v4, v33
	global_store_short v[40:41], v4, off offset:160
	v_mul_f32_e32 v0, v0, v20
	v_mov_b32_e32 v4, v28
	s_waitcnt vmcnt(7)
	v_lshlrev_b32_e32 v8, 16, v66
	v_mul_f32_e32 v0, v0, v4
	v_mul_f32_e32 v4, 0xbfb8aa3b, v8
	v_lshl_add_u64 v[48:49], v[48:49], 0, s[40:41]
	v_exp_f32_e32 v39, v4
	v_mul_f32_e32 v4, v25, v25
	v_mov_b32_e32 v12, v21
	global_load_ushort v28, v[48:49], off offset:32
	global_load_ushort v47, v[48:49], off offset:64
	v_fmac_f32_e32 v4, v29, v29
	v_mul_f32_e32 v20, v16, v69
	v_fma_f32 v4, v12, v12, v4
	v_fma_f32 v12, v13, v13, v4
	v_mov_b32_e32 v4, v9
	v_mov_b32_e32 v16, v1
	v_fma_f32 v4, v4, v4, v12
	v_fma_f32 v4, v5, v5, v4
	v_pk_mul_f32 v[64:65], v[16:17], v[16:17]
	v_add_f32_e32 v16, 1.0, v39
	v_add_f32_e32 v4, v4, v64
	v_add_f32_e32 v4, v4, v65
	ds_bpermute_b32 v12, v32, v4
	v_rcp_f32_e32 v43, v16
	v_cvt_pk_bf16_f32 v0, v0, v33
	s_waitcnt lgkmcnt(0)
	v_add_f32_e32 v4, v4, v12
	ds_bpermute_b32 v12, v44, v4
	global_store_short v[40:41], v0, off offset:192
	v_mul_f32_e32 v0, v20, v8
	s_waitcnt lgkmcnt(0)
; __device__ __forceinline__ float bf2f(unsigned short b) { return __uint_as_float(((unsigned)b) << 16); }
; __device__ __forceinline__ unsigned short f2bf(float f) { return (unsigned short)(cvt_pk_bf16(f, 0.f) & 0xffffu); }
; __device__ __forceinline__ float sigmoidf_(float x) { return 1.f / (1.f + __expf(-x)); }
; __device__ __forceinline__ void retout_item(PRef p, int layer, int item, unsigned char* shm) {
;     ...
; #pragma unroll
;     for (int r = 0; r < 4; ++r) { float ss = 0.f;
; #pragma unroll
;         for (int et = 0; et < 8; ++et) ss += acc[et][r] * acc[et][r];
;         ss += __shfl_xor(ss, 1); ss += __shfl_xor(ss, 2); ss += __shfl_xor(ss, 4); ss += __shfl_xor(ss, 8);
;         const float rinv = rsqrtf(ss * (1.f / 128.f) + 1e-6f);
;         const size_t row = (size_t)(row0 + 16 * wave + fq * 4 + r);
; #pragma unroll
;         for (int et = 0; et < 8; ++et) { const int e = 16 * et + fr; const float gg = bf2f(A[row * NIN + C_G + h * 128 + e]);
;             MIX[row * 2048 + 512 + h * 128 + e] = f2bf(acc[et][r] * rinv * gg * sigmoidf_(gg)); } }
	v_add_f32_e32 v4, v4, v12
	ds_bpermute_b32 v8, v45, v4
	s_waitcnt lgkmcnt(0)
	v_add_f32_e32 v4, v4, v8
	ds_bpermute_b32 v8, v46, v4
	v_mov_b32_e32 v12, v43
	s_waitcnt lgkmcnt(0)
	v_add_f32_e32 v4, v4, v8
	v_fmamk_f32 v4, v4, 0x3c000000, v50
	v_mul_f32_e32 v8, 0x4b800000, v4
	v_cmp_gt_f32_e32 vcc, s60, v4
	v_mul_f32_e32 v0, v0, v12
	v_cvt_pk_bf16_f32 v0, v0, v33
	global_store_short v[40:41], v0, off offset:224
	v_cndmask_b32_e32 v4, v4, v8, vcc
	global_load_ushort v8, v[48:49], off offset:96
	global_load_ushort v12, v[48:49], off offset:128
	global_load_ushort v16, v[48:49], off offset:160
	global_load_ushort v20, v[48:49], off offset:192
	global_load_ushort v39, v[48:49], off offset:224
	v_rsq_f32_e32 v4, v4
	v_ashrrev_i32_e32 v43, 31, v42
	v_mul_f32_e32 v0, 0x45800000, v4
	v_cndmask_b32_e32 v49, v4, v0, vcc
	v_mul_f32_e32 v29, v29, v49
	s_waitcnt vmcnt(10)
	v_lshlrev_b32_e32 v24, 16, v24
	v_mul_f32_e32 v40, 0xbfb8aa3b, v24
	v_exp_f32_e32 v48, v40
	v_lshlrev_b64 v[40:41], 12, v[42:43]
	v_mul_f32_e32 v24, v29, v24
	v_lshl_add_u64 v[40:41], s[2:3], 0, v[40:41]
	v_add_f32_e32 v0, 1.0, v48
	v_rcp_f32_e32 v0, v0
	v_mul_f32_e32 v1, v1, v49
	v_mul_f32_e32 v17, v17, v49
	v_mul_f32_e32 v0, v0, v24
	s_waitcnt vmcnt(8)
	v_lshlrev_b32_e32 v4, 16, v28
	v_mul_f32_e32 v28, 0xbfb8aa3b, v4
	v_exp_f32_e32 v42, v28
	v_lshl_add_u64 v[28:29], v[40:41], 0, v[34:35]
	v_cvt_pk_bf16_f32 v0, v0, v33
	global_store_short v[28:29], v0, off
	v_add_f32_e32 v24, 1.0, v42
	v_rcp_f32_e32 v41, v24
	v_mul_f32_e32 v0, v25, v49
	v_mul_f32_e32 v0, v0, v4
	s_waitcnt vmcnt(8)
	v_lshlrev_b32_e32 v25, 16, v47
	v_mul_f32_e32 v40, 0xbfb8aa3b, v25
	v_exp_f32_e32 v40, v40
	v_mov_b32_e32 v4, v41
	v_mul_f32_e32 v0, v0, v4
	v_cvt_pk_bf16_f32 v0, v0, v33
	v_add_f32_e32 v4, 1.0, v40
	v_rcp_f32_e32 v4, v4
	global_store_short v[28:29], v0, off offset:32
	v_mul_f32_e32 v0, v21, v49
	v_mul_f32_e32 v0, v0, v25
	v_mul_f32_e32 v0, v0, v4
	v_cvt_pk_bf16_f32 v0, v0, v33
	s_waitcnt vmcnt(6)
	v_lshlrev_b32_e32 v8, 16, v8
	v_mul_f32_e32 v24, 0xbfb8aa3b, v8
	v_exp_f32_e32 v24, v24
	global_store_short v[28:29], v0, off offset:64
	v_mul_f32_e32 v0, v13, v49
	v_mul_f32_e32 v0, v0, v8
	v_add_f32_e32 v4, 1.0, v24
	v_rcp_f32_e32 v4, v4
	s_waitcnt vmcnt(6)
	v_lshlrev_b32_e32 v12, 16, v12
	v_mul_f32_e32 v13, 0xbfb8aa3b, v12
	v_exp_f32_e32 v13, v13
	v_mul_f32_e32 v0, v0, v4
	v_cvt_pk_bf16_f32 v0, v0, v33
	v_add_f32_e32 v4, 1.0, v13
	v_rcp_f32_e32 v4, v4
	global_store_short v[28:29], v0, off offset:96
	v_mul_f32_e32 v0, v9, v49
	v_mul_f32_e32 v0, v0, v12
	s_waitcnt vmcnt(6)
	v_lshlrev_b32_e32 v9, 16, v16
	v_mul_f32_e32 v12, 0xbfb8aa3b, v9
	v_exp_f32_e32 v12, v12
	v_mul_f32_e32 v0, v0, v4
	v_cvt_pk_bf16_f32 v0, v0, v33
	v_add_f32_e32 v4, 1.0, v12
	v_rcp_f32_e32 v4, v4
	global_store_short v[28:29], v0, off offset:128
	v_mul_f32_e32 v0, v5, v49
	v_mul_f32_e32 v0, v0, v9
	s_waitcnt vmcnt(6)
	v_lshlrev_b32_e32 v12, 16, v20
	v_mul_f32_e32 v8, 0xbfb8aa3b, v12
	v_exp_f32_e32 v8, v8
	v_mul_f32_e32 v0, v0, v4
	v_cvt_pk_bf16_f32 v13, v0, v33
	v_add_u32_e32 v0, 2, v38
	v_mad_i64_i32 v[4:5], s[4:5], v0, s37, v[36:37]
	v_lshl_add_u64 v[4:5], v[4:5], 0, s[22:23]
	v_add_f32_e32 v16, 1.0, v8
	v_lshl_add_u64 v[4:5], v[4:5], 0, v[34:35]
	v_add_co_u32_e32 v8, vcc, s39, v4
	v_rcp_f32_e32 v21, v16
	s_nop 0
	v_addc_co_u32_e32 v9, vcc, 0, v5, vcc
	global_load_ushort v24, v[8:9], off offset:3072
	v_mul_f32_e32 v1, v1, v12
	v_mov_b32_e32 v8, v21
	v_mul_f32_e32 v1, v1, v8
	v_cvt_pk_bf16_f32 v1, v1, v33
	global_store_short v[28:29], v1, off offset:192
	s_waitcnt vmcnt(7)
	v_lshlrev_b32_e32 v1, 16, v39
	v_mul_f32_e32 v8, 0xbfb8aa3b, v1
	global_store_short v[28:29], v13, off offset:160
	v_exp_f32_e32 v12, v8
	v_mul_f32_e32 v13, v26, v26
	v_mov_b32_e32 v8, v22
	v_mov_b32_e32 v9, v14
	v_fmac_f32_e32 v13, v30, v30
	v_pk_mul_f32 v[8:9], v[8:9], v[8:9]
	v_lshl_add_u64 v[4:5], v[4:5], 0, s[40:41]
	v_add_f32_e32 v8, v13, v8
	global_load_ushort v16, v[4:5], off offset:32
	global_load_ushort v21, v[4:5], off offset:64
	v_add_f32_e32 v13, v8, v9
	v_mov_b32_e32 v8, v10
	v_mov_b32_e32 v9, v6
	v_pk_mul_f32 v[8:9], v[8:9], v[8:9]
	v_add_f32_e32 v12, 1.0, v12
	v_add_f32_e32 v8, v13, v8
	v_add_f32_e32 v13, v8, v9
	v_mov_b32_e32 v8, v2
	v_mov_b32_e32 v9, v18
	v_pk_mul_f32 v[8:9], v[8:9], v[8:9]
	v_mul_f32_e32 v1, v17, v1
	v_add_f32_e32 v8, v13, v8
	v_add_f32_e32 v8, v8, v9
	ds_bpermute_b32 v9, v32, v8
	v_rcp_f32_e32 v12, v12
	s_waitcnt lgkmcnt(0)
	v_add_f32_e32 v8, v8, v9
	ds_bpermute_b32 v9, v44, v8
	s_waitcnt lgkmcnt(0)
	v_add_f32_e32 v8, v8, v9
	ds_bpermute_b32 v9, v45, v8
	s_waitcnt lgkmcnt(0)
	v_add_f32_e32 v8, v8, v9
	ds_bpermute_b32 v9, v46, v8
	v_mul_f32_e32 v1, v1, v12
	v_cvt_pk_bf16_f32 v1, v1, v33
	s_waitcnt lgkmcnt(0)
	v_add_f32_e32 v8, v8, v9
	v_fmamk_f32 v8, v8, 0x3c000000, v50
	v_mul_f32_e32 v9, 0x4b800000, v8
	v_cmp_gt_f32_e32 vcc, s60, v8
	global_store_short v[28:29], v1, off offset:224
	s_nop 0
	v_cndmask_b32_e32 v8, v8, v9, vcc
	global_load_ushort v9, v[4:5], off offset:96
	global_load_ushort v12, v[4:5], off offset:128
	global_load_ushort v13, v[4:5], off offset:160
	global_load_ushort v17, v[4:5], off offset:192
	s_nop 0
	global_load_ushort v5, v[4:5], off offset:224
	v_rsq_f32_e32 v8, v8
	s_waitcnt vmcnt(10)
	v_lshlrev_b32_e32 v4, 16, v24
	v_mul_f32_e32 v20, 0xbfb8aa3b, v4
	v_exp_f32_e32 v20, v20
	v_mul_f32_e32 v1, 0x45800000, v8
	v_cndmask_b32_e32 v24, v8, v1, vcc
	v_mul_f32_e32 v28, v30, v24
	v_add_f32_e32 v8, 1.0, v20
	v_rcp_f32_e32 v8, v8
	v_mul_f32_e32 v4, v28, v4
	v_ashrrev_i32_e32 v1, 31, v0
	v_lshlrev_b64 v[0:1], 12, v[0:1]
	v_mul_f32_e32 v4, v8, v4
	v_lshl_add_u64 v[0:1], s[2:3], 0, v[0:1]
	v_cvt_pk_bf16_f32 v4, v4, v33
	s_waitcnt vmcnt(7)
; __device__ __forceinline__ float bf2f(unsigned short b) { return __uint_as_float(((unsigned)b) << 16); }
; __device__ __forceinline__ unsigned short f2bf(float f) { return (unsigned short)(cvt_pk_bf16(f, 0.f) & 0xffffu); }
; __device__ __forceinline__ float sigmoidf_(float x) { return 1.f / (1.f + __expf(-x)); }
; __device__ __forceinline__ void retout_item(PRef p, int layer, int item, unsigned char* shm) {
;     ...
; #pragma unroll
;     for (int r = 0; r < 4; ++r) { float ss = 0.f;
; #pragma unroll
;         for (int et = 0; et < 8; ++et) ss += acc[et][r] * acc[et][r];
;         ss += __shfl_xor(ss, 1); ss += __shfl_xor(ss, 2); ss += __shfl_xor(ss, 4); ss += __shfl_xor(ss, 8);
;         const float rinv = rsqrtf(ss * (1.f / 128.f) + 1e-6f);
;         const size_t row = (size_t)(row0 + 16 * wave + fq * 4 + r);
; #pragma unroll
;         for (int et = 0; et < 8; ++et) { const int e = 16 * et + fr; const float gg = bf2f(A[row * NIN + C_G + h * 128 + e]);
;             MIX[row * 2048 + 512 + h * 128 + e] = f2bf(acc[et][r] * rinv * gg * sigmoidf_(gg)); } }
;     __syncthreads();
	v_lshlrev_b32_e32 v16, 16, v16
	v_mul_f32_e32 v20, 0xbfb8aa3b, v16
	v_exp_f32_e32 v20, v20
	v_lshl_add_u64 v[0:1], v[0:1], 0, v[34:35]
	global_store_short v[0:1], v4, off
	v_mul_f32_e32 v4, v26, v24
	v_add_f32_e32 v8, 1.0, v20
	v_rcp_f32_e32 v8, v8
	v_mul_f32_e32 v4, v4, v16
	v_mul_f32_e32 v2, v2, v24
	s_waitcnt vmcnt(7)
	v_lshlrev_b32_e32 v20, 16, v21
	v_mul_f32_e32 v21, 0xbfb8aa3b, v20
	v_exp_f32_e32 v21, v21
	v_mul_f32_e32 v4, v4, v8
	v_add_f32_e32 v8, 1.0, v21
	v_rcp_f32_e32 v8, v8
	v_cvt_pk_bf16_f32 v4, v4, v33
	global_store_short v[0:1], v4, off offset:32
	v_mul_f32_e32 v4, v22, v24
	v_mul_f32_e32 v4, v4, v20
	s_waitcnt vmcnt(6)
	v_lshlrev_b32_e32 v9, 16, v9
	v_mul_f32_e32 v20, 0xbfb8aa3b, v9
	v_exp_f32_e32 v20, v20
	v_mul_f32_e32 v4, v4, v8
	v_cvt_pk_bf16_f32 v4, v4, v33
	global_store_short v[0:1], v4, off offset:64
	v_add_f32_e32 v8, 1.0, v20
	v_rcp_f32_e32 v8, v8
	v_mul_f32_e32 v4, v14, v24
	v_mul_f32_e32 v4, v4, v9
	s_waitcnt vmcnt(6)
	v_lshlrev_b32_e32 v12, 16, v12
	v_mul_f32_e32 v14, 0xbfb8aa3b, v12
	v_exp_f32_e32 v14, v14
	v_mul_f32_e32 v4, v4, v8
	v_cvt_pk_bf16_f32 v4, v4, v33
	v_add_f32_e32 v8, 1.0, v14
	v_rcp_f32_e32 v8, v8
	global_store_short v[0:1], v4, off offset:96
	v_mul_f32_e32 v4, v10, v24
	v_mul_f32_e32 v4, v4, v12
	s_waitcnt vmcnt(6)
	v_lshlrev_b32_e32 v10, 16, v13
	v_mul_f32_e32 v12, 0xbfb8aa3b, v10
	v_exp_f32_e32 v12, v12
	v_mul_f32_e32 v4, v4, v8
	v_cvt_pk_bf16_f32 v4, v4, v33
	v_add_f32_e32 v8, 1.0, v12
	v_rcp_f32_e32 v12, v8
	global_store_short v[0:1], v4, off offset:128
	v_mul_f32_e32 v4, v6, v24
	v_mul_f32_e32 v4, v4, v10
	s_waitcnt vmcnt(6)
	v_lshlrev_b32_e32 v10, 16, v17
	v_mul_f32_e32 v9, 0xbfb8aa3b, v10
	v_exp_f32_e32 v9, v9
	v_mov_b32_e32 v6, v12
	v_mul_f32_e32 v4, v4, v6
	v_cvt_pk_bf16_f32 v6, v4, v33
	v_add_u32_e32 v4, 3, v38
	v_add_f32_e32 v14, 1.0, v9
	v_mad_i64_i32 v[8:9], s[4:5], v4, s37, v[36:37]
	v_lshl_add_u64 v[8:9], v[8:9], 0, s[22:23]
	v_lshl_add_u64 v[8:9], v[8:9], 0, v[34:35]
	v_add_co_u32_e32 v12, vcc, s39, v8
	global_store_short v[0:1], v6, off offset:160
	s_nop 0
	v_addc_co_u32_e32 v13, vcc, 0, v9, vcc
	global_load_ushort v16, v[12:13], off offset:3072
	v_rcp_f32_e32 v6, v14
	v_mul_f32_e32 v2, v2, v10
	s_waitcnt vmcnt(7)
	v_lshlrev_b32_e32 v5, 16, v5
	v_lshl_add_u64 v[8:9], v[8:9], 0, s[40:41]
	v_mul_f32_e32 v2, v2, v6
	v_mul_f32_e32 v6, 0xbfb8aa3b, v5
	v_exp_f32_e32 v20, v6
	v_mul_f32_e32 v6, v27, v27
	v_mov_b32_e32 v14, v23
	v_fmac_f32_e32 v6, v31, v31
	global_load_ushort v17, v[8:9], off offset:32
	v_fma_f32 v6, v14, v14, v6
	v_fma_f32 v14, v15, v15, v6
	v_mov_b32_e32 v6, v11
	v_mul_f32_e32 v10, v18, v24
	v_fma_f32 v6, v6, v6, v14
	v_mov_b32_e32 v18, v3
	v_fma_f32 v6, v7, v7, v6
	v_cvt_pk_bf16_f32 v2, v2, v33
	global_store_short v[0:1], v2, off offset:192
	v_fma_f32 v6, v18, v18, v6
	v_fma_f32 v6, v19, v19, v6
	ds_bpermute_b32 v12, v32, v6
	v_add_f32_e32 v13, 1.0, v20
	v_rcp_f32_e32 v18, v13
	s_waitcnt lgkmcnt(0)
	v_add_f32_e32 v6, v6, v12
	ds_bpermute_b32 v12, v44, v6
	global_load_ushort v20, v[8:9], off offset:64
	v_mul_f32_e32 v2, v10, v5
	s_waitcnt lgkmcnt(0)
	v_add_f32_e32 v5, v6, v12
	ds_bpermute_b32 v6, v45, v5
	s_waitcnt lgkmcnt(0)
	v_add_f32_e32 v5, v5, v6
	ds_bpermute_b32 v6, v46, v5
	v_mov_b32_e32 v10, v18
	s_waitcnt lgkmcnt(0)
	v_add_f32_e32 v5, v5, v6
	v_fmamk_f32 v5, v5, 0x3c000000, v50
	v_mul_f32_e32 v6, 0x4b800000, v5
	v_cmp_gt_f32_e32 vcc, s60, v5
	v_mul_f32_e32 v2, v2, v10
	v_cvt_pk_bf16_f32 v2, v2, v33
	global_store_short v[0:1], v2, off offset:224
	v_cndmask_b32_e32 v5, v5, v6, vcc
	global_load_ushort v6, v[8:9], off offset:96
	global_load_ushort v2, v[8:9], off offset:128
	global_load_ushort v10, v[8:9], off offset:160
	global_load_ushort v12, v[8:9], off offset:192
	s_nop 0
	global_load_ushort v8, v[8:9], off offset:224
	v_rsq_f32_e32 v5, v5
	s_waitcnt vmcnt(9)
	v_lshlrev_b32_e32 v9, 16, v16
	v_mul_f32_e32 v1, 0xbfb8aa3b, v9
	v_exp_f32_e32 v13, v1
	v_mul_f32_e32 v0, 0x45800000, v5
	v_cndmask_b32_e32 v14, v5, v0, vcc
	v_ashrrev_i32_e32 v5, 31, v4
	v_lshlrev_b64 v[0:1], 12, v[4:5]
	v_add_f32_e32 v4, 1.0, v13
	v_rcp_f32_e32 v4, v4
	v_mul_f32_e32 v16, v31, v14
	v_mul_f32_e32 v9, v16, v9
	v_lshl_add_u64 v[0:1], s[2:3], 0, v[0:1]
	s_waitcnt vmcnt(8)
	v_lshlrev_b32_e32 v5, 16, v17
	v_mul_f32_e32 v13, 0xbfb8aa3b, v5
	v_exp_f32_e32 v13, v13
	v_mul_f32_e32 v4, v4, v9
	v_cvt_pk_bf16_f32 v4, v4, v33
	v_lshl_add_u64 v[0:1], v[0:1], 0, v[34:35]
	v_add_f32_e32 v9, 1.0, v13
	global_store_short v[0:1], v4, off
	v_mul_f32_e32 v4, v27, v14
	v_mul_f32_e32 v4, v4, v5
	s_waitcnt vmcnt(7)
	v_lshlrev_b32_e32 v13, 16, v20
	v_mul_f32_e32 v16, 0xbfb8aa3b, v13
	v_exp_f32_e32 v16, v16
	v_rcp_f32_e32 v5, v9
	s_nop 0
	v_mul_f32_e32 v4, v4, v5
	v_cvt_pk_bf16_f32 v4, v4, v33
	v_add_f32_e32 v5, 1.0, v16
	v_rcp_f32_e32 v5, v5
	global_store_short v[0:1], v4, off offset:32
	v_mul_f32_e32 v4, v23, v14
	v_mul_f32_e32 v4, v4, v13
	s_waitcnt vmcnt(6)
	v_lshlrev_b32_e32 v6, 16, v6
	v_mul_f32_e32 v13, 0xbfb8aa3b, v6
	v_exp_f32_e32 v13, v13
	v_mul_f32_e32 v4, v4, v5
	v_cvt_pk_bf16_f32 v4, v4, v33
	global_store_short v[0:1], v4, off offset:64
	v_add_f32_e32 v5, 1.0, v13
	v_rcp_f32_e32 v5, v5
	v_mul_f32_e32 v4, v15, v14
	v_mul_f32_e32 v4, v4, v6
	s_waitcnt vmcnt(6)
	v_lshlrev_b32_e32 v2, 16, v2
	v_mul_f32_e32 v9, 0xbfb8aa3b, v2
	v_exp_f32_e32 v9, v9
	v_mul_f32_e32 v4, v4, v5
	v_add_f32_e32 v5, 1.0, v9
	v_cvt_pk_bf16_f32 v4, v4, v33
	global_store_short v[0:1], v4, off offset:96
	v_mul_f32_e32 v4, v11, v14
	v_mul_f32_e32 v2, v4, v2
	s_waitcnt vmcnt(6)
	v_lshlrev_b32_e32 v6, 16, v10
	v_mul_f32_e32 v9, 0xbfb8aa3b, v6
	v_exp_f32_e32 v9, v9
	v_rcp_f32_e32 v4, v5
	s_nop 0
	v_mul_f32_e32 v2, v2, v4
	v_cvt_pk_bf16_f32 v2, v2, v33
	v_add_f32_e32 v4, 1.0, v9
	v_rcp_f32_e32 v4, v4
	global_store_short v[0:1], v2, off offset:128
	v_mul_f32_e32 v2, v7, v14
	v_mul_f32_e32 v2, v2, v6
	s_waitcnt vmcnt(6)
	v_lshlrev_b32_e32 v6, 16, v12
	v_mul_f32_e32 v7, 0xbfb8aa3b, v6
	v_exp_f32_e32 v7, v7
	v_mul_f32_e32 v2, v2, v4
	v_cvt_pk_bf16_f32 v2, v2, v33
	v_add_f32_e32 v4, 1.0, v7
	v_rcp_f32_e32 v7, v4
	global_store_short v[0:1], v2, off offset:160
	v_mul_f32_e32 v2, v3, v14
	v_mul_f32_e32 v2, v2, v6
	s_waitcnt vmcnt(6)
	v_lshlrev_b32_e32 v5, 16, v8
	v_mul_f32_e32 v6, 0xbfb8aa3b, v5
	v_exp_f32_e32 v6, v6
	v_mov_b32_e32 v3, v7
	v_mul_f32_e32 v2, v2, v3
	v_cvt_pk_bf16_f32 v2, v2, v33
	v_add_f32_e32 v3, 1.0, v6
	v_rcp_f32_e32 v3, v3
	global_store_short v[0:1], v2, off offset:192
	v_mul_f32_e32 v2, v19, v14
	v_mul_f32_e32 v2, v2, v5
	v_mul_f32_e32 v2, v2, v3
	s_mov_b64 s[2:3], 0
	v_cvt_pk_bf16_f32 v2, v2, v33
	global_store_short v[0:1], v2, off offset:224
	s_barrier

; __device__ __forceinline__ unsigned short f2bf(float f) { return (unsigned short)(cvt_pk_bf16(f, 0.f) & 0xffffu); }
; __device__ __forceinline__ void retout_item(PRef p, int layer, int item, unsigned char* shm) {
;     ...
;     { const float* SF = (const float*)(p.ws + O_RETST) + ((size_t)((b * 8 + h) * 2 + 0) * 34 + cidx) * 8192;
;       const float* SB = (const float*)(p.ws + O_RETST) + ((size_t)((b * 8 + h) * 2 + 1) * 34 + cidx) * 8192;
; #pragma unroll 4
;       for (int i = 0; i < 16; ++i) { const int idx = tid + 512 * i, d = idx >> 7, e = idx & 127;
;           sTf[e * 72 + d] = f2bf(SF[idx]); sTb[e * 72 + d] = f2bf(SB[idx]); } }
.LBB0_921:
	v_add_u32_e32 v3, s12, v8
	v_add_co_u32_e32 v4, vcc, 0x110000, v0
	v_add_u32_e32 v6, 0x400, v3
	s_nop 0
	v_addc_co_u32_e32 v5, vcc, 0, v1, vcc
	v_add_u32_e32 v14, 0x600, v3
	v_ashrrev_i32_e32 v7, 31, v6
	global_load_dword v9, v[0:1], off
	global_load_dword v10, v[0:1], off offset:2048
	global_load_dword v13, v[4:5], off
	global_load_dword v22, v[4:5], off offset:2048
	v_ashrrev_i32_e32 v15, 31, v14
	v_lshlrev_b64 v[4:5], 2, v[6:7]
	v_lshlrev_b64 v[16:17], 2, v[14:15]
	v_lshl_add_u64 v[18:19], s[36:37], 0, v[4:5]
	v_lshl_add_u64 v[4:5], s[38:39], 0, v[4:5]
	v_lshl_add_u64 v[20:21], s[36:37], 0, v[16:17]
	v_lshl_add_u64 v[16:17], s[38:39], 0, v[16:17]
	global_load_dword v7, v[18:19], off
	s_nop 0
	global_load_dword v4, v[4:5], off
	s_nop 0
	global_load_dword v5, v[20:21], off
	global_load_dword v15, v[16:17], off
	v_ashrrev_i32_e32 v16, 7, v3
	v_add_u32_e32 v3, 0x200, v3
	v_add_u32_e32 v16, v16, v2
	v_ashrrev_i32_e32 v3, 7, v3
	v_ashrrev_i32_e32 v6, 7, v6
	v_lshl_add_u32 v16, v16, 1, 0
	v_add_u32_e32 v3, v3, v2
	s_addk_i32 s12, 0x800
	v_ashrrev_i32_e32 v14, 7, v14
	v_add_u32_e32 v6, v6, v2
	v_lshl_add_u32 v3, v3, 1, 0
	v_lshl_add_u64 v[0:1], v[0:1], 0, s[22:23]
	v_add_u32_e32 v14, v14, v2
	v_lshl_add_u32 v6, v6, 1, 0
	v_lshl_add_u32 v14, v14, 1, 0
	v_add_u32_e32 v149, s12, v8
	v_add_co_u32_e32 v150, vcc, 0x110000, v0
	v_add_u32_e32 v152, 0x400, v149
	s_nop 0
	v_addc_co_u32_e32 v151, vcc, 0, v1, vcc
	v_add_u32_e32 v160, 0x600, v149
	v_ashrrev_i32_e32 v153, 31, v152
	global_load_dword v155, v[0:1], off
	global_load_dword v156, v[0:1], off offset:2048
	global_load_dword v159, v[150:151], off
	global_load_dword v168, v[150:151], off offset:2048
	v_ashrrev_i32_e32 v161, 31, v160
	v_lshlrev_b64 v[150:151], 2, v[152:153]
	v_lshlrev_b64 v[162:163], 2, v[160:161]
	v_lshl_add_u64 v[164:165], s[36:37], 0, v[150:151]
	v_lshl_add_u64 v[150:151], s[38:39], 0, v[150:151]
	v_lshl_add_u64 v[166:167], s[36:37], 0, v[162:163]
	v_lshl_add_u64 v[162:163], s[38:39], 0, v[162:163]
	global_load_dword v153, v[164:165], off
	s_nop 0
	global_load_dword v150, v[150:151], off
	s_nop 0
	global_load_dword v151, v[166:167], off
	global_load_dword v161, v[162:163], off
	v_ashrrev_i32_e32 v162, 7, v149
	v_add_u32_e32 v149, 0x200, v149
	v_add_u32_e32 v162, v162, v2
	v_ashrrev_i32_e32 v149, 7, v149
	v_ashrrev_i32_e32 v152, 7, v152
	v_lshl_add_u32 v162, v162, 1, 0
	v_add_u32_e32 v149, v149, v2
	s_addk_i32 s12, 0x800
	v_ashrrev_i32_e32 v160, 7, v160
	v_add_u32_e32 v152, v152, v2
	v_lshl_add_u32 v149, v149, 1, 0
	v_lshl_add_u64 v[0:1], v[0:1], 0, s[22:23]
	v_add_u32_e32 v160, v160, v2
	v_lshl_add_u32 v152, v152, 1, 0
	v_lshl_add_u32 v160, v160, 1, 0
	v_add_u32_e32 v173, s12, v8
	v_add_co_u32_e32 v174, vcc, 0x110000, v0
	v_add_u32_e32 v176, 0x400, v173
	s_nop 0
	v_addc_co_u32_e32 v175, vcc, 0, v1, vcc
	v_add_u32_e32 v184, 0x600, v173
	v_ashrrev_i32_e32 v177, 31, v176
	global_load_dword v179, v[0:1], off
	global_load_dword v180, v[0:1], off offset:2048
	global_load_dword v183, v[174:175], off
	global_load_dword v192, v[174:175], off offset:2048
	v_ashrrev_i32_e32 v185, 31, v184
	v_lshlrev_b64 v[174:175], 2, v[176:177]
	v_lshlrev_b64 v[186:187], 2, v[184:185]
	v_lshl_add_u64 v[188:189], s[36:37], 0, v[174:175]
	v_lshl_add_u64 v[174:175], s[38:39], 0, v[174:175]
	v_lshl_add_u64 v[190:191], s[36:37], 0, v[186:187]
	v_lshl_add_u64 v[186:187], s[38:39], 0, v[186:187]
	global_load_dword v177, v[188:189], off
	s_nop 0
	global_load_dword v174, v[174:175], off
	s_nop 0
	global_load_dword v175, v[190:191], off
	global_load_dword v185, v[186:187], off
	v_ashrrev_i32_e32 v186, 7, v173
	v_add_u32_e32 v173, 0x200, v173
	v_add_u32_e32 v186, v186, v2
	v_ashrrev_i32_e32 v173, 7, v173
	v_ashrrev_i32_e32 v176, 7, v176
	v_lshl_add_u32 v186, v186, 1, 0
	v_add_u32_e32 v173, v173, v2
	s_addk_i32 s12, 0x800
	v_ashrrev_i32_e32 v184, 7, v184
	v_add_u32_e32 v176, v176, v2
	v_lshl_add_u32 v173, v173, 1, 0
	v_lshl_add_u64 v[0:1], v[0:1], 0, s[22:23]
	v_add_u32_e32 v184, v184, v2
	v_lshl_add_u32 v176, v176, 1, 0
	v_lshl_add_u32 v184, v184, 1, 0
	v_add_u32_e32 v197, s12, v8
	v_add_co_u32_e32 v198, vcc, 0x110000, v0
	v_add_u32_e32 v200, 0x400, v197
	s_nop 0
	v_addc_co_u32_e32 v199, vcc, 0, v1, vcc
	v_add_u32_e32 v208, 0x600, v197
	v_ashrrev_i32_e32 v201, 31, v200
	global_load_dword v203, v[0:1], off
	global_load_dword v204, v[0:1], off offset:2048
	global_load_dword v207, v[198:199], off
	global_load_dword v216, v[198:199], off offset:2048
	v_ashrrev_i32_e32 v209, 31, v208
	v_lshlrev_b64 v[198:199], 2, v[200:201]
	v_lshlrev_b64 v[210:211], 2, v[208:209]
	v_lshl_add_u64 v[212:213], s[36:37], 0, v[198:199]
	v_lshl_add_u64 v[198:199], s[38:39], 0, v[198:199]
	v_lshl_add_u64 v[214:215], s[36:37], 0, v[210:211]
	v_lshl_add_u64 v[210:211], s[38:39], 0, v[210:211]
	global_load_dword v201, v[212:213], off
	s_nop 0
	global_load_dword v198, v[198:199], off
	s_nop 0
	global_load_dword v199, v[214:215], off
	global_load_dword v209, v[210:211], off
	v_ashrrev_i32_e32 v210, 7, v197
	v_add_u32_e32 v197, 0x200, v197
	v_add_u32_e32 v210, v210, v2
	v_ashrrev_i32_e32 v197, 7, v197
	v_ashrrev_i32_e32 v200, 7, v200
	v_lshl_add_u32 v210, v210, 1, 0
	v_add_u32_e32 v197, v197, v2
	s_addk_i32 s12, 0x800
	v_ashrrev_i32_e32 v208, 7, v208
	v_add_u32_e32 v200, v200, v2
	v_lshl_add_u32 v197, v197, 1, 0
	v_lshl_add_u64 v[0:1], v[0:1], 0, s[22:23]
	v_add_u32_e32 v208, v208, v2
	v_lshl_add_u32 v200, v200, 1, 0
	v_lshl_add_u32 v208, v208, 1, 0
	s_waitcnt vmcnt(31)
	v_cvt_pk_bf16_f32 v9, v9, v33
	ds_write_b16 v16, v9 offset:34816
	s_waitcnt vmcnt(29)
	v_cvt_pk_bf16_f32 v9, v13, v33
	v_cvt_pk_bf16_f32 v10, v10, v33
	s_waitcnt vmcnt(28)
; __device__ __forceinline__ unsigned short f2bf(float f) { return (unsigned short)(cvt_pk_bf16(f, 0.f) & 0xffffu); }
; __device__ __forceinline__ void retout_item(PRef p, int layer, int item, unsigned char* shm) {
;     ...
;     { const float* SF = (const float*)(p.ws + O_RETST) + ((size_t)((b * 8 + h) * 2 + 0) * 34 + cidx) * 8192;
;       const float* SB = (const float*)(p.ws + O_RETST) + ((size_t)((b * 8 + h) * 2 + 1) * 34 + cidx) * 8192;
; #pragma unroll 4
;       for (int i = 0; i < 16; ++i) { const int idx = tid + 512 * i, d = idx >> 7, e = idx & 127;
;           sTf[e * 72 + d] = f2bf(SF[idx]); sTb[e * 72 + d] = f2bf(SB[idx]); } }
;     __syncthreads();
;     bf16x8 qa[2];
; #pragma unroll
;     for (int kk = 0; kk < 2; ++kk) qa[kk] = *(const bf16x8*)(A + (size_t)(row0 + 16 * wave + fr) * NIN + C_Q + h * 64 + kk * 32 + fq * 8);
; #pragma unroll
;     for (int nt = 0; nt < 8; ++nt) { f32x4 s = (f32x4){0.f, 0.f, 0.f, 0.f};
; #pragma unroll
;         for (int kk = 0; kk < 2; ++kk) { const bf16x8 kb = *(const bf16x8*)(A + (size_t)(row0 + 16 * nt + fr) * NIN + C_K + h * 64 + kk * 32 + fq * 8);
;             s = __builtin_amdgcn_mfma_f32_16x16x32_bf16(qa[kk], kb, s, 0, 0, 0); }
;         const int m = 16 * nt + fr;
; #pragma unroll
;         for (int r = 0; r < 4; ++r) { const int c = 16 * wave + fq * 4 + r; const float dd = (float)(c - m);
;             const float dec = (m <= c) ? expf(dd * lgf) : expf(-dd * lgb);
;             Pw[(fq * 4 + r) * LDK + m] = f2bf(s[r] * 0.125f * dec); } }
	v_cvt_pk_bf16_f32 v13, v22, v33
	ds_write_b16 v16, v9 offset:53248
	ds_write_b16 v3, v10 offset:34816
	ds_write_b16 v3, v13 offset:53248
	s_waitcnt vmcnt(27)
	v_cvt_pk_bf16_f32 v3, v7, v33
	s_waitcnt vmcnt(26)
	v_cvt_pk_bf16_f32 v4, v4, v33
	s_waitcnt vmcnt(25)
	v_cvt_pk_bf16_f32 v5, v5, v33
	s_waitcnt vmcnt(24)
	v_cvt_pk_bf16_f32 v7, v15, v33
	ds_write_b16 v6, v3 offset:34816
	ds_write_b16 v6, v4 offset:53248
	ds_write_b16 v14, v5 offset:34816
	ds_write_b16 v14, v7 offset:53248
	s_waitcnt vmcnt(23)
	v_cvt_pk_bf16_f32 v155, v155, v33
	ds_write_b16 v162, v155 offset:34816
	s_waitcnt vmcnt(21)
	v_cvt_pk_bf16_f32 v155, v159, v33
	v_cvt_pk_bf16_f32 v156, v156, v33
	s_waitcnt vmcnt(20)
	v_cvt_pk_bf16_f32 v159, v168, v33
	ds_write_b16 v162, v155 offset:53248
	ds_write_b16 v149, v156 offset:34816
	ds_write_b16 v149, v159 offset:53248
	s_waitcnt vmcnt(19)
	v_cvt_pk_bf16_f32 v149, v153, v33
	s_waitcnt vmcnt(18)
	v_cvt_pk_bf16_f32 v150, v150, v33
	s_waitcnt vmcnt(17)
	v_cvt_pk_bf16_f32 v151, v151, v33
	s_waitcnt vmcnt(16)
	v_cvt_pk_bf16_f32 v153, v161, v33
	ds_write_b16 v152, v149 offset:34816
	ds_write_b16 v152, v150 offset:53248
	ds_write_b16 v160, v151 offset:34816
	ds_write_b16 v160, v153 offset:53248
	s_waitcnt vmcnt(15)
	v_cvt_pk_bf16_f32 v179, v179, v33
	ds_write_b16 v186, v179 offset:34816
	s_waitcnt vmcnt(13)
	v_cvt_pk_bf16_f32 v179, v183, v33
	v_cvt_pk_bf16_f32 v180, v180, v33
	s_waitcnt vmcnt(12)
	v_cvt_pk_bf16_f32 v183, v192, v33
	ds_write_b16 v186, v179 offset:53248
	ds_write_b16 v173, v180 offset:34816
	ds_write_b16 v173, v183 offset:53248
	s_waitcnt vmcnt(11)
	v_cvt_pk_bf16_f32 v173, v177, v33
	s_waitcnt vmcnt(10)
	v_cvt_pk_bf16_f32 v174, v174, v33
	s_waitcnt vmcnt(9)
	v_cvt_pk_bf16_f32 v175, v175, v33
	s_waitcnt vmcnt(8)
	v_cvt_pk_bf16_f32 v177, v185, v33
	ds_write_b16 v176, v173 offset:34816
	ds_write_b16 v176, v174 offset:53248
	ds_write_b16 v184, v175 offset:34816
	ds_write_b16 v184, v177 offset:53248
	s_waitcnt vmcnt(7)
	v_cvt_pk_bf16_f32 v203, v203, v33
	ds_write_b16 v210, v203 offset:34816
	s_waitcnt vmcnt(5)
	v_cvt_pk_bf16_f32 v203, v207, v33
	v_cvt_pk_bf16_f32 v204, v204, v33
	s_waitcnt vmcnt(4)
	v_cvt_pk_bf16_f32 v207, v216, v33
	ds_write_b16 v210, v203 offset:53248
	ds_write_b16 v197, v204 offset:34816
	ds_write_b16 v197, v207 offset:53248
	s_waitcnt vmcnt(3)
	v_cvt_pk_bf16_f32 v197, v201, v33
	s_waitcnt vmcnt(2)
	v_cvt_pk_bf16_f32 v198, v198, v33
	s_waitcnt vmcnt(1)
	v_cvt_pk_bf16_f32 v199, v199, v33
	s_waitcnt vmcnt(0)
	v_cvt_pk_bf16_f32 v201, v209, v33
	ds_write_b16 v200, v197 offset:34816
	ds_write_b16 v200, v198 offset:53248
	ds_write_b16 v208, v199 offset:34816
	ds_write_b16 v208, v201 offset:53248
	v_ashrrev_i32_e32 v10, 2, v8
	v_and_b32_e32 v9, 15, v8
	v_and_b32_e32 v14, -16, v10
	v_or_b32_e32 v15, s62, v9
	v_add_u32_e32 v0, v15, v14
	v_mov_b64_e32 v[36:37], s[10:11]
	v_bfe_u32 v13, v8, 4, 2
	v_mad_i64_i32 v[0:1], s[36:37], v0, s46, v[36:37]
	s_mov_b32 s35, s21
	v_lshl_add_u64 v[0:1], v[0:1], 0, s[34:35]
	v_lshlrev_b32_e32 v32, 4, v13
	v_lshl_add_u64 v[0:1], v[0:1], 0, v[32:33]
	s_waitcnt lgkmcnt(0)
	s_barrier
	global_load_dwordx4 v[4:7], v[0:1], off offset:3072
	v_mad_u64_u32 v[2:3], s[36:37], v15, s46, v[36:37]
	v_lshl_add_u64 v[2:3], v[2:3], 0, s[34:35]
	v_lshl_add_u64 v[16:17], v[2:3], 0, v[32:33]
	v_add_co_u32_e32 v2, vcc, s48, v16
	v_mul_lo_u32 v30, v14, s47
	s_nop 0
	v_addc_co_u32_e32 v3, vcc, 0, v17, vcc
	global_load_dwordx4 v[20:23], v[2:3], off
	s_nop 0
	global_load_dwordx4 v[0:3], v[0:1], off offset:3136
	v_lshl_add_u64 v[16:17], v[16:17], 0, s[24:25]
	global_load_dwordx4 v[24:27], v[16:17], off offset:64
	v_mul_f32_e32 v16, 0x3fb8aa3b, v11
	v_mul_f32_e32 v17, 0x3fb8aa3b, v12
	v_rndne_f32_e32 v18, v16
	v_fma_f32 v19, v11, s50, -v16
	v_rndne_f32_e32 v28, v17
	v_fma_f32 v29, v12, s50, -v17
	v_sub_f32_e32 v31, v16, v18
	v_fmac_f32_e32 v19, 0x32a5705f, v11
	v_sub_f32_e32 v17, v17, v28
	v_fmac_f32_e32 v29, 0x32a5705f, v12
	v_add_f32_e32 v19, v31, v19
	v_cvt_i32_f32_e32 v35, v18
	v_add_f32_e32 v17, v17, v29
	v_exp_f32_e32 v19, v19
	v_cvt_i32_f32_e32 v40, v28
	v_exp_f32_e32 v17, v17
	v_lshl_or_b32 v16, v13, 2, v14
	v_ldexp_f32 v19, v19, v35
	v_cmp_ngt_f32_e32 vcc, s51, v11
	v_add_u32_e32 v14, s53, v30
	v_sub_u32_e32 v30, v16, v9
	v_ldexp_f32 v17, v17, v40
	v_cndmask_b32_e32 v19, 0, v19, vcc
	v_cmp_ngt_f32_e32 vcc, s51, v12
	v_cvt_f32_i32_e32 v30, v30
	v_or_b32_e32 v28, 16, v15
	v_cndmask_b32_e32 v17, 0, v17, vcc
	v_cmp_nlt_f32_e32 vcc, s52, v11
	v_mad_u64_u32 v[28:29], s[36:37], v28, s46, v[36:37]
	s_nop 0
	v_cndmask_b32_e32 v11, v63, v19, vcc
	v_cmp_nlt_f32_e32 vcc, s52, v12
	v_lshl_add_u64 v[28:29], v[28:29], 0, s[34:35]
	v_lshl_add_u64 v[38:39], v[28:29], 0, v[32:33]
	v_cndmask_b32_e32 v12, v63, v17, vcc
	v_cmp_lt_i32_e32 vcc, v16, v9
	v_or_b32_e32 v18, 1, v16
	v_sub_u32_e32 v31, v18, v9
	v_cndmask_b32_e64 v17, -v12, v11, vcc
	v_mul_f32_e32 v17, v17, v30
	v_mul_f32_e32 v19, 0x3fb8aa3b, v17
	v_fma_f32 v28, v17, s50, -v19
	v_rndne_f32_e32 v29, v19
	v_fmac_f32_e32 v28, 0x32a5705f, v17
	v_sub_f32_e32 v19, v19, v29
	v_add_f32_e32 v19, v19, v28
	v_add_co_u32_e32 v28, vcc, s48, v38
	v_cvt_i32_f32_e32 v35, v29
	s_nop 0
	v_addc_co_u32_e32 v29, vcc, 0, v39, vcc
	v_cvt_f32_i32_e32 v41, v31
	global_load_dwordx4 v[28:31], v[28:29], off
	v_lshl_add_u64 v[38:39], v[38:39], 0, s[24:25]
	v_exp_f32_e32 v19, v19
	v_cmp_ngt_f32_e32 vcc, s51, v17
	v_lshlrev_b32_e32 v34, 1, v9
	v_mad_u32_u24 v75, v9, s47, v64
	v_ldexp_f32 v19, v19, v35
	v_cndmask_b32_e32 v19, 0, v19, vcc
	v_cmp_nlt_f32_e32 vcc, s52, v17
	s_waitcnt vmcnt(3)
	v_mfma_f32_16x16x32_bf16 v[20:23], v[4:7], v[20:23], 0
	v_cndmask_b32_e32 v17, v63, v19, vcc
	v_cmp_lt_i32_e32 vcc, v18, v9
	v_bitop3_b32 v103, v9, s55, v70 bitop3:0xc8
	s_waitcnt vmcnt(1)
; __device__ __forceinline__ unsigned short f2bf(float f) { return (unsigned short)(cvt_pk_bf16(f, 0.f) & 0xffffu); }
; __device__ __forceinline__ void retout_item(PRef p, int layer, int item, unsigned char* shm) {
;     ...
;     for (int nt = 0; nt < 8; ++nt) { f32x4 s = (f32x4){0.f, 0.f, 0.f, 0.f};
; #pragma unroll
;         for (int kk = 0; kk < 2; ++kk) { const bf16x8 kb = *(const bf16x8*)(A + (size_t)(row0 + 16 * nt + fr) * NIN + C_K + h * 64 + kk * 32 + fq * 8);
;             s = __builtin_amdgcn_mfma_f32_16x16x32_bf16(qa[kk], kb, s, 0, 0, 0); }
;         const int m = 16 * nt + fr;
; #pragma unroll
;         for (int r = 0; r < 4; ++r) { const int c = 16 * wave + fq * 4 + r; const float dd = (float)(c - m);
;             const float dec = (m <= c) ? expf(dd * lgf) : expf(-dd * lgb);
;             Pw[(fq * 4 + r) * LDK + m] = f2bf(s[r] * 0.125f * dec); } }
	v_mfma_f32_16x16x32_bf16 v[20:23], v[0:3], v[24:27], v[20:23]
	global_load_dwordx4 v[24:27], v[38:39], off offset:64
	v_cndmask_b32_e64 v19, -v12, v11, vcc
	v_mul_f32_e32 v19, v19, v41
	v_mul_f32_e32 v35, 0x3fb8aa3b, v19
	v_fma_f32 v40, v19, s50, -v35
	s_nop 2
	v_mul_f32_e32 v20, 0x3e000000, v20
	v_mul_f32_e32 v17, v17, v20
	v_cvt_pk_bf16_f32 v20, v17, v33
	v_rndne_f32_e32 v17, v35
	v_fmac_f32_e32 v40, 0x32a5705f, v19
	v_sub_f32_e32 v35, v35, v17
	v_add_f32_e32 v35, v35, v40
	v_exp_f32_e32 v35, v35
	v_cvt_i32_f32_e32 v38, v17
	v_mul_u32_u24_e32 v17, 0x440, v13
	v_add3_u32 v17, v14, v34, v17
	ds_write_b16 v17, v20
	v_ldexp_f32 v20, v35, v38
	v_cmp_ngt_f32_e32 vcc, s51, v19
	v_mul_f32_e32 v21, 0x3e000000, v21
	v_mul_f32_e32 v22, 0x3e000000, v22
	v_cndmask_b32_e32 v20, 0, v20, vcc
	v_cmp_nlt_f32_e32 vcc, s52, v19
	s_waitcnt vmcnt(1)
	v_mfma_f32_16x16x32_bf16 v[28:31], v[4:7], v[28:31], 0
	v_cndmask_b32_e32 v19, v63, v20, vcc
	v_or_b32_e32 v20, 2, v16
	v_sub_u32_e32 v35, v20, v9
	v_cvt_f32_i32_e32 v35, v35
	v_cmp_lt_i32_e32 vcc, v20, v9
	v_mul_f32_e32 v19, v19, v21
	v_cvt_pk_bf16_f32 v19, v19, v33
	ds_write_b16 v17, v19 offset:272
	v_cndmask_b32_e64 v38, -v12, v11, vcc
	v_mul_f32_e32 v35, v38, v35
	v_mul_f32_e32 v38, 0x3fb8aa3b, v35
	v_fma_f32 v39, v35, s50, -v38
	v_rndne_f32_e32 v40, v38
	v_fmac_f32_e32 v39, 0x32a5705f, v35
	v_sub_f32_e32 v38, v38, v40
	v_add_f32_e32 v38, v38, v39
	v_exp_f32_e32 v38, v38
	v_cvt_i32_f32_e32 v39, v40
	v_cmp_ngt_f32_e32 vcc, s51, v35
	v_lshlrev_b32_e32 v13, 3, v13
	v_bitop3_b32 v105, v9, s45, v72 bitop3:0xc8
	v_ldexp_f32 v19, v38, v39
	v_cndmask_b32_e32 v19, 0, v19, vcc
	v_cmp_nlt_f32_e32 vcc, s52, v35
	v_add_u32_e32 v88, v13, v103
	v_add_u32_e32 v92, v13, v105
	v_cndmask_b32_e32 v21, v63, v19, vcc
	v_or_b32_e32 v19, 3, v16
	v_sub_u32_e32 v35, v19, v9
	v_cvt_f32_i32_e32 v35, v35
	v_cmp_lt_i32_e32 vcc, v19, v9
	v_mul_f32_e32 v21, v21, v22
	v_cvt_pk_bf16_f32 v21, v21, v33
	ds_write_b16 v17, v21 offset:544
	v_cndmask_b32_e64 v38, -v12, v11, vcc
	v_mul_f32_e32 v35, v38, v35
	v_mul_f32_e32 v38, 0x3fb8aa3b, v35
	v_fma_f32 v39, v35, s50, -v38
	v_rndne_f32_e32 v40, v38
	v_fmac_f32_e32 v39, 0x32a5705f, v35
	v_sub_f32_e32 v38, v38, v40
	v_add_f32_e32 v38, v38, v39
	v_exp_f32_e32 v38, v38
	v_cvt_i32_f32_e32 v39, v40
	v_cmp_ngt_f32_e32 vcc, s51, v35
	v_mul_f32_e32 v22, 0x3e000000, v23
	v_bitop3_b32 v97, v9, 56, 48 bitop3:0xc8
	v_ldexp_f32 v21, v38, v39
	v_cndmask_b32_e32 v21, 0, v21, vcc
	v_cmp_nlt_f32_e32 vcc, s52, v35
	v_or_b32_e32 v35, 16, v9
	v_bitop3_b32 v99, v9, s49, 64 bitop3:0xc8
	v_cndmask_b32_e32 v21, v63, v21, vcc
	v_mul_f32_e32 v21, v21, v22
	v_sub_u32_e32 v22, v16, v35
	v_cvt_f32_i32_e32 v22, v22
	v_cmp_lt_i32_e32 vcc, v16, v35
	v_cvt_pk_bf16_f32 v21, v21, v33
	ds_write_b16 v17, v21 offset:816
	v_bitop3_b32 v101, v9, s54, v68 bitop3:0xc8
	v_cndmask_b32_e64 v23, -v12, v11, vcc
	v_mul_f32_e32 v38, v23, v22
	v_mul_f32_e32 v22, 0x3fb8aa3b, v38
	v_fma_f32 v23, v38, s50, -v22
	v_rndne_f32_e32 v39, v22
	v_fmac_f32_e32 v23, 0x32a5705f, v38
	v_sub_f32_e32 v22, v22, v39
	v_add_f32_e32 v22, v22, v23
	v_exp_f32_e32 v40, v22
	s_waitcnt vmcnt(0)
	v_mfma_f32_16x16x32_bf16 v[22:25], v[0:3], v[24:27], v[28:31]
	v_or_b32_e32 v26, 32, v15
	v_mad_u64_u32 v[26:27], s[36:37], v26, s46, v[36:37]
	v_lshl_add_u64 v[26:27], v[26:27], 0, s[34:35]
	v_lshl_add_u64 v[30:31], v[26:27], 0, v[32:33]
	v_add_co_u32_e32 v26, vcc, s48, v30
	v_cvt_i32_f32_e32 v39, v39
	s_nop 0
	v_addc_co_u32_e32 v27, vcc, 0, v31, vcc
	global_load_dwordx4 v[26:29], v[26:27], off
	v_ldexp_f32 v21, v40, v39
	v_cmp_ngt_f32_e32 vcc, s51, v38
	v_mul_f32_e32 v22, 0x3e000000, v22
	v_lshl_add_u64 v[30:31], v[30:31], 0, s[24:25]
	v_cndmask_b32_e32 v21, 0, v21, vcc
	v_cmp_nlt_f32_e32 vcc, s52, v38
	v_mul_f32_e32 v23, 0x3e000000, v23
	v_and_b32_e32 v88, 0x78, v88
	v_cndmask_b32_e32 v21, v63, v21, vcc
	v_mul_f32_e32 v21, v21, v22
	v_sub_u32_e32 v22, v18, v35
	v_cvt_f32_i32_e32 v22, v22
	v_cmp_lt_i32_e32 vcc, v18, v35
	v_cvt_pk_bf16_f32 v21, v21, v33
	ds_write_b16 v17, v21 offset:32
	v_and_b32_e32 v92, 0x78, v92
	v_cndmask_b32_e64 v38, -v12, v11, vcc
	v_mul_f32_e32 v22, v38, v22
	v_mul_f32_e32 v38, 0x3fb8aa3b, v22
	v_fma_f32 v39, v22, s50, -v38
	v_rndne_f32_e32 v40, v38
	v_fmac_f32_e32 v39, 0x32a5705f, v22
	v_sub_f32_e32 v38, v38, v40
	v_add_f32_e32 v38, v38, v39
	v_exp_f32_e32 v42, v38
	v_cvt_i32_f32_e32 v43, v40
	global_load_dwordx4 v[38:41], v[30:31], off offset:64
	v_cmp_ngt_f32_e32 vcc, s51, v22
	v_mad_u32_u24 v96, v9, s47, v65
	v_ldexp_f32 v21, v42, v43
	v_cndmask_b32_e32 v21, 0, v21, vcc
	v_cmp_nlt_f32_e32 vcc, s52, v22
	v_sub_u32_e32 v22, v20, v35
	v_cvt_f32_i32_e32 v22, v22
	v_cndmask_b32_e32 v21, v63, v21, vcc
	v_cmp_lt_i32_e32 vcc, v20, v35
	v_mul_f32_e32 v21, v21, v23
	v_cvt_pk_bf16_f32 v21, v21, v33
	ds_write_b16 v17, v21 offset:304
	v_cndmask_b32_e64 v30, -v12, v11, vcc
	v_mul_f32_e32 v22, v30, v22
	v_mul_f32_e32 v30, 0x3fb8aa3b, v22
	v_fma_f32 v31, v22, s50, -v30
	v_rndne_f32_e32 v42, v30
	v_fmac_f32_e32 v31, 0x32a5705f, v22
	v_sub_f32_e32 v30, v30, v42
	v_add_f32_e32 v30, v30, v31
	v_exp_f32_e32 v30, v30
	v_cvt_i32_f32_e32 v31, v42
	v_cmp_ngt_f32_e32 vcc, s51, v22
	v_mul_f32_e32 v23, 0x3e000000, v24
	v_lshlrev_b32_e32 v58, 1, v97
	v_ldexp_f32 v21, v30, v31
	v_cndmask_b32_e32 v21, 0, v21, vcc
	v_cmp_nlt_f32_e32 vcc, s52, v22
	v_sub_u32_e32 v22, v19, v35
	v_cvt_f32_i32_e32 v22, v22
	v_cndmask_b32_e32 v21, v63, v21, vcc
	v_cmp_lt_i32_e32 vcc, v19, v35
	v_mul_f32_e32 v21, v21, v23
	v_cvt_pk_bf16_f32 v21, v21, v33
	ds_write_b16 v17, v21 offset:576
	v_cndmask_b32_e64 v24, -v12, v11, vcc
	v_mul_f32_e32 v22, v24, v22
	v_mul_f32_e32 v24, 0x3fb8aa3b, v22
	v_fma_f32 v30, v22, s50, -v24
	v_rndne_f32_e32 v31, v24
	v_fmac_f32_e32 v30, 0x32a5705f, v22
	v_sub_f32_e32 v24, v24, v31
	v_add_f32_e32 v24, v24, v30
	v_exp_f32_e32 v24, v24
	v_cvt_i32_f32_e32 v30, v31
	v_cmp_ngt_f32_e32 vcc, s51, v22
	v_mad_u32_u24 v98, v9, s47, v66
	v_lshlrev_b32_e32 v80, 1, v99
	v_ldexp_f32 v21, v24, v30
	v_cndmask_b32_e32 v21, 0, v21, vcc
	v_cmp_nlt_f32_e32 vcc, s52, v22
	v_mul_f32_e32 v22, 0x3e000000, v25
	v_mad_u32_u24 v100, v9, s47, v67
	v_cndmask_b32_e32 v21, v63, v21, vcc
	v_mul_f32_e32 v21, v21, v22
	v_cvt_pk_bf16_f32 v21, v21, v33
	ds_write_b16 v17, v21 offset:848
	v_or_b32_e32 v21, 32, v9
	v_sub_u32_e32 v22, v16, v21
	v_cvt_f32_i32_e32 v30, v22
	v_cmp_lt_i32_e32 vcc, v16, v21
	s_waitcnt vmcnt(1)
; __device__ __forceinline__ unsigned short f2bf(float f) { return (unsigned short)(cvt_pk_bf16(f, 0.f) & 0xffffu); }
; __device__ __forceinline__ void retout_item(PRef p, int layer, int item, unsigned char* shm) {
;     ...
;     for (int nt = 0; nt < 8; ++nt) { f32x4 s = (f32x4){0.f, 0.f, 0.f, 0.f};
; #pragma unroll
;         for (int kk = 0; kk < 2; ++kk) { const bf16x8 kb = *(const bf16x8*)(A + (size_t)(row0 + 16 * nt + fr) * NIN + C_K + h * 64 + kk * 32 + fq * 8);
;             s = __builtin_amdgcn_mfma_f32_16x16x32_bf16(qa[kk], kb, s, 0, 0, 0); }
;         const int m = 16 * nt + fr;
; #pragma unroll
;         for (int r = 0; r < 4; ++r) { const int c = 16 * wave + fq * 4 + r; const float dd = (float)(c - m);
;             const float dec = (m <= c) ? expf(dd * lgf) : expf(-dd * lgb);
;             Pw[(fq * 4 + r) * LDK + m] = f2bf(s[r] * 0.125f * dec); } }
	v_mfma_f32_16x16x32_bf16 v[22:25], v[4:7], v[26:29], 0
	v_lshlrev_b32_e32 v84, 1, v101
	v_cndmask_b32_e64 v26, -v12, v11, vcc
	v_mul_f32_e32 v35, v26, v30
	v_mul_f32_e32 v26, 0x3fb8aa3b, v35
	v_fma_f32 v27, v35, s50, -v26
	v_rndne_f32_e32 v28, v26
	v_fmac_f32_e32 v27, 0x32a5705f, v35
	v_sub_f32_e32 v26, v26, v28
	v_add_f32_e32 v26, v26, v27
	v_exp_f32_e32 v42, v26
	v_or_b32_e32 v26, 48, v15
	v_mad_u64_u32 v[26:27], s[36:37], v26, s46, v[36:37]
	v_lshl_add_u64 v[26:27], v[26:27], 0, s[34:35]
	v_lshl_add_u64 v[30:31], v[26:27], 0, v[32:33]
	v_add_co_u32_e32 v26, vcc, s48, v30
	v_cvt_i32_f32_e32 v43, v28
	s_nop 0
	v_addc_co_u32_e32 v27, vcc, 0, v31, vcc
	global_load_dwordx4 v[26:29], v[26:27], off
	s_waitcnt vmcnt(1)
	v_mfma_f32_16x16x32_bf16 v[22:25], v[0:3], v[38:41], v[22:25]
	v_ldexp_f32 v38, v42, v43
	v_cmp_ngt_f32_e32 vcc, s51, v35
	v_lshl_add_u64 v[30:31], v[30:31], 0, s[24:25]
	v_mad_u32_u24 v102, v9, s47, v69
	v_cndmask_b32_e32 v38, 0, v38, vcc
	v_cmp_nlt_f32_e32 vcc, s52, v35
	s_nop 1
	v_mul_f32_e32 v22, 0x3e000000, v22
	v_mul_f32_e32 v23, 0x3e000000, v23
	v_cndmask_b32_e32 v35, v63, v38, vcc
	v_sub_u32_e32 v38, v18, v21
	v_cvt_f32_i32_e32 v38, v38
	v_cmp_lt_i32_e32 vcc, v18, v21
	v_mul_f32_e32 v22, v35, v22
	v_cvt_pk_bf16_f32 v22, v22, v33
	ds_write_b16 v17, v22 offset:64
	v_cndmask_b32_e64 v39, -v12, v11, vcc
	v_mul_f32_e32 v42, v39, v38
	global_load_dwordx4 v[38:41], v[30:31], off offset:64
	v_mul_f32_e32 v30, 0x3fb8aa3b, v42
	v_fma_f32 v31, v42, s50, -v30
	v_rndne_f32_e32 v43, v30
	v_fmac_f32_e32 v31, 0x32a5705f, v42
	v_sub_f32_e32 v30, v30, v43
	v_add_f32_e32 v30, v30, v31
	v_exp_f32_e32 v30, v30
	v_cvt_i32_f32_e32 v31, v43
	v_cmp_ngt_f32_e32 vcc, s51, v42
	v_mul_f32_e32 v24, 0x3e000000, v24
	v_lshlrev_b32_e32 v88, 1, v88
	v_ldexp_f32 v22, v30, v31
	v_sub_u32_e32 v30, v20, v21
	v_cvt_f32_i32_e32 v30, v30
	v_cndmask_b32_e32 v22, 0, v22, vcc
	v_cmp_nlt_f32_e32 vcc, s52, v42
	v_mad_u32_u24 v104, v9, s47, v71
	v_lshlrev_b32_e32 v92, 1, v92
	v_cndmask_b32_e32 v22, v63, v22, vcc
	v_cmp_lt_i32_e32 vcc, v20, v21
	v_mul_f32_e32 v22, v22, v23
	v_cvt_pk_bf16_f32 v22, v22, v33
	v_sub_u32_e32 v23, v19, v21
	v_cndmask_b32_e64 v31, -v12, v11, vcc
	v_mul_f32_e32 v30, v31, v30
	v_mul_f32_e32 v31, 0x3fb8aa3b, v30
	v_fma_f32 v35, v30, s50, -v31
	v_rndne_f32_e32 v42, v31
	v_fmac_f32_e32 v35, 0x32a5705f, v30
	v_sub_f32_e32 v31, v31, v42
	v_add_f32_e32 v31, v31, v35
	v_exp_f32_e32 v31, v31
	v_cvt_i32_f32_e32 v35, v42
	ds_write_b16 v17, v22 offset:336
	v_cmp_ngt_f32_e32 vcc, s51, v30
	v_cvt_f32_i32_e32 v23, v23
	v_ldexp_f32 v22, v31, v35
	v_cndmask_b32_e32 v22, 0, v22, vcc
	v_cmp_nlt_f32_e32 vcc, s52, v30
	v_or_b32_e32 v35, 48, v9
	v_mad_u32_u24 v106, v9, s47, v73
	v_cndmask_b32_e32 v22, v63, v22, vcc
	v_cmp_lt_i32_e32 vcc, v19, v21
	v_mul_f32_e32 v22, v22, v24
	v_cvt_pk_bf16_f32 v22, v22, v33
	ds_write_b16 v17, v22 offset:608
	v_cndmask_b32_e64 v21, -v12, v11, vcc
	v_mul_f32_e32 v21, v21, v23
	v_mul_f32_e32 v23, 0x3fb8aa3b, v21
	v_fma_f32 v30, v21, s50, -v23
	v_rndne_f32_e32 v31, v23
	v_fmac_f32_e32 v30, 0x32a5705f, v21
	v_sub_f32_e32 v23, v23, v31
	v_add_f32_e32 v23, v23, v30
	v_exp_f32_e32 v23, v23
	v_cvt_i32_f32_e32 v30, v31
	v_cmp_ngt_f32_e32 vcc, s51, v21
	v_add3_u32 v88, 0, v88, v104
	v_add3_u32 v92, 0, v92, v106
	v_ldexp_f32 v22, v23, v30
	v_cndmask_b32_e32 v22, 0, v22, vcc
	v_cmp_nlt_f32_e32 vcc, s52, v21
	s_lshl_b32 s20, s34, 1
	s_nop 0
	v_cndmask_b32_e32 v21, v63, v22, vcc
	v_mul_f32_e32 v22, 0x3e000000, v25
	v_mul_f32_e32 v21, v21, v22
	v_sub_u32_e32 v22, v16, v35
	v_cvt_f32_i32_e32 v30, v22
	v_cmp_lt_i32_e32 vcc, v16, v35
	s_waitcnt vmcnt(1)
	v_mfma_f32_16x16x32_bf16 v[22:25], v[4:7], v[26:29], 0
	v_cvt_pk_bf16_f32 v21, v21, v33
	ds_write_b16 v17, v21 offset:880
	v_cndmask_b32_e64 v26, -v12, v11, vcc
	v_mul_f32_e32 v42, v26, v30
	v_mul_f32_e32 v26, 0x3fb8aa3b, v42
	v_fma_f32 v27, v42, s50, -v26
	v_rndne_f32_e32 v28, v26
	v_fmac_f32_e32 v27, 0x32a5705f, v42
	v_sub_f32_e32 v26, v26, v28
	v_add_f32_e32 v26, v26, v27
	v_exp_f32_e32 v26, v26
	v_cvt_i32_f32_e32 v27, v28
	s_waitcnt vmcnt(0)
	v_mfma_f32_16x16x32_bf16 v[22:25], v[0:3], v[38:41], v[22:25]
	v_ldexp_f32 v21, v26, v27
	v_or_b32_e32 v26, 64, v15
	v_mad_u64_u32 v[26:27], s[36:37], v26, s46, v[36:37]
	v_lshl_add_u64 v[26:27], v[26:27], 0, s[34:35]
	v_lshl_add_u64 v[30:31], v[26:27], 0, v[32:33]
	v_add_co_u32_e32 v26, vcc, s48, v30
	s_nop 1
	v_mul_f32_e32 v22, 0x3e000000, v22
	v_addc_co_u32_e32 v27, vcc, 0, v31, vcc
	global_load_dwordx4 v[26:29], v[26:27], off
	v_cmp_ngt_f32_e32 vcc, s51, v42
	v_lshl_add_u64 v[30:31], v[30:31], 0, s[24:25]
	v_mul_f32_e32 v23, 0x3e000000, v23
	v_cndmask_b32_e32 v21, 0, v21, vcc
	v_cmp_nlt_f32_e32 vcc, s52, v42
	s_nop 1
	v_cndmask_b32_e32 v21, v63, v21, vcc
	v_mul_f32_e32 v21, v21, v22
	v_sub_u32_e32 v22, v18, v35
	v_cvt_f32_i32_e32 v22, v22
	v_cmp_lt_i32_e32 vcc, v18, v35
	v_cvt_pk_bf16_f32 v21, v21, v33
	ds_write_b16 v17, v21 offset:96
	s_nop 0
	v_cndmask_b32_e64 v38, -v12, v11, vcc
	v_mul_f32_e32 v22, v38, v22
	v_mul_f32_e32 v38, 0x3fb8aa3b, v22
	v_fma_f32 v39, v22, s50, -v38
	v_rndne_f32_e32 v40, v38
	v_fmac_f32_e32 v39, 0x32a5705f, v22
	v_sub_f32_e32 v38, v38, v40
	v_add_f32_e32 v38, v38, v39
	v_exp_f32_e32 v42, v38
	v_cvt_i32_f32_e32 v43, v40
	global_load_dwordx4 v[38:41], v[30:31], off offset:64
	v_cmp_ngt_f32_e32 vcc, s51, v22
	v_ldexp_f32 v21, v42, v43
	s_nop 0
	v_cndmask_b32_e32 v21, 0, v21, vcc
	v_cmp_nlt_f32_e32 vcc, s52, v22
	v_sub_u32_e32 v22, v20, v35
	v_cvt_f32_i32_e32 v22, v22
	v_cndmask_b32_e32 v21, v63, v21, vcc
	v_cmp_lt_i32_e32 vcc, v20, v35
	v_mul_f32_e32 v21, v21, v23
	v_cvt_pk_bf16_f32 v21, v21, v33
	ds_write_b16 v17, v21 offset:368
; __device__ __forceinline__ unsigned short f2bf(float f) { return (unsigned short)(cvt_pk_bf16(f, 0.f) & 0xffffu); }
; __device__ __forceinline__ void retout_item(PRef p, int layer, int item, unsigned char* shm) {
;     ...
;     for (int nt = 0; nt < 8; ++nt) { f32x4 s = (f32x4){0.f, 0.f, 0.f, 0.f};
; #pragma unroll
;         for (int kk = 0; kk < 2; ++kk) { const bf16x8 kb = *(const bf16x8*)(A + (size_t)(row0 + 16 * nt + fr) * NIN + C_K + h * 64 + kk * 32 + fq * 8);
;             s = __builtin_amdgcn_mfma_f32_16x16x32_bf16(qa[kk], kb, s, 0, 0, 0); }
;         const int m = 16 * nt + fr;
; #pragma unroll
;         for (int r = 0; r < 4; ++r) { const int c = 16 * wave + fq * 4 + r; const float dd = (float)(c - m);
;             const float dec = (m <= c) ? expf(dd * lgf) : expf(-dd * lgb);
;             Pw[(fq * 4 + r) * LDK + m] = f2bf(s[r] * 0.125f * dec); } }
	v_cndmask_b32_e64 v30, -v12, v11, vcc
	v_mul_f32_e32 v22, v30, v22
	v_mul_f32_e32 v30, 0x3fb8aa3b, v22
	v_fma_f32 v31, v22, s50, -v30
	v_rndne_f32_e32 v42, v30
	v_fmac_f32_e32 v31, 0x32a5705f, v22
	v_sub_f32_e32 v30, v30, v42
	v_add_f32_e32 v30, v30, v31
	v_exp_f32_e32 v30, v30
	v_cvt_i32_f32_e32 v31, v42
	v_cmp_ngt_f32_e32 vcc, s51, v22
	v_mul_f32_e32 v23, 0x3e000000, v24
	v_ldexp_f32 v21, v30, v31
	v_cndmask_b32_e32 v21, 0, v21, vcc
	v_cmp_nlt_f32_e32 vcc, s52, v22
	v_sub_u32_e32 v22, v19, v35
	v_cvt_f32_i32_e32 v22, v22
	v_cndmask_b32_e32 v21, v63, v21, vcc
	v_cmp_lt_i32_e32 vcc, v19, v35
	v_mul_f32_e32 v21, v21, v23
	v_cvt_pk_bf16_f32 v21, v21, v33
	ds_write_b16 v17, v21 offset:640
	v_cndmask_b32_e64 v24, -v12, v11, vcc
	v_mul_f32_e32 v22, v24, v22
	v_mul_f32_e32 v24, 0x3fb8aa3b, v22
	v_fma_f32 v30, v22, s50, -v24
	v_rndne_f32_e32 v31, v24
	v_fmac_f32_e32 v30, 0x32a5705f, v22
	v_sub_f32_e32 v24, v24, v31
	v_add_f32_e32 v24, v24, v30
	v_exp_f32_e32 v24, v24
	v_cvt_i32_f32_e32 v30, v31
	v_cmp_ngt_f32_e32 vcc, s51, v22
	v_ldexp_f32 v21, v24, v30
	s_nop 0
	v_cndmask_b32_e32 v21, 0, v21, vcc
	v_cmp_nlt_f32_e32 vcc, s52, v22
	v_mul_f32_e32 v22, 0x3e000000, v25
	s_nop 0
	v_cndmask_b32_e32 v21, v63, v21, vcc
	v_mul_f32_e32 v21, v21, v22
	v_cvt_pk_bf16_f32 v21, v21, v33
	ds_write_b16 v17, v21 offset:912
	v_or_b32_e32 v21, 64, v9
	v_sub_u32_e32 v22, v16, v21
	v_cvt_f32_i32_e32 v30, v22
	v_cmp_lt_i32_e32 vcc, v16, v21
	s_waitcnt vmcnt(1)
	v_mfma_f32_16x16x32_bf16 v[22:25], v[4:7], v[26:29], 0
	v_cndmask_b32_e64 v26, -v12, v11, vcc
	v_mul_f32_e32 v35, v26, v30
	v_mul_f32_e32 v26, 0x3fb8aa3b, v35
	v_fma_f32 v27, v35, s50, -v26
	v_rndne_f32_e32 v28, v26
	v_fmac_f32_e32 v27, 0x32a5705f, v35
	v_sub_f32_e32 v26, v26, v28
	v_add_f32_e32 v26, v26, v27
	v_exp_f32_e32 v42, v26
	v_or_b32_e32 v26, 0x50, v15
	v_mad_u64_u32 v[26:27], s[36:37], v26, s46, v[36:37]
	v_lshl_add_u64 v[26:27], v[26:27], 0, s[34:35]
	v_lshl_add_u64 v[30:31], v[26:27], 0, v[32:33]
	v_add_co_u32_e32 v26, vcc, s48, v30
	v_cvt_i32_f32_e32 v43, v28
	s_nop 0
	v_addc_co_u32_e32 v27, vcc, 0, v31, vcc
	global_load_dwordx4 v[26:29], v[26:27], off
	s_waitcnt vmcnt(1)
	v_mfma_f32_16x16x32_bf16 v[22:25], v[0:3], v[38:41], v[22:25]
	v_ldexp_f32 v38, v42, v43
	v_cmp_ngt_f32_e32 vcc, s51, v35
	v_lshl_add_u64 v[30:31], v[30:31], 0, s[24:25]
	s_nop 0
	v_cndmask_b32_e32 v38, 0, v38, vcc
	v_cmp_nlt_f32_e32 vcc, s52, v35
	s_nop 1
	v_mul_f32_e32 v22, 0x3e000000, v22
	v_mul_f32_e32 v23, 0x3e000000, v23
	v_cndmask_b32_e32 v35, v63, v38, vcc
	v_sub_u32_e32 v38, v18, v21
	v_cvt_f32_i32_e32 v38, v38
	v_cmp_lt_i32_e32 vcc, v18, v21
	v_mul_f32_e32 v22, v35, v22
	v_cvt_pk_bf16_f32 v22, v22, v33
	ds_write_b16 v17, v22 offset:128
	v_cndmask_b32_e64 v39, -v12, v11, vcc
	v_mul_f32_e32 v42, v39, v38
	global_load_dwordx4 v[38:41], v[30:31], off offset:64
	v_mul_f32_e32 v30, 0x3fb8aa3b, v42
	v_fma_f32 v31, v42, s50, -v30
	v_rndne_f32_e32 v43, v30
	v_fmac_f32_e32 v31, 0x32a5705f, v42
	v_sub_f32_e32 v30, v30, v43
	v_add_f32_e32 v30, v30, v31
	v_exp_f32_e32 v30, v30
	v_cvt_i32_f32_e32 v31, v43
	v_cmp_ngt_f32_e32 vcc, s51, v42
	v_mul_f32_e32 v24, 0x3e000000, v24
	v_ldexp_f32 v22, v30, v31
	v_sub_u32_e32 v30, v20, v21
	v_cvt_f32_i32_e32 v30, v30
	v_cndmask_b32_e32 v22, 0, v22, vcc
	v_cmp_nlt_f32_e32 vcc, s52, v42
	s_nop 1
	v_cndmask_b32_e32 v22, v63, v22, vcc
	v_cmp_lt_i32_e32 vcc, v20, v21
	v_mul_f32_e32 v22, v22, v23
	v_cvt_pk_bf16_f32 v22, v22, v33
	v_sub_u32_e32 v23, v19, v21
	v_cndmask_b32_e64 v31, -v12, v11, vcc
	v_mul_f32_e32 v30, v31, v30
	v_mul_f32_e32 v31, 0x3fb8aa3b, v30
	v_fma_f32 v35, v30, s50, -v31
	v_rndne_f32_e32 v42, v31
	v_fmac_f32_e32 v35, 0x32a5705f, v30
	v_sub_f32_e32 v31, v31, v42
	v_add_f32_e32 v31, v31, v35
	v_exp_f32_e32 v31, v31
	v_cvt_i32_f32_e32 v35, v42
	ds_write_b16 v17, v22 offset:400
	v_cmp_ngt_f32_e32 vcc, s51, v30
	v_cvt_f32_i32_e32 v23, v23
	v_ldexp_f32 v22, v31, v35
	v_cndmask_b32_e32 v22, 0, v22, vcc
	v_cmp_nlt_f32_e32 vcc, s52, v30
	v_or_b32_e32 v35, 0x50, v9
	s_nop 0
	v_cndmask_b32_e32 v22, v63, v22, vcc
	v_cmp_lt_i32_e32 vcc, v19, v21
	v_mul_f32_e32 v22, v22, v24
	v_cvt_pk_bf16_f32 v22, v22, v33
	ds_write_b16 v17, v22 offset:672
	v_cndmask_b32_e64 v21, -v12, v11, vcc
	v_mul_f32_e32 v21, v21, v23
	v_mul_f32_e32 v23, 0x3fb8aa3b, v21
	v_fma_f32 v30, v21, s50, -v23
	v_rndne_f32_e32 v31, v23
	v_fmac_f32_e32 v30, 0x32a5705f, v21
	v_sub_f32_e32 v23, v23, v31
	v_add_f32_e32 v23, v23, v30
	v_exp_f32_e32 v23, v23
	v_cvt_i32_f32_e32 v30, v31
	v_cmp_ngt_f32_e32 vcc, s51, v21
	v_ldexp_f32 v22, v23, v30
	s_nop 0
	v_cndmask_b32_e32 v22, 0, v22, vcc
	v_cmp_nlt_f32_e32 vcc, s52, v21
	s_nop 1
	v_cndmask_b32_e32 v21, v63, v22, vcc
	v_mul_f32_e32 v22, 0x3e000000, v25
	v_mul_f32_e32 v21, v21, v22
	v_sub_u32_e32 v22, v16, v35
	v_cvt_f32_i32_e32 v30, v22
	v_cmp_lt_i32_e32 vcc, v16, v35
	s_waitcnt vmcnt(1)
	v_mfma_f32_16x16x32_bf16 v[22:25], v[4:7], v[26:29], 0
	v_cvt_pk_bf16_f32 v21, v21, v33
	ds_write_b16 v17, v21 offset:944
	v_cndmask_b32_e64 v26, -v12, v11, vcc
	v_mul_f32_e32 v42, v26, v30
	v_mul_f32_e32 v26, 0x3fb8aa3b, v42
	v_fma_f32 v27, v42, s50, -v26
	v_rndne_f32_e32 v28, v26
	v_fmac_f32_e32 v27, 0x32a5705f, v42
	v_sub_f32_e32 v26, v26, v28
	v_add_f32_e32 v26, v26, v27
	v_exp_f32_e32 v26, v26
	v_cvt_i32_f32_e32 v27, v28
	s_waitcnt vmcnt(0)
; __device__ __forceinline__ unsigned short f2bf(float f) { return (unsigned short)(cvt_pk_bf16(f, 0.f) & 0xffffu); }
; __device__ __forceinline__ void retout_item(PRef p, int layer, int item, unsigned char* shm) {
;     ...
;     for (int nt = 0; nt < 8; ++nt) { f32x4 s = (f32x4){0.f, 0.f, 0.f, 0.f};
; #pragma unroll
;         for (int kk = 0; kk < 2; ++kk) { const bf16x8 kb = *(const bf16x8*)(A + (size_t)(row0 + 16 * nt + fr) * NIN + C_K + h * 64 + kk * 32 + fq * 8);
;             s = __builtin_amdgcn_mfma_f32_16x16x32_bf16(qa[kk], kb, s, 0, 0, 0); }
;         const int m = 16 * nt + fr;
; #pragma unroll
;         for (int r = 0; r < 4; ++r) { const int c = 16 * wave + fq * 4 + r; const float dd = (float)(c - m);
;             const float dec = (m <= c) ? expf(dd * lgf) : expf(-dd * lgb);
;             Pw[(fq * 4 + r) * LDK + m] = f2bf(s[r] * 0.125f * dec); } }
	v_mfma_f32_16x16x32_bf16 v[22:25], v[0:3], v[38:41], v[22:25]
	v_ldexp_f32 v21, v26, v27
	v_or_b32_e32 v26, 0x60, v15
	v_mad_u64_u32 v[26:27], s[36:37], v26, s46, v[36:37]
	v_lshl_add_u64 v[26:27], v[26:27], 0, s[34:35]
	v_lshl_add_u64 v[30:31], v[26:27], 0, v[32:33]
	v_add_co_u32_e32 v26, vcc, s48, v30
	s_nop 1
	v_mul_f32_e32 v22, 0x3e000000, v22
	v_addc_co_u32_e32 v27, vcc, 0, v31, vcc
	global_load_dwordx4 v[26:29], v[26:27], off
	v_cmp_ngt_f32_e32 vcc, s51, v42
	v_lshl_add_u64 v[30:31], v[30:31], 0, s[24:25]
	v_mul_f32_e32 v23, 0x3e000000, v23
	v_cndmask_b32_e32 v21, 0, v21, vcc
	v_cmp_nlt_f32_e32 vcc, s52, v42
	v_or_b32_e32 v15, 0x70, v15
	s_nop 0
	v_cndmask_b32_e32 v21, v63, v21, vcc
	v_mul_f32_e32 v21, v21, v22
	v_sub_u32_e32 v22, v18, v35
	v_cvt_f32_i32_e32 v22, v22
	v_cmp_lt_i32_e32 vcc, v18, v35
	v_cvt_pk_bf16_f32 v21, v21, v33
	ds_write_b16 v17, v21 offset:160
	s_nop 0
	v_cndmask_b32_e64 v38, -v12, v11, vcc
	v_mul_f32_e32 v22, v38, v22
	v_mul_f32_e32 v38, 0x3fb8aa3b, v22
	v_fma_f32 v39, v22, s50, -v38
	v_rndne_f32_e32 v40, v38
	v_fmac_f32_e32 v39, 0x32a5705f, v22
	v_sub_f32_e32 v38, v38, v40
	v_add_f32_e32 v38, v38, v39
	v_exp_f32_e32 v42, v38
	v_cvt_i32_f32_e32 v43, v40
	global_load_dwordx4 v[38:41], v[30:31], off offset:64
	v_cmp_ngt_f32_e32 vcc, s51, v22
	v_ldexp_f32 v21, v42, v43
	s_nop 0
	v_cndmask_b32_e32 v21, 0, v21, vcc
	v_cmp_nlt_f32_e32 vcc, s52, v22
	v_sub_u32_e32 v22, v20, v35
	v_cvt_f32_i32_e32 v22, v22
	v_cndmask_b32_e32 v21, v63, v21, vcc
	v_cmp_lt_i32_e32 vcc, v20, v35
	v_mul_f32_e32 v21, v21, v23
	v_cvt_pk_bf16_f32 v21, v21, v33
	ds_write_b16 v17, v21 offset:432
	v_cndmask_b32_e64 v30, -v12, v11, vcc
	v_mul_f32_e32 v22, v30, v22
	v_mul_f32_e32 v30, 0x3fb8aa3b, v22
	v_fma_f32 v31, v22, s50, -v30
	v_rndne_f32_e32 v42, v30
	v_fmac_f32_e32 v31, 0x32a5705f, v22
	v_sub_f32_e32 v30, v30, v42
	v_add_f32_e32 v30, v30, v31
	v_exp_f32_e32 v30, v30
	v_cvt_i32_f32_e32 v31, v42
	v_cmp_ngt_f32_e32 vcc, s51, v22
	v_mul_f32_e32 v23, 0x3e000000, v24
	v_ldexp_f32 v21, v30, v31
	v_cndmask_b32_e32 v21, 0, v21, vcc
	v_cmp_nlt_f32_e32 vcc, s52, v22
	v_sub_u32_e32 v22, v19, v35
	v_cvt_f32_i32_e32 v22, v22
	v_cndmask_b32_e32 v21, v63, v21, vcc
	v_cmp_lt_i32_e32 vcc, v19, v35
	v_mul_f32_e32 v21, v21, v23
	v_cvt_pk_bf16_f32 v21, v21, v33
	ds_write_b16 v17, v21 offset:704
	v_cndmask_b32_e64 v24, -v12, v11, vcc
	v_mul_f32_e32 v22, v24, v22
	v_mul_f32_e32 v24, 0x3fb8aa3b, v22
	v_fma_f32 v30, v22, s50, -v24
	v_rndne_f32_e32 v31, v24
	v_fmac_f32_e32 v30, 0x32a5705f, v22
	v_sub_f32_e32 v24, v24, v31
	v_add_f32_e32 v24, v24, v30
	v_exp_f32_e32 v24, v24
	v_cvt_i32_f32_e32 v30, v31
	v_cmp_ngt_f32_e32 vcc, s51, v22
	v_ldexp_f32 v21, v24, v30
	s_nop 0
	v_cndmask_b32_e32 v21, 0, v21, vcc
	v_cmp_nlt_f32_e32 vcc, s52, v22
	v_mul_f32_e32 v22, 0x3e000000, v25
	s_nop 0
	v_cndmask_b32_e32 v21, v63, v21, vcc
	v_mul_f32_e32 v21, v21, v22
	v_cvt_pk_bf16_f32 v21, v21, v33
	ds_write_b16 v17, v21 offset:976
	v_or_b32_e32 v21, 0x60, v9
	v_sub_u32_e32 v22, v16, v21
	v_cvt_f32_i32_e32 v30, v22
	v_cmp_lt_i32_e32 vcc, v16, v21
	s_waitcnt vmcnt(1)
	v_mfma_f32_16x16x32_bf16 v[22:25], v[4:7], v[26:29], 0
	v_cndmask_b32_e64 v26, -v12, v11, vcc
	v_mul_f32_e32 v35, v26, v30
	v_mul_f32_e32 v26, 0x3fb8aa3b, v35
	v_fma_f32 v27, v35, s50, -v26
	v_rndne_f32_e32 v28, v26
	v_fmac_f32_e32 v27, 0x32a5705f, v35
	v_sub_f32_e32 v26, v26, v28
	v_add_f32_e32 v26, v26, v27
	v_exp_f32_e32 v42, v26
	v_mad_u64_u32 v[26:27], s[36:37], v15, s46, v[36:37]
	v_lshl_add_u64 v[26:27], v[26:27], 0, s[34:35]
	v_lshl_add_u64 v[30:31], v[26:27], 0, v[32:33]
	v_add_co_u32_e32 v26, vcc, s48, v30
	v_cvt_i32_f32_e32 v43, v28
	s_nop 0
	v_addc_co_u32_e32 v27, vcc, 0, v31, vcc
	global_load_dwordx4 v[26:29], v[26:27], off
	v_ldexp_f32 v15, v42, v43
	v_cmp_ngt_f32_e32 vcc, s51, v35
	s_waitcnt vmcnt(1)
	v_mfma_f32_16x16x32_bf16 v[22:25], v[0:3], v[38:41], v[22:25]
	v_lshl_add_u64 v[30:31], v[30:31], 0, s[24:25]
	v_cndmask_b32_e32 v15, 0, v15, vcc
	v_cmp_nlt_f32_e32 vcc, s52, v35
	v_sub_u32_e32 v35, v18, v21
	v_cvt_f32_i32_e32 v35, v35
	v_cndmask_b32_e32 v15, v63, v15, vcc
	v_cmp_lt_i32_e32 vcc, v18, v21
	s_nop 0
	v_mul_f32_e32 v22, 0x3e000000, v22
	v_mul_f32_e32 v15, v15, v22
	v_cndmask_b32_e64 v38, -v12, v11, vcc
	v_mul_f32_e32 v35, v38, v35
	global_load_dwordx4 v[38:41], v[30:31], off offset:64
	v_mul_f32_e32 v30, 0x3fb8aa3b, v35
	v_fma_f32 v31, v35, s50, -v30
	v_rndne_f32_e32 v42, v30
	v_fmac_f32_e32 v31, 0x32a5705f, v35
	v_sub_f32_e32 v30, v30, v42
	v_add_f32_e32 v30, v30, v31
	v_exp_f32_e32 v30, v30
	v_cvt_i32_f32_e32 v31, v42
	v_cvt_pk_bf16_f32 v15, v15, v33
	v_sub_u32_e32 v22, v20, v21
	ds_write_b16 v17, v15 offset:192
	v_ldexp_f32 v15, v30, v31
	v_cmp_ngt_f32_e32 vcc, s51, v35
	v_cvt_f32_i32_e32 v22, v22
	v_mul_f32_e32 v23, 0x3e000000, v23
	v_cndmask_b32_e32 v15, 0, v15, vcc
	v_cmp_nlt_f32_e32 vcc, s52, v35
	s_nop 1
	v_cndmask_b32_e32 v15, v63, v15, vcc
	v_cmp_lt_i32_e32 vcc, v20, v21
	v_mul_f32_e32 v15, v15, v23
	v_cvt_pk_bf16_f32 v15, v15, v33
	ds_write_b16 v17, v15 offset:464
	v_cndmask_b32_e64 v30, -v12, v11, vcc
	v_mul_f32_e32 v22, v30, v22
	v_mul_f32_e32 v30, 0x3fb8aa3b, v22
	v_fma_f32 v31, v22, s50, -v30
	v_rndne_f32_e32 v35, v30
	v_fmac_f32_e32 v31, 0x32a5705f, v22
	v_sub_f32_e32 v30, v30, v35
	v_add_f32_e32 v30, v30, v31
	v_exp_f32_e32 v30, v30
	v_cvt_i32_f32_e32 v31, v35
	v_cmp_ngt_f32_e32 vcc, s51, v22
	v_mul_f32_e32 v23, 0x3e000000, v24
	v_ldexp_f32 v15, v30, v31
	v_cndmask_b32_e32 v15, 0, v15, vcc
	v_cmp_nlt_f32_e32 vcc, s52, v22
	v_sub_u32_e32 v22, v19, v21
	v_cvt_f32_i32_e32 v22, v22
	v_cndmask_b32_e32 v15, v63, v15, vcc
	v_cmp_lt_i32_e32 vcc, v19, v21
	v_mul_f32_e32 v15, v15, v23
	v_cvt_pk_bf16_f32 v15, v15, v33
	ds_write_b16 v17, v15 offset:736
	v_cndmask_b32_e64 v21, -v12, v11, vcc
	v_mul_f32_e32 v21, v21, v22
	v_mul_f32_e32 v22, 0x3fb8aa3b, v21
	v_fma_f32 v24, v21, s50, -v22
	v_rndne_f32_e32 v30, v22
	v_fmac_f32_e32 v24, 0x32a5705f, v21
	v_sub_f32_e32 v22, v22, v30
	v_add_f32_e32 v22, v22, v24
	v_exp_f32_e32 v22, v22
	v_cvt_i32_f32_e32 v24, v30
	v_cmp_ngt_f32_e32 vcc, s51, v21
	v_ldexp_f32 v15, v22, v24
	s_nop 0
	v_cndmask_b32_e32 v15, 0, v15, vcc
	v_cmp_nlt_f32_e32 vcc, s52, v21
	v_mul_f32_e32 v21, 0x3e000000, v25
	s_nop 0
	v_cndmask_b32_e32 v15, v63, v15, vcc
	v_mul_f32_e32 v15, v15, v21
	v_or_b32_e32 v21, 0x70, v9
	v_sub_u32_e32 v22, v16, v21
	v_cvt_f32_i32_e32 v30, v22
	v_cmp_lt_i32_e32 vcc, v16, v21
	s_waitcnt vmcnt(1)
; __device__ __forceinline__ unsigned short f2bf(float f) { return (unsigned short)(cvt_pk_bf16(f, 0.f) & 0xffffu); }
; __device__ __forceinline__ void retout_item(PRef p, int layer, int item, unsigned char* shm) {
;     ...
;         const int m = 16 * nt + fr;
; #pragma unroll
;         for (int r = 0; r < 4; ++r) { const int c = 16 * wave + fq * 4 + r; const float dd = (float)(c - m);
;             const float dec = (m <= c) ? expf(dd * lgf) : expf(-dd * lgb);
;             Pw[(fq * 4 + r) * LDK + m] = f2bf(s[r] * 0.125f * dec); } }
;     __syncthreads();
;     f32x4 acc[8];
; #pragma unroll
;     for (int et = 0; et < 8; ++et) acc[et] = (f32x4){0.f, 0.f, 0.f, 0.f};
; #pragma unroll
;     for (int kk = 0; kk < 4; ++kk) { const bf16x8 af = *(const bf16x8*)(Pw + fr * LDK + kk * 32 + fq * 8);
; #pragma unroll
;         for (int et = 0; et < 8; ++et) { const bf16x8 bf = *(const bf16x8*)(vT + tsw(16 * et + fr, kk * 32 + fq * 8));
;             acc[et] = __builtin_amdgcn_mfma_f32_16x16x32_bf16(af, bf, acc[et], 0, 0, 0); } }
	v_mfma_f32_16x16x32_bf16 v[22:25], v[4:7], v[26:29], 0
	v_cvt_pk_bf16_f32 v15, v15, v33
	ds_write_b16 v17, v15 offset:1008
	v_cndmask_b32_e64 v26, -v12, v11, vcc
	v_mul_f32_e32 v26, v26, v30
	v_mul_f32_e32 v27, 0x3fb8aa3b, v26
	v_fma_f32 v28, v26, s50, -v27
	v_rndne_f32_e32 v29, v27
	v_fmac_f32_e32 v28, 0x32a5705f, v26
	v_sub_f32_e32 v27, v27, v29
	v_add_f32_e32 v27, v27, v28
	v_exp_f32_e32 v27, v27
	v_cvt_i32_f32_e32 v28, v29
	v_cmp_ngt_f32_e32 vcc, s51, v26
	s_waitcnt vmcnt(0)
	v_mfma_f32_16x16x32_bf16 v[22:25], v[0:3], v[38:41], v[22:25]
	v_add_u32_e32 v30, 0, v32
	v_ldexp_f32 v15, v27, v28
	v_cndmask_b32_e32 v15, 0, v15, vcc
	v_cmp_nlt_f32_e32 vcc, s52, v26
	v_sub_u32_e32 v26, v18, v21
	v_cvt_f32_i32_e32 v26, v26
	v_cndmask_b32_e32 v15, v63, v15, vcc
	v_cmp_lt_i32_e32 vcc, v18, v21
	v_mul_f32_e32 v22, 0x3e000000, v22
	v_mul_f32_e32 v15, v15, v22
	v_cndmask_b32_e64 v18, -v12, v11, vcc
	v_mul_f32_e32 v18, v18, v26
	v_mul_f32_e32 v26, 0x3fb8aa3b, v18
	v_fma_f32 v27, v18, s50, -v26
	v_rndne_f32_e32 v28, v26
	v_fmac_f32_e32 v27, 0x32a5705f, v18
	v_sub_f32_e32 v26, v26, v28
	v_add_f32_e32 v26, v26, v27
	v_exp_f32_e32 v26, v26
	v_cvt_i32_f32_e32 v27, v28
	v_cvt_pk_bf16_f32 v15, v15, v33
	ds_write_b16 v17, v15 offset:224
	v_cmp_ngt_f32_e32 vcc, s51, v18
	v_ldexp_f32 v15, v26, v27
	v_mul_f32_e32 v22, 0x3e000000, v23
	v_cndmask_b32_e32 v15, 0, v15, vcc
	v_cmp_nlt_f32_e32 vcc, s52, v18
	v_sub_u32_e32 v18, v20, v21
	v_cvt_f32_i32_e32 v18, v18
	v_cndmask_b32_e32 v15, v63, v15, vcc
	v_cmp_lt_i32_e32 vcc, v20, v21
	v_mul_f32_e32 v15, v15, v22
	v_cvt_pk_bf16_f32 v15, v15, v33
	ds_write_b16 v17, v15 offset:496
	v_cndmask_b32_e64 v20, -v12, v11, vcc
	v_mul_f32_e32 v18, v20, v18
	v_mul_f32_e32 v20, 0x3fb8aa3b, v18
	v_fma_f32 v23, v18, s50, -v20
	v_rndne_f32_e32 v26, v20
	v_fmac_f32_e32 v23, 0x32a5705f, v18
	v_sub_f32_e32 v20, v20, v26
	v_add_f32_e32 v20, v20, v23
	v_exp_f32_e32 v20, v20
	v_cvt_i32_f32_e32 v23, v26
	v_cmp_ngt_f32_e32 vcc, s51, v18
	v_add3_u32 v76, v30, v58, v98
	v_add3_u32 v80, v30, v80, v100
	v_ldexp_f32 v15, v20, v23
	v_cndmask_b32_e32 v15, 0, v15, vcc
	v_cmp_nlt_f32_e32 vcc, s52, v18
	v_sub_u32_e32 v18, v19, v21
	v_cvt_f32_i32_e32 v18, v18
	v_cndmask_b32_e32 v15, v63, v15, vcc
	v_cmp_lt_i32_e32 vcc, v19, v21
	v_mul_f32_e32 v20, 0x3e000000, v24
	v_mul_f32_e32 v15, v15, v20
	v_cndmask_b32_e64 v19, -v12, v11, vcc
	v_mul_f32_e32 v18, v19, v18
	v_mul_f32_e32 v19, 0x3fb8aa3b, v18
	v_fma_f32 v21, v18, s50, -v19
	v_rndne_f32_e32 v22, v19
	v_fmac_f32_e32 v21, 0x32a5705f, v18
	v_sub_f32_e32 v19, v19, v22
	v_add_f32_e32 v19, v19, v21
	v_exp_f32_e32 v19, v19
	v_cvt_i32_f32_e32 v21, v22
	v_cvt_pk_bf16_f32 v15, v15, v33
	ds_write_b16 v17, v15 offset:768
	v_cmp_ngt_f32_e32 vcc, s51, v18
	v_ldexp_f32 v15, v19, v21
	v_add3_u32 v84, v30, v84, v102
	v_cndmask_b32_e32 v15, 0, v15, vcc
	v_cmp_nlt_f32_e32 vcc, s52, v18
	v_mul_f32_e32 v18, 0x3e000000, v25
	s_nop 0
	v_cndmask_b32_e32 v15, v63, v15, vcc
	v_mul_f32_e32 v15, v15, v18
	v_cvt_pk_bf16_f32 v15, v15, v33
	ds_write_b16 v17, v15 offset:1040
	v_mul_u32_u24_e32 v15, 0x110, v9
	v_add3_u32 v14, v14, v15, v32
	s_waitcnt lgkmcnt(0)
	s_barrier
	ds_read_b128 v[18:21], v14
	v_and_b32_e32 v17, 8, v8
	v_bitop3_b32 v32, v9, 24, 16 bitop3:0xc8
	v_lshlrev_b32_e32 v22, 1, v17
	v_lshlrev_b32_e32 v35, 1, v32
	v_add3_u32 v31, v30, v22, v15
	v_add3_u32 v35, v30, v35, v75
	ds_read_b128 v[22:25], v31
	ds_read_b128 v[26:29], v14 offset:64
	ds_read_b128 v[38:41], v31 offset:64
	ds_read_b128 v[42:45], v35
	ds_read_b128 v[46:49], v31 offset:128
	v_bitop3_b32 v31, v9, 40, 32 bitop3:0xc8
	v_lshlrev_b32_e32 v50, 1, v31
	v_add3_u32 v54, v30, v50, v96
	ds_read_b128 v[50:53], v54
	ds_read_b128 v[54:57], v54 offset:64
	ds_read_b128 v[58:61], v76
	ds_read_b128 v[76:79], v76 offset:64
	ds_read_b128 v[80:83], v80
	ds_read_b128 v[84:87], v84
	ds_read_b128 v[88:91], v88
	ds_read_b128 v[92:95], v92
	s_waitcnt lgkmcnt(12)
	v_mfma_f32_16x16x32_bf16 v[22:25], v[18:21], v[22:25], 0
	v_bfi_b32 v8, -16, v10, v8
	v_add_u32_e32 v10, 1, v8
	v_cvt_f32_i32_e32 v10, v10
	s_waitcnt lgkmcnt(9)
	v_mfma_f32_16x16x32_bf16 v[42:45], v[18:21], v[42:45], 0
	v_sub_u32_e32 v8, 0x80, v8
	v_cvt_f32_i32_e32 v8, v8
	v_mul_f32_e64 v10, v10, -v12
	s_waitcnt lgkmcnt(7)
	v_mfma_f32_16x16x32_bf16 v[50:53], v[18:21], v[50:53], 0
	v_mul_f32_e32 v12, 0x3fb8aa3b, v10
	v_mul_f32_e64 v8, v8, -v11
	v_mul_f32_e32 v11, 0x3fb8aa3b, v8
	s_waitcnt lgkmcnt(5)
	v_mfma_f32_16x16x32_bf16 v[58:61], v[18:21], v[58:61], 0
	v_cmp_ngt_f32_e32 vcc, s51, v10
	s_waitcnt lgkmcnt(3)
	v_mfma_f32_16x16x32_bf16 v[80:83], v[18:21], v[80:83], 0
	s_waitcnt lgkmcnt(2)
	v_mfma_f32_16x16x32_bf16 v[84:87], v[18:21], v[84:87], 0
	s_waitcnt lgkmcnt(1)
	v_mfma_f32_16x16x32_bf16 v[88:91], v[18:21], v[88:91], 0
	s_waitcnt lgkmcnt(0)
	v_mfma_f32_16x16x32_bf16 v[18:21], v[18:21], v[92:95], 0
	v_mfma_f32_16x16x32_bf16 v[22:25], v[26:29], v[38:41], v[22:25]
	ds_read_b128 v[38:41], v35 offset:64
	ds_read_b128 v[92:95], v35 offset:128
	v_or_b32_e32 v35, 32, v13
	s_waitcnt lgkmcnt(1)
	v_mfma_f32_16x16x32_bf16 v[38:41], v[26:29], v[38:41], v[42:45]
	v_mfma_f32_16x16x32_bf16 v[42:45], v[26:29], v[54:57], v[50:53]
	v_add_u32_e32 v54, v35, v99
	v_and_b32_e32 v54, 0x78, v54
	v_lshlrev_b32_e32 v54, 1, v54
	v_add3_u32 v54, 0, v54, v100
	ds_read_b128 v[54:57], v54
	v_mfma_f32_16x16x32_bf16 v[50:53], v[26:29], v[76:79], v[58:61]
	v_add_u32_e32 v76, v35, v103
	v_and_b32_e32 v76, 56, v76
	v_lshlrev_b32_e32 v76, 1, v76
	v_add_u32_e32 v58, v35, v101
	v_add_u32_e32 v35, v35, v105
	v_and_b32_e32 v58, 0x78, v58
	v_and_b32_e32 v35, 56, v35
	v_lshlrev_b32_e32 v58, 1, v58
	v_lshlrev_b32_e32 v35, 1, v35
	v_add3_u32 v58, 0, v58, v102
	v_add3_u32 v76, 0, v76, v104
	v_add3_u32 v35, 0, v35, v106
	ds_read_b128 v[58:61], v58
	ds_read_b128 v[76:79], v76
	s_waitcnt lgkmcnt(2)
; __device__ __forceinline__ unsigned cvt_pk_bf16(float lo, float hi) { unsigned r; asm("v_cvt_pk_bf16_f32 %0, %1, %2" : "=v"(r) : "v"(lo), "v"(hi)); return r; }
; __device__ __forceinline__ float bflo(unsigned w) { return __uint_as_float(w << 16); }
; __device__ __forceinline__ float bfhi(unsigned w) { return __uint_as_float(w & 0xffff0000u); }
; __device__ __forceinline__ bf16x8 scale8(bf16x8 q, float s) {
;     const u32x4 w = un8(q); u32x4 o;
;     o.x = cvt_pk_bf16(bflo(w.x) * s, bfhi(w.x) * s); o.y = cvt_pk_bf16(bflo(w.y) * s, bfhi(w.y) * s);
;     o.z = cvt_pk_bf16(bflo(w.z) * s, bfhi(w.z) * s); o.w = cvt_pk_bf16(bflo(w.w) * s, bfhi(w.w) * s);
;     return mk8(o);
; }
; __device__ __forceinline__ void retout_item(PRef p, int layer, int item, unsigned char* shm) {
;     ...
;     for (int kk = 0; kk < 4; ++kk) { const bf16x8 af = *(const bf16x8*)(Pw + fr * LDK + kk * 32 + fq * 8);
; #pragma unroll
;         for (int et = 0; et < 8; ++et) { const bf16x8 bf = *(const bf16x8*)(vT + tsw(16 * et + fr, kk * 32 + fq * 8));
;             acc[et] = __builtin_amdgcn_mfma_f32_16x16x32_bf16(af, bf, acc[et], 0, 0, 0); } }
;     { const int ca = 16 * wave + fr;
;       const float sf = expf((float)(ca + 1) * lgf), sb = expf((float)(128 - ca) * lgb);
; #pragma unroll
;       for (int kk = 0; kk < 2; ++kk) { const bf16x8 af = scale8(qa[kk], sf), ab = scale8(qa[kk], sb);
	v_mfma_f32_16x16x32_bf16 v[54:57], v[26:29], v[54:57], v[80:83]
	s_nop 2
	ds_read_b128 v[80:83], v35
	s_waitcnt lgkmcnt(2)
	v_mfma_f32_16x16x32_bf16 v[58:61], v[26:29], v[58:61], v[84:87]
	s_waitcnt lgkmcnt(1)
	v_mfma_f32_16x16x32_bf16 v[76:79], v[26:29], v[76:79], v[88:91]
	s_waitcnt lgkmcnt(0)
	v_mfma_f32_16x16x32_bf16 v[18:21], v[26:29], v[80:83], v[18:21]
	ds_read_b128 v[26:29], v14 offset:128
	ds_read_b128 v[80:83], v14 offset:192
	v_or_b32_e32 v14, 64, v13
	v_add_u32_e32 v35, v14, v31
	v_and_b32_e32 v35, 0x78, v35
	v_lshlrev_b32_e32 v35, 1, v35
	v_add3_u32 v35, 0, v35, v96
	s_waitcnt lgkmcnt(1)
	v_mfma_f32_16x16x32_bf16 v[22:25], v[26:29], v[46:49], v[22:25]
	ds_read_b128 v[46:49], v35
	v_add_u32_e32 v35, v14, v97
	v_and_b32_e32 v35, 0x78, v35
	v_lshlrev_b32_e32 v35, 1, v35
	v_add3_u32 v35, 0, v35, v98
	ds_read_b128 v[84:87], v35
	v_add_u32_e32 v35, v13, v99
	v_and_b32_e32 v35, 56, v35
	v_lshlrev_b32_e32 v35, 1, v35
	v_add3_u32 v35, 0, v35, v100
	s_waitcnt lgkmcnt(1)
	v_mfma_f32_16x16x32_bf16 v[42:45], v[26:29], v[46:49], v[42:45]
	s_waitcnt lgkmcnt(0)
	v_mfma_f32_16x16x32_bf16 v[46:49], v[26:29], v[84:87], v[50:53]
	s_nop 2
	ds_read_b128 v[50:53], v35
	v_add_u32_e32 v35, v13, v101
	v_and_b32_e32 v35, 56, v35
	v_lshlrev_b32_e32 v35, 1, v35
	v_add3_u32 v35, 0, v35, v102
	ds_read_b128 v[84:87], v35
	v_add_u32_e32 v35, v14, v103
	v_add_u32_e32 v14, v14, v105
	v_and_b32_e32 v35, 0x78, v35
	v_and_b32_e32 v14, 0x78, v14
	v_lshlrev_b32_e32 v35, 1, v35
	v_lshlrev_b32_e32 v14, 1, v14
	v_add3_u32 v35, 0, v35, v104
	v_add3_u32 v14, 0, v14, v106
	s_waitcnt lgkmcnt(1)
	v_mfma_f32_16x16x32_bf16 v[50:53], v[26:29], v[50:53], v[54:57]
	v_or_b32_e32 v13, 0x60, v13
	s_waitcnt lgkmcnt(0)
	v_mfma_f32_16x16x32_bf16 v[54:57], v[26:29], v[84:87], v[58:61]
	ds_read_b128 v[84:87], v14
	v_add_u32_e32 v14, v13, v17
	v_and_b32_e32 v14, 0x78, v14
	ds_read_b128 v[58:61], v35
	v_lshlrev_b32_e32 v14, 1, v14
	v_add3_u32 v14, 0, v14, v15
	v_mfma_f32_16x16x32_bf16 v[38:41], v[26:29], v[92:95], v[38:41]
	v_and_b32_e32 v35, 0xffff0000, v7
	s_waitcnt lgkmcnt(0)
	v_mfma_f32_16x16x32_bf16 v[58:61], v[26:29], v[58:61], v[76:79]
	v_mfma_f32_16x16x32_bf16 v[18:21], v[26:29], v[84:87], v[18:21]
	ds_read_b128 v[26:29], v14
	v_add_u32_e32 v14, v13, v32
	v_and_b32_e32 v14, 0x78, v14
	v_lshlrev_b32_e32 v14, 1, v14
	v_add3_u32 v14, 0, v14, v75
	ds_read_b128 v[76:79], v14
	v_add_u32_e32 v14, v13, v31
	v_and_b32_e32 v14, 56, v14
	v_lshlrev_b32_e32 v14, 1, v14
	v_add3_u32 v14, 0, v14, v96
	s_waitcnt lgkmcnt(1)
	v_mfma_f32_16x16x32_bf16 v[22:25], v[80:83], v[26:29], v[22:25]
	v_lshlrev_b32_e32 v32, 16, v7
	s_waitcnt lgkmcnt(0)
	v_mfma_f32_16x16x32_bf16 v[26:29], v[80:83], v[76:79], v[38:41]
	s_nop 2
	ds_read_b128 v[38:41], v14
	v_add_u32_e32 v14, v13, v97
	v_and_b32_e32 v14, 56, v14
	v_lshlrev_b32_e32 v14, 1, v14
	v_add3_u32 v14, 0, v14, v98
	ds_read_b128 v[76:79], v14
	v_add_u32_e32 v14, v13, v99
	v_and_b32_e32 v14, 0x78, v14
	v_lshlrev_b32_e32 v14, 1, v14
	v_add3_u32 v14, 0, v14, v100
	s_waitcnt lgkmcnt(1)
	v_mfma_f32_16x16x32_bf16 v[38:41], v[80:83], v[38:41], v[42:45]
	s_waitcnt lgkmcnt(0)
	v_mfma_f32_16x16x32_bf16 v[42:45], v[80:83], v[76:79], v[46:49]
	s_nop 2
	ds_read_b128 v[46:49], v14
	v_add_u32_e32 v14, v13, v101
	v_and_b32_e32 v14, 0x78, v14
	v_lshlrev_b32_e32 v14, 1, v14
	v_add3_u32 v14, 0, v14, v102
	ds_read_b128 v[76:79], v14
	v_add_u32_e32 v14, v13, v103
	v_add_u32_e32 v13, v13, v105
	v_and_b32_e32 v14, 0x78, v14
	v_and_b32_e32 v13, 0x78, v13
	v_lshlrev_b32_e32 v14, 1, v14
	v_lshlrev_b32_e32 v13, 1, v13
	v_add3_u32 v14, 0, v14, v104
	v_add3_u32 v13, 0, v13, v106
	s_waitcnt lgkmcnt(1)
	v_mfma_f32_16x16x32_bf16 v[46:49], v[80:83], v[46:49], v[50:53]
	s_waitcnt lgkmcnt(0)
	v_mfma_f32_16x16x32_bf16 v[50:53], v[80:83], v[76:79], v[54:57]
	ds_read_b128 v[76:79], v13
	v_fma_f32 v13, v10, s50, -v12
	v_fmac_f32_e32 v13, 0x32a5705f, v10
	ds_read_b128 v[54:57], v14
	v_rndne_f32_e32 v14, v12
	v_sub_f32_e32 v12, v12, v14
	v_add_f32_e32 v12, v12, v13
	v_exp_f32_e32 v17, v12
	v_cvt_i32_f32_e32 v31, v14
	s_waitcnt lgkmcnt(1)
	v_mfma_f32_16x16x32_bf16 v[12:15], v[80:83], v[76:79], v[18:21]
	v_ldexp_f32 v17, v17, v31
	s_nop 1
	v_fma_f32 v18, v8, s50, -v11
	v_rndne_f32_e32 v19, v11
	v_fmac_f32_e32 v18, 0x32a5705f, v8
	v_sub_f32_e32 v11, v11, v19
	v_add_f32_e32 v11, v11, v18
	v_exp_f32_e32 v11, v11
	v_cvt_i32_f32_e32 v18, v19
	v_cndmask_b32_e32 v17, 0, v17, vcc
	v_cmp_nlt_f32_e32 vcc, s52, v10
	v_and_b32_e32 v19, 0xffff0000, v5
	v_ldexp_f32 v10, v11, v18
	v_cndmask_b32_e32 v17, v63, v17, vcc
	v_cmp_ngt_f32_e32 vcc, s51, v8
	v_and_b32_e32 v11, 0xffff0000, v4
	v_and_b32_e32 v21, 0xffff0000, v6
	v_cndmask_b32_e32 v10, 0, v10, vcc
	v_cmp_nlt_f32_e32 vcc, s52, v8
	v_lshlrev_b32_e32 v8, 16, v4
	v_mul_f32_e32 v4, v17, v11
	v_cndmask_b32_e32 v31, v63, v10, vcc
	v_mul_u32_u24_e32 v10, 0x48, v9
	v_mul_f32_e32 v9, v17, v8
	v_cvt_pk_bf16_f32 v4, v9, v4
	v_lshlrev_b32_e32 v9, 16, v5
	v_mul_f32_e32 v18, v17, v9
	v_mul_f32_e32 v5, v17, v19
	v_cvt_pk_bf16_f32 v5, v18, v5
	v_lshlrev_b32_e32 v18, 16, v6
	v_mul_f32_e32 v20, v17, v18
	v_mul_f32_e32 v6, v17, v21
	v_mul_f32_e32 v8, v31, v8
	v_mul_f32_e32 v11, v31, v11
	v_cvt_pk_bf16_f32 v6, v20, v6
	v_mul_f32_e32 v20, v17, v32
	v_mul_f32_e32 v7, v17, v35
	v_cvt_pk_bf16_f32 v8, v8, v11
	v_mul_f32_e32 v9, v31, v9
	v_mul_f32_e32 v11, v31, v19
	v_lshl_add_u32 v30, v10, 1, v30
	s_waitcnt lgkmcnt(0)
	v_mfma_f32_16x16x32_bf16 v[54:57], v[80:83], v[54:57], v[58:61]
	v_cvt_pk_bf16_f32 v7, v20, v7
	v_cvt_pk_bf16_f32 v9, v9, v11
	v_mul_f32_e32 v11, v31, v18
	s_nop 1
	v_mul_f32_e32 v58, v31, v21
	ds_read_b128 v[18:21], v30 offset:34816
	v_cvt_pk_bf16_f32 v10, v11, v58
	ds_read_b128 v[58:61], v30 offset:53248
	ds_read_b128 v[76:79], v30 offset:34880
	s_waitcnt lgkmcnt(2)
; __device__ __forceinline__ float bf2f(unsigned short b) { return __uint_as_float(((unsigned)b) << 16); }
; __device__ __forceinline__ void retout_item(PRef p, int layer, int item, unsigned char* shm) {
;     ...
;     { const int ca = 16 * wave + fr;
;       const float sf = expf((float)(ca + 1) * lgf), sb = expf((float)(128 - ca) * lgb);
; #pragma unroll
;       for (int kk = 0; kk < 2; ++kk) { const bf16x8 af = scale8(qa[kk], sf), ab = scale8(qa[kk], sb);
; #pragma unroll
;           for (int et = 0; et < 8; ++et) { const bf16x8 b1 = *(const bf16x8*)(sTf + (16 * et + fr) * 72 + kk * 32 + fq * 8);
;               acc[et] = __builtin_amdgcn_mfma_f32_16x16x32_bf16(af, b1, acc[et], 0, 0, 0);
;               const bf16x8 b2 = *(const bf16x8*)(sTb + (16 * et + fr) * 72 + kk * 32 + fq * 8);
;               acc[et] = __builtin_amdgcn_mfma_f32_16x16x32_bf16(ab, b2, acc[et], 0, 0, 0); } } }
; #pragma unroll
;     for (int r = 0; r < 4; ++r) { float ss = 0.f;
; #pragma unroll
;         for (int et = 0; et < 8; ++et) ss += acc[et][r] * acc[et][r];
;         ss += __shfl_xor(ss, 1); ss += __shfl_xor(ss, 2); ss += __shfl_xor(ss, 4); ss += __shfl_xor(ss, 8);
;         const float rinv = rsqrtf(ss * (1.f / 128.f) + 1e-6f);
;         const size_t row = (size_t)(row0 + 16 * wave + fq * 4 + r);
; #pragma unroll
;         for (int et = 0; et < 8; ++et) { const int e = 16 * et + fr; const float gg = bf2f(A[row * NIN + C_G + h * 128 + e]);
	v_mfma_f32_16x16x32_bf16 v[18:21], v[4:7], v[18:21], v[22:25]
	v_mul_f32_e32 v11, v31, v32
	s_nop 1
	v_mul_f32_e32 v22, v31, v35
	v_cvt_pk_bf16_f32 v11, v11, v22
	ds_read_b128 v[22:25], v30 offset:53312
	s_waitcnt lgkmcnt(2)
	v_mfma_f32_16x16x32_bf16 v[18:21], v[8:11], v[58:61], v[18:21]
	ds_read_b128 v[58:61], v30 offset:37120
	ds_read_b128 v[80:83], v30 offset:37184
	v_add_u32_e32 v32, 0x900, v30
	v_mov_b32_e32 v35, v33
	s_waitcnt lgkmcnt(1)
	v_mfma_f32_16x16x32_bf16 v[26:29], v[4:7], v[58:61], v[26:29]
	ds_read_b128 v[58:61], v30 offset:55552
	ds_read_b128 v[84:87], v30 offset:55616
	s_waitcnt lgkmcnt(1)
	v_mfma_f32_16x16x32_bf16 v[58:61], v[8:11], v[58:61], v[26:29]
	s_nop 3
	ds_read_b128 v[26:29], v30 offset:39424
	ds_read_b128 v[88:91], v30 offset:39488
	s_waitcnt lgkmcnt(1)
	v_mfma_f32_16x16x32_bf16 v[26:29], v[4:7], v[26:29], v[38:41]
	s_nop 2
	ds_read_b128 v[38:41], v30 offset:57856
	ds_read_b128 v[92:95], v30 offset:57920
	s_waitcnt lgkmcnt(1)
	v_mfma_f32_16x16x32_bf16 v[38:41], v[8:11], v[38:41], v[26:29]
	s_nop 2
	ds_read_b128 v[26:29], v30 offset:41728
	ds_read_b128 v[96:99], v30 offset:41792
	s_waitcnt lgkmcnt(1)
	v_mfma_f32_16x16x32_bf16 v[26:29], v[4:7], v[26:29], v[42:45]
	s_nop 2
	ds_read_b128 v[42:45], v30 offset:60160
	ds_read_b128 v[100:103], v30 offset:60224
	s_waitcnt lgkmcnt(1)
	v_mfma_f32_16x16x32_bf16 v[42:45], v[8:11], v[42:45], v[26:29]
	s_nop 2
	ds_read_b128 v[26:29], v30 offset:44032
	ds_read_b128 v[104:107], v30 offset:44096
	s_waitcnt lgkmcnt(1)
	v_mfma_f32_16x16x32_bf16 v[26:29], v[4:7], v[26:29], v[46:49]
	s_nop 2
	ds_read_b128 v[46:49], v30 offset:62464
	ds_read_b128 v[108:111], v30 offset:62528
	s_waitcnt lgkmcnt(1)
	v_mfma_f32_16x16x32_bf16 v[46:49], v[8:11], v[46:49], v[26:29]
	s_nop 2
	ds_read_b128 v[26:29], v30 offset:46336
	ds_read_b128 v[112:115], v30 offset:46400
	s_waitcnt lgkmcnt(1)
	v_mfma_f32_16x16x32_bf16 v[26:29], v[4:7], v[26:29], v[50:53]
	s_nop 2
	ds_read_b128 v[50:53], v30 offset:64768
	ds_read_b128 v[116:119], v30 offset:64832
	ds_read_b128 v[120:123], v30 offset:48704
	s_waitcnt lgkmcnt(2)
	v_mfma_f32_16x16x32_bf16 v[50:53], v[8:11], v[50:53], v[26:29]
	s_nop 2
	ds_read_b128 v[26:29], v30 offset:48640
	s_waitcnt lgkmcnt(0)
	v_mfma_f32_16x16x32_bf16 v[26:29], v[4:7], v[26:29], v[54:57]
	s_nop 2
	ds_read_b128 v[54:57], v32 offset:64768
	ds_read_b128 v[124:127], v32 offset:64832
	v_add_u32_e32 v32, 0x1200, v30
	ds_read_b128 v[128:131], v30 offset:51008
	s_waitcnt lgkmcnt(2)
	v_mfma_f32_16x16x32_bf16 v[54:57], v[8:11], v[54:57], v[26:29]
	s_nop 2
	ds_read_b128 v[26:29], v30 offset:50944
	s_waitcnt lgkmcnt(0)
	v_mfma_f32_16x16x32_bf16 v[4:7], v[4:7], v[26:29], v[12:15]
	s_nop 2
	ds_read_b128 v[12:15], v32 offset:64768
	ds_read_b128 v[132:135], v32 offset:64832
	v_xor_b32_e32 v32, 1, v74
	s_waitcnt lgkmcnt(1)
	v_mfma_f32_16x16x32_bf16 v[136:139], v[8:11], v[12:15], v[4:7]
	v_and_b32_e32 v9, 0xffff0000, v3
	s_nop 1
	v_lshlrev_b32_e32 v4, 16, v0
	v_mul_f32_e32 v5, v17, v4
	v_and_b32_e32 v0, 0xffff0000, v0
	v_mul_f32_e32 v6, v17, v0
	v_cvt_pk_bf16_f32 v140, v5, v6
	v_lshlrev_b32_e32 v5, 16, v1
	v_mul_f32_e32 v6, v17, v5
	v_and_b32_e32 v1, 0xffff0000, v1
	v_mul_f32_e32 v7, v17, v1
	v_cvt_pk_bf16_f32 v141, v6, v7
	v_lshlrev_b32_e32 v6, 16, v2
	v_mul_f32_e32 v7, v17, v6
	v_and_b32_e32 v2, 0xffff0000, v2
	v_mul_f32_e32 v8, v17, v2
	v_cvt_pk_bf16_f32 v142, v7, v8
	v_lshlrev_b32_e32 v7, 16, v3
	v_mul_f32_e32 v3, v17, v9
	v_mul_f32_e32 v0, v31, v0
	v_mul_f32_e32 v8, v17, v7
	v_cvt_pk_bf16_f32 v143, v8, v3
	v_mul_f32_e32 v3, v31, v4
	v_cvt_pk_bf16_f32 v144, v3, v0
	v_mul_f32_e32 v0, v31, v5
	v_mul_f32_e32 v1, v31, v1
	v_cvt_pk_bf16_f32 v145, v0, v1
	v_mul_f32_e32 v0, v31, v6
	v_mul_f32_e32 v1, v31, v2
	v_cvt_pk_bf16_f32 v146, v0, v1
	v_mfma_f32_16x16x32_bf16 v[0:3], v[140:143], v[76:79], v[18:21]
	v_mul_f32_e32 v4, v31, v7
	v_mul_f32_e32 v5, v31, v9
	v_cvt_pk_bf16_f32 v147, v4, v5
	s_nop 0
	v_mfma_f32_16x16x32_bf16 v[28:31], v[144:147], v[22:25], v[0:3]
	v_mfma_f32_16x16x32_bf16 v[0:3], v[140:143], v[80:83], v[58:61]
	v_mfma_f32_16x16x32_bf16 v[24:27], v[144:147], v[84:87], v[0:3]
	v_mfma_f32_16x16x32_bf16 v[0:3], v[140:143], v[88:91], v[38:41]
	s_nop 2
	v_add_u32_e32 v38, s62, v16
	v_mad_i64_i32 v[16:17], s[34:35], v38, s46, v[36:37]
	v_lshl_add_u64 v[16:17], v[16:17], 0, s[20:21]
	v_mfma_f32_16x16x32_bf16 v[20:23], v[144:147], v[92:95], v[0:3]
	s_add_u32 s34, s13, s20
	s_addc_u32 s35, s14, 0
	v_mfma_f32_16x16x32_bf16 v[0:3], v[140:143], v[96:99], v[42:45]
	s_nop 2
	v_lshl_add_u64 v[44:45], v[16:17], 0, v[34:35]
	v_add_co_u32_e32 v16, vcc, s48, v44
	v_mfma_f32_16x16x32_bf16 v[12:15], v[144:147], v[100:103], v[0:3]
	s_nop 0
	v_addc_co_u32_e32 v17, vcc, 0, v45, vcc
	global_load_ushort v39, v[16:17], off offset:3072
	v_mfma_f32_16x16x32_bf16 v[0:3], v[140:143], v[104:107], v[46:49]
	v_mfma_f32_16x16x32_bf16 v[8:11], v[144:147], v[108:111], v[0:3]
	s_nop 1
	v_mul_f32_e32 v47, v24, v24
	v_fmac_f32_e32 v47, v28, v28
	v_xor_b32_e32 v49, 8, v74
	v_mfma_f32_16x16x32_bf16 v[0:3], v[140:143], v[112:115], v[50:53]
	v_mfma_f32_16x16x32_bf16 v[40:43], v[140:143], v[128:131], v[136:139]
	v_mfma_f32_16x16x32_bf16 v[4:7], v[144:147], v[116:119], v[0:3]
	v_mfma_f32_16x16x32_bf16 v[0:3], v[140:143], v[120:123], v[54:57]
	s_waitcnt lgkmcnt(0)
	v_mfma_f32_16x16x32_bf16 v[16:19], v[144:147], v[132:135], v[40:43]
	s_waitcnt vmcnt(0)
; __device__ __forceinline__ float bf2f(unsigned short b) { return __uint_as_float(((unsigned)b) << 16); }
; __device__ __forceinline__ unsigned short f2bf(float f) { return (unsigned short)(cvt_pk_bf16(f, 0.f) & 0xffffu); }
; __device__ __forceinline__ float sigmoidf_(float x) { return 1.f / (1.f + __expf(-x)); }
; __device__ __forceinline__ void retout_item(PRef p, int layer, int item, unsigned char* shm) {
;     ...
; #pragma unroll
;     for (int r = 0; r < 4; ++r) { float ss = 0.f;
; #pragma unroll
;         for (int et = 0; et < 8; ++et) ss += acc[et][r] * acc[et][r];
;         ss += __shfl_xor(ss, 1); ss += __shfl_xor(ss, 2); ss += __shfl_xor(ss, 4); ss += __shfl_xor(ss, 8);
;         const float rinv = rsqrtf(ss * (1.f / 128.f) + 1e-6f);
;         const size_t row = (size_t)(row0 + 16 * wave + fq * 4 + r);
; #pragma unroll
;         for (int et = 0; et < 8; ++et) { const int e = 16 * et + fr; const float gg = bf2f(A[row * NIN + C_G + h * 128 + e]);
;             MIX[row * 2048 + 512 + h * 128 + e] = f2bf(acc[et][r] * rinv * gg * sigmoidf_(gg)); } }
	v_lshlrev_b32_e32 v54, 16, v39
	s_nop 1
	v_and_b32_e32 v40, 64, v74
	v_add_u32_e32 v46, 64, v40
	v_lshl_add_u64 v[40:41], v[44:45], 0, s[26:27]
	v_mov_b32_e32 v42, v20
	v_mov_b32_e32 v43, v12
	global_load_ushort v48, v[40:41], off offset:32
	v_pk_mul_f32 v[42:43], v[42:43], v[42:43]
	v_mfma_f32_16x16x32_bf16 v[0:3], v[144:147], v[124:127], v[0:3]
	v_add_f32_e32 v42, v47, v42
	v_add_f32_e32 v44, v42, v43
	v_mov_b32_e32 v42, v8
	v_mov_b32_e32 v43, v4
	v_pk_mul_f32 v[42:43], v[42:43], v[42:43]
	v_cmp_lt_i32_e32 vcc, v32, v46
	v_add_f32_e32 v42, v44, v42
	v_add_f32_e32 v44, v42, v43
	v_mov_b32_e32 v42, v0
	v_mov_b32_e32 v43, v16
	v_pk_mul_f32 v[42:43], v[42:43], v[42:43]
	v_cndmask_b32_e32 v32, v74, v32, vcc
	v_add_f32_e32 v42, v44, v42
	v_lshlrev_b32_e32 v32, 2, v32
	v_add_f32_e32 v42, v42, v43
	ds_bpermute_b32 v43, v32, v42
	v_xor_b32_e32 v44, 2, v74
	v_cmp_lt_i32_e32 vcc, v44, v46
	v_xor_b32_e32 v45, 4, v74
	v_mul_f32_e32 v39, 0xbfb8aa3b, v54
	v_cndmask_b32_e32 v44, v74, v44, vcc
	v_lshlrev_b32_e32 v44, 2, v44
	s_waitcnt lgkmcnt(0)
	v_add_f32_e32 v42, v42, v43
	ds_bpermute_b32 v47, v44, v42
	global_load_ushort v43, v[40:41], off offset:64
	v_cmp_lt_i32_e32 vcc, v45, v46
	v_exp_f32_e32 v55, v39
	v_ashrrev_i32_e32 v39, 31, v38
	v_cndmask_b32_e32 v45, v74, v45, vcc
	v_lshlrev_b32_e32 v45, 2, v45
	s_waitcnt lgkmcnt(0)
	v_add_f32_e32 v42, v42, v47
	ds_bpermute_b32 v47, v45, v42
	v_cmp_lt_i32_e32 vcc, v49, v46
	s_waitcnt lgkmcnt(0)
	v_add_f32_e32 v42, v42, v47
	v_cndmask_b32_e32 v46, v74, v49, vcc
	v_lshlrev_b32_e32 v46, 2, v46
	ds_bpermute_b32 v47, v46, v42
	s_waitcnt lgkmcnt(0)
	v_add_f32_e32 v42, v42, v47
	v_fmamk_f32 v42, v42, 0x3c000000, v62
	v_mul_f32_e32 v47, 0x4b800000, v42
	v_cmp_gt_f32_e32 vcc, s56, v42
	s_nop 1
	v_cndmask_b32_e32 v42, v42, v47, vcc
	global_load_ushort v47, v[40:41], off offset:96
	global_load_ushort v50, v[40:41], off offset:128
	global_load_ushort v51, v[40:41], off offset:160
	global_load_ushort v52, v[40:41], off offset:192
	global_load_ushort v53, v[40:41], off offset:224
	v_rsq_f32_e32 v42, v42
	v_lshlrev_b64 v[40:41], 12, v[38:39]
	v_add_f32_e32 v39, 1.0, v55
	v_lshl_add_u64 v[40:41], s[34:35], 0, v[40:41]
	v_mul_f32_e32 v49, 0x45800000, v42
	v_cndmask_b32_e32 v56, v42, v49, vcc
	v_rcp_f32_e32 v39, v39
	v_mul_f32_e32 v28, v28, v56
	v_mul_f32_e32 v28, v28, v54
	v_lshl_add_u64 v[40:41], v[40:41], 0, v[34:35]
	v_mul_f32_e32 v28, v39, v28
	v_cvt_pk_bf16_f32 v28, v28, v33
	s_waitcnt vmcnt(6)
	v_lshlrev_b32_e32 v42, 16, v48
	v_mul_f32_e32 v48, 0xbfb8aa3b, v42
	v_exp_f32_e32 v48, v48
	global_store_short v[40:41], v28, off
	v_mul_f32_e32 v24, v24, v56
	v_mul_f32_e32 v24, v24, v42
	v_add_f32_e32 v39, 1.0, v48
	v_rcp_f32_e32 v28, v39
	v_mul_f32_e32 v20, v20, v56
	v_mul_f32_e32 v12, v12, v56
	v_mul_f32_e32 v8, v8, v56
	v_mul_f32_e32 v24, v24, v28
	v_cvt_pk_bf16_f32 v24, v24, v33
	global_store_short v[40:41], v24, off offset:32
	v_mul_f32_e32 v4, v4, v56
	s_waitcnt vmcnt(7)
	v_lshlrev_b32_e32 v42, 16, v43
	v_mul_f32_e32 v43, 0xbfb8aa3b, v42
	v_exp_f32_e32 v43, v43
	v_mul_f32_e32 v20, v20, v42
	v_mul_f32_e32 v0, v0, v56
	v_add_f32_e32 v28, 1.0, v43
	v_rcp_f32_e32 v24, v28
	s_nop 0
	v_mul_f32_e32 v20, v20, v24
	v_cvt_pk_bf16_f32 v20, v20, v33
	global_store_short v[40:41], v20, off offset:64
	s_waitcnt vmcnt(7)
	v_lshlrev_b32_e32 v39, 16, v47
	v_mul_f32_e32 v42, 0xbfb8aa3b, v39
	v_exp_f32_e32 v42, v42
	v_mul_f32_e32 v12, v12, v39
	v_add_f32_e32 v24, 1.0, v42
	v_rcp_f32_e32 v20, v24
	s_nop 0
	s_waitcnt vmcnt(6)
	v_lshlrev_b32_e32 v28, 16, v50
	v_mul_f32_e32 v39, 0xbfb8aa3b, v28
	v_exp_f32_e32 v39, v39
	v_mul_f32_e32 v12, v12, v20
	v_cvt_pk_bf16_f32 v12, v12, v33
	v_add_f32_e32 v20, 1.0, v39
	v_rcp_f32_e32 v39, v20
	global_store_short v[40:41], v12, off offset:96
	v_mul_f32_e32 v8, v8, v28
	s_waitcnt vmcnt(6)
	v_lshlrev_b32_e32 v24, 16, v51
	v_mul_f32_e32 v28, 0xbfb8aa3b, v24
	v_exp_f32_e32 v28, v28
	v_mov_b32_e32 v12, v39
	v_mul_f32_e32 v8, v8, v12
	v_cvt_pk_bf16_f32 v8, v8, v33
	v_add_f32_e32 v12, 1.0, v28
	v_rcp_f32_e32 v28, v12
	global_store_short v[40:41], v8, off offset:128
	v_mul_f32_e32 v4, v4, v24
	v_or_b32_e32 v42, 1, v38
	s_waitcnt vmcnt(6)
	v_lshlrev_b32_e32 v20, 16, v52
	v_mul_f32_e32 v24, 0xbfb8aa3b, v20
	v_mad_i64_i32 v[48:49], s[36:37], v42, s46, v[36:37]
	v_exp_f32_e32 v24, v24
	v_lshl_add_u64 v[48:49], v[48:49], 0, s[20:21]
	v_lshl_add_u64 v[48:49], v[48:49], 0, v[34:35]
	v_add_co_u32_e32 v50, vcc, s48, v48
	v_mov_b32_e32 v8, v28
	s_nop 0
	v_addc_co_u32_e32 v51, vcc, 0, v49, vcc
	v_mul_f32_e32 v4, v4, v8
	v_add_f32_e32 v8, 1.0, v24
	global_load_ushort v24, v[50:51], off offset:3072
	v_rcp_f32_e32 v28, v8
	v_cvt_pk_bf16_f32 v4, v4, v33
	global_store_short v[40:41], v4, off offset:160
	v_mul_f32_e32 v0, v0, v20
	v_mov_b32_e32 v4, v28
	s_waitcnt vmcnt(7)
	v_lshlrev_b32_e32 v8, 16, v53
	v_mul_f32_e32 v0, v0, v4
	v_mul_f32_e32 v4, 0xbfb8aa3b, v8
	v_lshl_add_u64 v[48:49], v[48:49], 0, s[26:27]
	v_exp_f32_e32 v39, v4
	v_mul_f32_e32 v4, v25, v25
	v_mov_b32_e32 v12, v21
	global_load_ushort v28, v[48:49], off offset:32
	global_load_ushort v47, v[48:49], off offset:64
	v_fmac_f32_e32 v4, v29, v29
	v_mul_f32_e32 v20, v16, v56
	v_fma_f32 v4, v12, v12, v4
	v_fma_f32 v12, v13, v13, v4
	v_mov_b32_e32 v4, v9
	v_mov_b32_e32 v16, v1
	v_fma_f32 v4, v4, v4, v12
	v_fma_f32 v4, v5, v5, v4
	v_pk_mul_f32 v[50:51], v[16:17], v[16:17]
	v_add_f32_e32 v16, 1.0, v39
	v_add_f32_e32 v4, v4, v50
	v_add_f32_e32 v4, v4, v51
	ds_bpermute_b32 v12, v32, v4
	v_rcp_f32_e32 v43, v16
	v_cvt_pk_bf16_f32 v0, v0, v33
	s_waitcnt lgkmcnt(0)
	v_add_f32_e32 v4, v4, v12
	ds_bpermute_b32 v12, v44, v4
	global_store_short v[40:41], v0, off offset:192
	v_mul_f32_e32 v0, v20, v8
	s_waitcnt lgkmcnt(0)
; __device__ __forceinline__ float bf2f(unsigned short b) { return __uint_as_float(((unsigned)b) << 16); }
; __device__ __forceinline__ unsigned short f2bf(float f) { return (unsigned short)(cvt_pk_bf16(f, 0.f) & 0xffffu); }
; __device__ __forceinline__ float sigmoidf_(float x) { return 1.f / (1.f + __expf(-x)); }
; __device__ __forceinline__ void retout_item(PRef p, int layer, int item, unsigned char* shm) {
;     ...
; #pragma unroll
;     for (int r = 0; r < 4; ++r) { float ss = 0.f;
; #pragma unroll
;         for (int et = 0; et < 8; ++et) ss += acc[et][r] * acc[et][r];
;         ss += __shfl_xor(ss, 1); ss += __shfl_xor(ss, 2); ss += __shfl_xor(ss, 4); ss += __shfl_xor(ss, 8);
;         const float rinv = rsqrtf(ss * (1.f / 128.f) + 1e-6f);
;         const size_t row = (size_t)(row0 + 16 * wave + fq * 4 + r);
; #pragma unroll
;         for (int et = 0; et < 8; ++et) { const int e = 16 * et + fr; const float gg = bf2f(A[row * NIN + C_G + h * 128 + e]);
;             MIX[row * 2048 + 512 + h * 128 + e] = f2bf(acc[et][r] * rinv * gg * sigmoidf_(gg)); } }
	v_add_f32_e32 v4, v4, v12
	ds_bpermute_b32 v8, v45, v4
	s_waitcnt lgkmcnt(0)
	v_add_f32_e32 v4, v4, v8
	ds_bpermute_b32 v8, v46, v4
	v_mov_b32_e32 v12, v43
	s_waitcnt lgkmcnt(0)
	v_add_f32_e32 v4, v4, v8
	v_fmamk_f32 v4, v4, 0x3c000000, v62
	v_mul_f32_e32 v8, 0x4b800000, v4
	v_cmp_gt_f32_e32 vcc, s56, v4
	v_mul_f32_e32 v0, v0, v12
	v_cvt_pk_bf16_f32 v0, v0, v33
	global_store_short v[40:41], v0, off offset:224
	v_cndmask_b32_e32 v4, v4, v8, vcc
	global_load_ushort v8, v[48:49], off offset:96
	global_load_ushort v12, v[48:49], off offset:128
	global_load_ushort v16, v[48:49], off offset:160
	global_load_ushort v20, v[48:49], off offset:192
	global_load_ushort v39, v[48:49], off offset:224
	v_rsq_f32_e32 v4, v4
	v_ashrrev_i32_e32 v43, 31, v42
	v_mul_f32_e32 v0, 0x45800000, v4
	v_cndmask_b32_e32 v49, v4, v0, vcc
	v_mul_f32_e32 v29, v29, v49
	s_waitcnt vmcnt(10)
	v_lshlrev_b32_e32 v24, 16, v24
	v_mul_f32_e32 v40, 0xbfb8aa3b, v24
	v_exp_f32_e32 v48, v40
	v_lshlrev_b64 v[40:41], 12, v[42:43]
	v_mul_f32_e32 v24, v29, v24
	v_lshl_add_u64 v[40:41], s[34:35], 0, v[40:41]
	v_add_f32_e32 v0, 1.0, v48
	v_rcp_f32_e32 v0, v0
	v_mul_f32_e32 v1, v1, v49
	v_mul_f32_e32 v17, v17, v49
	v_mul_f32_e32 v0, v0, v24
	s_waitcnt vmcnt(8)
	v_lshlrev_b32_e32 v4, 16, v28
	v_mul_f32_e32 v28, 0xbfb8aa3b, v4
	v_exp_f32_e32 v42, v28
	v_lshl_add_u64 v[28:29], v[40:41], 0, v[34:35]
	v_cvt_pk_bf16_f32 v0, v0, v33
	global_store_short v[28:29], v0, off
	v_add_f32_e32 v24, 1.0, v42
	v_rcp_f32_e32 v41, v24
	v_mul_f32_e32 v0, v25, v49
	v_mul_f32_e32 v0, v0, v4
	s_waitcnt vmcnt(8)
	v_lshlrev_b32_e32 v25, 16, v47
	v_mul_f32_e32 v40, 0xbfb8aa3b, v25
	v_exp_f32_e32 v40, v40
	v_mov_b32_e32 v4, v41
	v_mul_f32_e32 v0, v0, v4
	v_cvt_pk_bf16_f32 v0, v0, v33
	v_add_f32_e32 v4, 1.0, v40
	v_rcp_f32_e32 v4, v4
	global_store_short v[28:29], v0, off offset:32
	v_mul_f32_e32 v0, v21, v49
	v_mul_f32_e32 v0, v0, v25
	v_mul_f32_e32 v0, v0, v4
	v_cvt_pk_bf16_f32 v0, v0, v33
	s_waitcnt vmcnt(6)
	v_lshlrev_b32_e32 v8, 16, v8
	v_mul_f32_e32 v24, 0xbfb8aa3b, v8
	v_exp_f32_e32 v24, v24
	global_store_short v[28:29], v0, off offset:64
	v_mul_f32_e32 v0, v13, v49
	v_mul_f32_e32 v0, v0, v8
	v_add_f32_e32 v4, 1.0, v24
	v_rcp_f32_e32 v4, v4
	s_waitcnt vmcnt(6)
	v_lshlrev_b32_e32 v12, 16, v12
	v_mul_f32_e32 v13, 0xbfb8aa3b, v12
	v_exp_f32_e32 v13, v13
	v_mul_f32_e32 v0, v0, v4
	v_cvt_pk_bf16_f32 v0, v0, v33
	v_add_f32_e32 v4, 1.0, v13
	v_rcp_f32_e32 v4, v4
	global_store_short v[28:29], v0, off offset:96
	v_mul_f32_e32 v0, v9, v49
	v_mul_f32_e32 v0, v0, v12
	s_waitcnt vmcnt(6)
	v_lshlrev_b32_e32 v9, 16, v16
	v_mul_f32_e32 v12, 0xbfb8aa3b, v9
	v_exp_f32_e32 v12, v12
	v_mul_f32_e32 v0, v0, v4
	v_cvt_pk_bf16_f32 v0, v0, v33
	v_add_f32_e32 v4, 1.0, v12
	v_rcp_f32_e32 v4, v4
	global_store_short v[28:29], v0, off offset:128
	v_mul_f32_e32 v0, v5, v49
	v_mul_f32_e32 v0, v0, v9
	s_waitcnt vmcnt(6)
	v_lshlrev_b32_e32 v12, 16, v20
	v_mul_f32_e32 v8, 0xbfb8aa3b, v12
	v_exp_f32_e32 v8, v8
	v_mul_f32_e32 v0, v0, v4
	v_cvt_pk_bf16_f32 v13, v0, v33
	v_or_b32_e32 v0, 2, v38
	v_mad_i64_i32 v[4:5], s[36:37], v0, s46, v[36:37]
	v_lshl_add_u64 v[4:5], v[4:5], 0, s[20:21]
	v_add_f32_e32 v16, 1.0, v8
	v_lshl_add_u64 v[4:5], v[4:5], 0, v[34:35]
	v_add_co_u32_e32 v8, vcc, s48, v4
	v_rcp_f32_e32 v21, v16
	s_nop 0
	v_addc_co_u32_e32 v9, vcc, 0, v5, vcc
	global_load_ushort v24, v[8:9], off offset:3072
	v_mul_f32_e32 v1, v1, v12
	v_mov_b32_e32 v8, v21
	v_mul_f32_e32 v1, v1, v8
	v_cvt_pk_bf16_f32 v1, v1, v33
	global_store_short v[28:29], v1, off offset:192
	s_waitcnt vmcnt(7)
	v_lshlrev_b32_e32 v1, 16, v39
	v_mul_f32_e32 v8, 0xbfb8aa3b, v1
	global_store_short v[28:29], v13, off offset:160
	v_exp_f32_e32 v12, v8
	v_mul_f32_e32 v13, v26, v26
	v_mov_b32_e32 v8, v22
	v_mov_b32_e32 v9, v14
	v_fmac_f32_e32 v13, v30, v30
	v_pk_mul_f32 v[8:9], v[8:9], v[8:9]
	v_lshl_add_u64 v[4:5], v[4:5], 0, s[26:27]
	v_add_f32_e32 v8, v13, v8
	global_load_ushort v16, v[4:5], off offset:32
	global_load_ushort v21, v[4:5], off offset:64
	v_add_f32_e32 v13, v8, v9
	v_mov_b32_e32 v8, v10
	v_mov_b32_e32 v9, v6
	v_pk_mul_f32 v[8:9], v[8:9], v[8:9]
	v_add_f32_e32 v12, 1.0, v12
	v_add_f32_e32 v8, v13, v8
	v_add_f32_e32 v13, v8, v9
	v_mov_b32_e32 v8, v2
	v_mov_b32_e32 v9, v18
	v_pk_mul_f32 v[8:9], v[8:9], v[8:9]
	v_mul_f32_e32 v1, v17, v1
	v_add_f32_e32 v8, v13, v8
	v_add_f32_e32 v8, v8, v9
	ds_bpermute_b32 v9, v32, v8
	v_rcp_f32_e32 v12, v12
	s_waitcnt lgkmcnt(0)
	v_add_f32_e32 v8, v8, v9
	ds_bpermute_b32 v9, v44, v8
	s_waitcnt lgkmcnt(0)
	v_add_f32_e32 v8, v8, v9
	ds_bpermute_b32 v9, v45, v8
	s_waitcnt lgkmcnt(0)
	v_add_f32_e32 v8, v8, v9
	ds_bpermute_b32 v9, v46, v8
	v_mul_f32_e32 v1, v1, v12
	v_cvt_pk_bf16_f32 v1, v1, v33
	s_waitcnt lgkmcnt(0)
	v_add_f32_e32 v8, v8, v9
	v_fmamk_f32 v8, v8, 0x3c000000, v62
	v_mul_f32_e32 v9, 0x4b800000, v8
	v_cmp_gt_f32_e32 vcc, s56, v8
	global_store_short v[28:29], v1, off offset:224
	s_nop 0
	v_cndmask_b32_e32 v8, v8, v9, vcc
	global_load_ushort v9, v[4:5], off offset:96
	global_load_ushort v12, v[4:5], off offset:128
	global_load_ushort v13, v[4:5], off offset:160
	global_load_ushort v17, v[4:5], off offset:192
	s_nop 0
	global_load_ushort v5, v[4:5], off offset:224
	v_rsq_f32_e32 v8, v8
	s_waitcnt vmcnt(10)
	v_lshlrev_b32_e32 v4, 16, v24
	v_mul_f32_e32 v20, 0xbfb8aa3b, v4
	v_exp_f32_e32 v20, v20
	v_mul_f32_e32 v1, 0x45800000, v8
	v_cndmask_b32_e32 v24, v8, v1, vcc
	v_mul_f32_e32 v28, v30, v24
	v_add_f32_e32 v8, 1.0, v20
	v_rcp_f32_e32 v8, v8
	v_mul_f32_e32 v4, v28, v4
	v_ashrrev_i32_e32 v1, 31, v0
	v_lshlrev_b64 v[0:1], 12, v[0:1]
	v_mul_f32_e32 v4, v8, v4
	v_lshl_add_u64 v[0:1], s[34:35], 0, v[0:1]
	v_cvt_pk_bf16_f32 v4, v4, v33
	s_waitcnt vmcnt(7)
; __device__ __forceinline__ float bf2f(unsigned short b) { return __uint_as_float(((unsigned)b) << 16); }
; __device__ __forceinline__ unsigned short f2bf(float f) { return (unsigned short)(cvt_pk_bf16(f, 0.f) & 0xffffu); }
; __device__ __forceinline__ float sigmoidf_(float x) { return 1.f / (1.f + __expf(-x)); }
; __device__ __forceinline__ void retout_item(PRef p, int layer, int item, unsigned char* shm) {
;     ...
; #pragma unroll
;     for (int r = 0; r < 4; ++r) { float ss = 0.f;
; #pragma unroll
;         for (int et = 0; et < 8; ++et) ss += acc[et][r] * acc[et][r];
;         ss += __shfl_xor(ss, 1); ss += __shfl_xor(ss, 2); ss += __shfl_xor(ss, 4); ss += __shfl_xor(ss, 8);
;         const float rinv = rsqrtf(ss * (1.f / 128.f) + 1e-6f);
;         const size_t row = (size_t)(row0 + 16 * wave + fq * 4 + r);
; #pragma unroll
;         for (int et = 0; et < 8; ++et) { const int e = 16 * et + fr; const float gg = bf2f(A[row * NIN + C_G + h * 128 + e]);
;             MIX[row * 2048 + 512 + h * 128 + e] = f2bf(acc[et][r] * rinv * gg * sigmoidf_(gg)); } }
;     __syncthreads();
	v_lshlrev_b32_e32 v16, 16, v16
	v_mul_f32_e32 v20, 0xbfb8aa3b, v16
	v_exp_f32_e32 v20, v20
	v_lshl_add_u64 v[0:1], v[0:1], 0, v[34:35]
	global_store_short v[0:1], v4, off
	v_mul_f32_e32 v4, v26, v24
	v_add_f32_e32 v8, 1.0, v20
	v_rcp_f32_e32 v8, v8
	v_mul_f32_e32 v4, v4, v16
	v_mul_f32_e32 v2, v2, v24
	s_waitcnt vmcnt(7)
	v_lshlrev_b32_e32 v20, 16, v21
	v_mul_f32_e32 v21, 0xbfb8aa3b, v20
	v_exp_f32_e32 v21, v21
	v_mul_f32_e32 v4, v4, v8
	v_add_f32_e32 v8, 1.0, v21
	v_rcp_f32_e32 v8, v8
	v_cvt_pk_bf16_f32 v4, v4, v33
	global_store_short v[0:1], v4, off offset:32
	v_mul_f32_e32 v4, v22, v24
	v_mul_f32_e32 v4, v4, v20
	s_waitcnt vmcnt(6)
	v_lshlrev_b32_e32 v9, 16, v9
	v_mul_f32_e32 v20, 0xbfb8aa3b, v9
	v_exp_f32_e32 v20, v20
	v_mul_f32_e32 v4, v4, v8
	v_cvt_pk_bf16_f32 v4, v4, v33
	global_store_short v[0:1], v4, off offset:64
	v_add_f32_e32 v8, 1.0, v20
	v_rcp_f32_e32 v8, v8
	v_mul_f32_e32 v4, v14, v24
	v_mul_f32_e32 v4, v4, v9
	s_waitcnt vmcnt(6)
	v_lshlrev_b32_e32 v12, 16, v12
	v_mul_f32_e32 v14, 0xbfb8aa3b, v12
	v_exp_f32_e32 v14, v14
	v_mul_f32_e32 v4, v4, v8
	v_cvt_pk_bf16_f32 v4, v4, v33
	v_add_f32_e32 v8, 1.0, v14
	v_rcp_f32_e32 v8, v8
	global_store_short v[0:1], v4, off offset:96
	v_mul_f32_e32 v4, v10, v24
	v_mul_f32_e32 v4, v4, v12
	s_waitcnt vmcnt(6)
	v_lshlrev_b32_e32 v10, 16, v13
	v_mul_f32_e32 v12, 0xbfb8aa3b, v10
	v_exp_f32_e32 v12, v12
	v_mul_f32_e32 v4, v4, v8
	v_cvt_pk_bf16_f32 v4, v4, v33
	v_add_f32_e32 v8, 1.0, v12
	v_rcp_f32_e32 v12, v8
	global_store_short v[0:1], v4, off offset:128
	v_mul_f32_e32 v4, v6, v24
	v_mul_f32_e32 v4, v4, v10
	s_waitcnt vmcnt(6)
	v_lshlrev_b32_e32 v10, 16, v17
	v_mul_f32_e32 v9, 0xbfb8aa3b, v10
	v_exp_f32_e32 v9, v9
	v_mov_b32_e32 v6, v12
	v_mul_f32_e32 v4, v4, v6
	v_cvt_pk_bf16_f32 v6, v4, v33
	v_or_b32_e32 v4, 3, v38
	v_add_f32_e32 v14, 1.0, v9
	v_mad_i64_i32 v[8:9], s[36:37], v4, s46, v[36:37]
	v_lshl_add_u64 v[8:9], v[8:9], 0, s[20:21]
	v_lshl_add_u64 v[8:9], v[8:9], 0, v[34:35]
	v_add_co_u32_e32 v12, vcc, s48, v8
	global_store_short v[0:1], v6, off offset:160
	s_nop 0
	v_addc_co_u32_e32 v13, vcc, 0, v9, vcc
	global_load_ushort v16, v[12:13], off offset:3072
	v_rcp_f32_e32 v6, v14
	v_mul_f32_e32 v2, v2, v10
	s_waitcnt vmcnt(7)
	v_lshlrev_b32_e32 v5, 16, v5
	v_lshl_add_u64 v[8:9], v[8:9], 0, s[26:27]
	v_mul_f32_e32 v2, v2, v6
	v_mul_f32_e32 v6, 0xbfb8aa3b, v5
	v_exp_f32_e32 v20, v6
	v_mul_f32_e32 v6, v27, v27
	v_mov_b32_e32 v14, v23
	v_fmac_f32_e32 v6, v31, v31
	global_load_ushort v17, v[8:9], off offset:32
	v_fma_f32 v6, v14, v14, v6
	v_fma_f32 v14, v15, v15, v6
	v_mov_b32_e32 v6, v11
	v_mul_f32_e32 v10, v18, v24
	v_fma_f32 v6, v6, v6, v14
	v_mov_b32_e32 v18, v3
	v_fma_f32 v6, v7, v7, v6
	v_cvt_pk_bf16_f32 v2, v2, v33
	global_store_short v[0:1], v2, off offset:192
	v_fma_f32 v6, v18, v18, v6
	v_fma_f32 v6, v19, v19, v6
	ds_bpermute_b32 v12, v32, v6
	v_add_f32_e32 v13, 1.0, v20
	v_rcp_f32_e32 v18, v13
	s_waitcnt lgkmcnt(0)
	v_add_f32_e32 v6, v6, v12
	ds_bpermute_b32 v12, v44, v6
	global_load_ushort v20, v[8:9], off offset:64
	v_mul_f32_e32 v2, v10, v5
	s_waitcnt lgkmcnt(0)
	v_add_f32_e32 v5, v6, v12
	ds_bpermute_b32 v6, v45, v5
	s_waitcnt lgkmcnt(0)
	v_add_f32_e32 v5, v5, v6
	ds_bpermute_b32 v6, v46, v5
	v_mov_b32_e32 v10, v18
	s_waitcnt lgkmcnt(0)
	v_add_f32_e32 v5, v5, v6
	v_fmamk_f32 v5, v5, 0x3c000000, v62
	v_mul_f32_e32 v6, 0x4b800000, v5
	v_cmp_gt_f32_e32 vcc, s56, v5
	v_mul_f32_e32 v2, v2, v10
	v_cvt_pk_bf16_f32 v2, v2, v33
	global_store_short v[0:1], v2, off offset:224
	v_cndmask_b32_e32 v5, v5, v6, vcc
	global_load_ushort v6, v[8:9], off offset:96
	global_load_ushort v2, v[8:9], off offset:128
	global_load_ushort v10, v[8:9], off offset:160
	global_load_ushort v12, v[8:9], off offset:192
	s_nop 0
	global_load_ushort v8, v[8:9], off offset:224
	v_rsq_f32_e32 v5, v5
	s_waitcnt vmcnt(9)
	v_lshlrev_b32_e32 v9, 16, v16
	v_mul_f32_e32 v1, 0xbfb8aa3b, v9
	v_exp_f32_e32 v13, v1
	v_mul_f32_e32 v0, 0x45800000, v5
	v_cndmask_b32_e32 v14, v5, v0, vcc
	v_ashrrev_i32_e32 v5, 31, v4
	v_lshlrev_b64 v[0:1], 12, v[4:5]
	v_add_f32_e32 v4, 1.0, v13
	v_rcp_f32_e32 v4, v4
	v_mul_f32_e32 v16, v31, v14
	v_mul_f32_e32 v9, v16, v9
	v_lshl_add_u64 v[0:1], s[34:35], 0, v[0:1]
	s_waitcnt vmcnt(8)
	v_lshlrev_b32_e32 v5, 16, v17
	v_mul_f32_e32 v13, 0xbfb8aa3b, v5
	v_exp_f32_e32 v13, v13
	v_mul_f32_e32 v4, v4, v9
	v_cvt_pk_bf16_f32 v4, v4, v33
	v_lshl_add_u64 v[0:1], v[0:1], 0, v[34:35]
	v_add_f32_e32 v9, 1.0, v13
	global_store_short v[0:1], v4, off
	v_mul_f32_e32 v4, v27, v14
	v_mul_f32_e32 v4, v4, v5
	s_waitcnt vmcnt(7)
	v_lshlrev_b32_e32 v13, 16, v20
	v_mul_f32_e32 v16, 0xbfb8aa3b, v13
	v_exp_f32_e32 v16, v16
	v_rcp_f32_e32 v5, v9
	s_nop 0
	v_mul_f32_e32 v4, v4, v5
	v_cvt_pk_bf16_f32 v4, v4, v33
	v_add_f32_e32 v5, 1.0, v16
	v_rcp_f32_e32 v5, v5
	global_store_short v[0:1], v4, off offset:32
	v_mul_f32_e32 v4, v23, v14
	v_mul_f32_e32 v4, v4, v13
	s_waitcnt vmcnt(6)
	v_lshlrev_b32_e32 v6, 16, v6
	v_mul_f32_e32 v13, 0xbfb8aa3b, v6
	v_exp_f32_e32 v13, v13
	v_mul_f32_e32 v4, v4, v5
	v_cvt_pk_bf16_f32 v4, v4, v33
	global_store_short v[0:1], v4, off offset:64
	v_add_f32_e32 v5, 1.0, v13
	v_rcp_f32_e32 v5, v5
	v_mul_f32_e32 v4, v15, v14
	v_mul_f32_e32 v4, v4, v6
	s_waitcnt vmcnt(6)
	v_lshlrev_b32_e32 v2, 16, v2
	v_mul_f32_e32 v9, 0xbfb8aa3b, v2
	v_exp_f32_e32 v9, v9
	v_mul_f32_e32 v4, v4, v5
	v_add_f32_e32 v5, 1.0, v9
	v_cvt_pk_bf16_f32 v4, v4, v33
	global_store_short v[0:1], v4, off offset:96
	v_mul_f32_e32 v4, v11, v14
	v_mul_f32_e32 v2, v4, v2
	s_waitcnt vmcnt(6)
	v_lshlrev_b32_e32 v6, 16, v10
	v_mul_f32_e32 v9, 0xbfb8aa3b, v6
	v_exp_f32_e32 v9, v9
	v_rcp_f32_e32 v4, v5
	s_nop 0
	v_mul_f32_e32 v2, v2, v4
	v_cvt_pk_bf16_f32 v2, v2, v33
	v_add_f32_e32 v4, 1.0, v9
	v_rcp_f32_e32 v4, v4
	global_store_short v[0:1], v2, off offset:128
	v_mul_f32_e32 v2, v7, v14
	v_mul_f32_e32 v2, v2, v6
	s_waitcnt vmcnt(6)
	v_lshlrev_b32_e32 v6, 16, v12
	v_mul_f32_e32 v7, 0xbfb8aa3b, v6
	v_exp_f32_e32 v7, v7
	v_mul_f32_e32 v2, v2, v4
	v_cvt_pk_bf16_f32 v2, v2, v33
	v_add_f32_e32 v4, 1.0, v7
	v_rcp_f32_e32 v7, v4
	global_store_short v[0:1], v2, off offset:160
	v_mul_f32_e32 v2, v3, v14
	v_mul_f32_e32 v2, v2, v6
	s_waitcnt vmcnt(6)
	v_lshlrev_b32_e32 v5, 16, v8
	v_mul_f32_e32 v6, 0xbfb8aa3b, v5
	v_exp_f32_e32 v6, v6
	v_mov_b32_e32 v3, v7
	v_mul_f32_e32 v2, v2, v3
	v_cvt_pk_bf16_f32 v2, v2, v33
	v_add_f32_e32 v3, 1.0, v6
	v_rcp_f32_e32 v3, v3
	global_store_short v[0:1], v2, off offset:192
	v_mul_f32_e32 v2, v19, v14
	v_mul_f32_e32 v2, v2, v5
	v_mul_f32_e32 v2, v2, v3
	s_mov_b64 s[34:35], 0
	v_cvt_pk_bf16_f32 v2, v2, v33
	global_store_short v[0:1], v2, off offset:224
	s_barrier

; __device__ __forceinline__ int otid() { int t = (int)__builtin_amdgcn_workitem_id_x(); asm volatile("" : "+v"(t)); return t; }
; __device__ __forceinline__ void final_norm_phase(const float* h, const float* g, float* out) {
;     const int lane = otid() & 63, gw = blockIdx.x * 8 + (otid() >> 6), ngw = gridDim.x * 8;
;     for (int row = gw; row < RL; row += ngw) {
;         const float4* xr = (const float4*)(h + (size_t)row * D) + lane;
;         float4 v[8]; float s = 0.f;
; #pragma unroll
;         for (int j = 0; j < 8; ++j) { v[j] = xr[64 * j]; s += v[j].x * v[j].x + v[j].y * v[j].y + v[j].z * v[j].z + v[j].w * v[j].w; }
;         const float r = rsqrtf(wave_sum(s) * (1.f / D) + 1e-6f);
;         float4* o = (float4*)(out + (size_t)row * D) + lane;
; #pragma unroll
;         for (int j = 0; j < 8; ++j) { const float4 gg = ((const float4*)g)[lane + 64 * j]; float4 w; w.x = v[j].x * r * gg.x; w.y = v[j].y * r * gg.y; w.z = v[j].z * r * gg.z; w.w = v[j].w * r * gg.w; o[64 * j] = w; }
.LBB0_1123:
	s_or_b64 exec, exec, s[2:3]
	s_mov_b64 s[2:3], s[0:1]
	s_mov_b64 s[4:5], s[0:1]
	v_mov_b32_e32 v1, v222
	s_barrier
	s_movk_i32 s6, 0x4000
	v_ashrrev_i32_e32 v0, 6, v222
	v_add_u32_e32 v0, s85, v0
	v_cmp_gt_i32_e32 vcc, s6, v0
	s_and_saveexec_b64 s[6:7], vcc
	s_xor_b64 s[6:7], exec, s[6:7]
	s_cbranch_execz .LBB0_1126
	v_mbcnt_hi_u32_b32 v2, -1, v223
	v_and_b32_e32 v3, 64, v2
	v_add_u32_e32 v3, 64, v3
	v_xor_b32_e32 v4, 1, v2
	v_cmp_lt_i32_e32 vcc, v4, v3
	s_load_dwordx2 s[6:7], s[2:3], 0x118
	s_load_dwordx2 s[8:9], s[4:5], 0x110
	s_load_dwordx2 s[10:11], s[0:1], 0x118
	v_cndmask_b32_e32 v4, v2, v4, vcc
	v_lshlrev_b32_e32 v18, 2, v4
	v_xor_b32_e32 v4, 2, v2
	v_cmp_lt_i32_e32 vcc, v4, v3
	v_and_b32_e32 v1, 63, v1
	s_mov_b64 s[0:1], 0x1000
	v_cndmask_b32_e32 v4, v2, v4, vcc
	v_lshlrev_b32_e32 v19, 2, v4
	v_xor_b32_e32 v4, 4, v2
	v_cmp_lt_i32_e32 vcc, v4, v3
	s_ashr_i32 s87, s86, 31
	s_mov_b64 s[2:3], 0
	v_cndmask_b32_e32 v4, v2, v4, vcc
	v_lshlrev_b32_e32 v20, 2, v4
	v_xor_b32_e32 v4, 8, v2
	v_cmp_lt_i32_e32 vcc, v4, v3
	s_movk_i32 s4, 0x1000
	s_mov_b32 s5, 0x800000
	v_cndmask_b32_e32 v4, v2, v4, vcc
	v_lshlrev_b32_e32 v21, 2, v4
	v_xor_b32_e32 v4, 16, v2
	v_cmp_lt_i32_e32 vcc, v4, v3
	s_nop 1
	v_cndmask_b32_e32 v4, v2, v4, vcc
	v_lshlrev_b32_e32 v22, 2, v4
	v_xor_b32_e32 v4, 32, v2
	v_cmp_lt_i32_e32 vcc, v4, v3
	v_mov_b32_e32 v3, 0
	s_nop 0
	v_cndmask_b32_e32 v2, v2, v4, vcc
	v_lshlrev_b32_e32 v23, 2, v2
	v_lshlrev_b32_e32 v2, 4, v1
	s_waitcnt lgkmcnt(0)
	v_lshl_add_u64 v[4:5], s[8:9], 0, v[2:3]
	v_lshl_add_u64 v[6:7], v[4:5], 0, s[0:1]
	s_mov_b64 s[0:1], 0x1400
	v_lshl_add_u64 v[8:9], v[4:5], 0, s[0:1]
	s_mov_b64 s[0:1], 0x1800
	v_ashrrev_i32_e32 v1, 31, v0
	v_lshl_add_u64 v[10:11], v[4:5], 0, s[0:1]
	s_mov_b64 s[0:1], 0x1c00
	v_lshlrev_b64 v[16:17], 13, v[0:1]
	v_lshl_add_u64 v[12:13], v[4:5], 0, s[0:1]
	v_lshl_add_u64 v[14:15], s[6:7], 0, v[16:17]
	s_lshl_b64 s[0:1], s[86:87], 13
	v_lshl_add_u64 v[16:17], s[10:11], 0, v[16:17]
	v_mov_b32_e32 v1, 0x358637bd
	s_movk_i32 s6, 0x3fff
	global_load_dwordx4 v[100:103], v[4:5], off
	global_load_dwordx4 v[104:107], v[4:5], off offset:1024
	global_load_dwordx4 v[108:111], v[4:5], off offset:2048
	global_load_dwordx4 v[112:115], v[4:5], off offset:3072
	global_load_dwordx4 v[116:119], v[6:7], off
	global_load_dwordx4 v[120:123], v[8:9], off
	global_load_dwordx4 v[124:127], v[10:11], off
	global_load_dwordx4 v[128:131], v[12:13], off
	s_waitcnt vmcnt(0)
; __device__ __forceinline__ float wave_sum(float v) {
; #pragma unroll
;     for (int o = 1; o < 64; o <<= 1) v += __shfl_xor(v, o);
;     return v;
; __device__ __forceinline__ void final_norm_phase(const float* h, const float* g, float* out) {
;     ...
;     for (int row = gw; row < RL; row += ngw) {
;         const float4* xr = (const float4*)(h + (size_t)row * D) + lane;
;         float4 v[8]; float s = 0.f;
; #pragma unroll
;         for (int j = 0; j < 8; ++j) { v[j] = xr[64 * j]; s += v[j].x * v[j].x + v[j].y * v[j].y + v[j].z * v[j].z + v[j].w * v[j].w; }
;         const float r = rsqrtf(wave_sum(s) * (1.f / D) + 1e-6f);
;         float4* o = (float4*)(out + (size_t)row * D) + lane;
; #pragma unroll
;         for (int j = 0; j < 8; ++j) { const float4 gg = ((const float4*)g)[lane + 64 * j]; float4 w; w.x = v[j].x * r * gg.x; w.y = v[j].y * r * gg.y; w.z = v[j].z * r * gg.z; w.w = v[j].w * r * gg.w; o[64 * j] = w; }
.LBB0_1125:
	v_lshl_add_u64 v[40:41], v[14:15], 0, v[2:3]
	v_add_co_u32_e32 v56, vcc, s4, v40
	global_load_dwordx4 v[24:27], v[40:41], off
	global_load_dwordx4 v[28:31], v[40:41], off offset:1024
	global_load_dwordx4 v[32:35], v[40:41], off offset:2048
	global_load_dwordx4 v[36:39], v[40:41], off offset:3072
	v_addc_co_u32_e32 v57, vcc, 0, v41, vcc
	global_load_dwordx4 v[40:43], v[56:57], off
	global_load_dwordx4 v[44:47], v[56:57], off offset:1024
	global_load_dwordx4 v[48:51], v[56:57], off offset:2048
	global_load_dwordx4 v[52:55], v[56:57], off offset:3072
	v_lshl_add_u64 v[60:61], v[16:17], 0, v[2:3]
	v_add_u32_e32 v0, s86, v0
	v_lshl_add_u64 v[14:15], v[14:15], 0, s[0:1]
	v_lshl_add_u64 v[16:17], v[16:17], 0, s[0:1]
	s_waitcnt vmcnt(7)
	v_pk_mul_f32 v[62:63], v[24:25], v[24:25]
	s_waitcnt vmcnt(6)
	v_pk_mul_f32 v[66:67], v[28:29], v[28:29]
	v_pk_mul_f32 v[64:65], v[26:27], v[26:27]
	v_pk_mul_f32 v[68:69], v[30:31], v[30:31]
	s_waitcnt vmcnt(5)
	v_pk_mul_f32 v[70:71], v[32:33], v[32:33]
	s_waitcnt vmcnt(1)
	v_mov_b32_e32 v88, v49
	s_waitcnt vmcnt(0)
	v_mov_b32_e32 v89, v53
	v_add_f32_e32 v94, v66, v67
	v_add_f32_e32 v95, v62, v63
	v_pk_mul_f32 v[72:73], v[34:35], v[34:35]
	v_pk_mul_f32 v[74:75], v[36:37], v[36:37]
	v_mov_b32_e32 v80, v41
	v_mov_b32_e32 v81, v45
	v_mov_b32_e32 v86, v48
	v_mov_b32_e32 v87, v52
	v_add_f32_e32 v70, v70, v71
	v_pk_mul_f32 v[66:67], v[88:89], v[88:89]
	v_add_f32_e32 v68, v94, v68
	v_add_f32_e32 v64, v95, v64
	v_pk_mul_f32 v[76:77], v[38:39], v[38:39]
	v_mov_b32_e32 v78, v40
	v_mov_b32_e32 v79, v44
	v_mov_b32_e32 v90, v50
	v_mov_b32_e32 v91, v54
	v_add_f32_e32 v71, v74, v75
	v_pk_mul_f32 v[62:63], v[80:81], v[80:81]
	v_add_f32_e32 v70, v70, v72
	v_pk_fma_f32 v[66:67], v[86:87], v[86:87], v[66:67]
	v_add_f32_e32 v68, v68, v69
	v_add_f32_e32 v69, v64, v65
	v_mov_b32_e32 v82, v42
	v_mov_b32_e32 v83, v46
	v_add_f32_e32 v71, v71, v76
	v_pk_fma_f32 v[62:63], v[78:79], v[78:79], v[62:63]
	v_add_f32_e32 v70, v70, v73
	v_pk_fma_f32 v[64:65], v[90:91], v[90:91], v[66:67]
	v_add_f32_e32 v66, v69, v68
	v_mov_b32_e32 v84, v43
	v_mov_b32_e32 v85, v47
	v_add_f32_e32 v71, v71, v77
	v_pk_fma_f32 v[62:63], v[82:83], v[82:83], v[62:63]
	v_add_f32_e32 v66, v66, v70
	v_pk_fma_f32 v[62:63], v[84:85], v[84:85], v[62:63]
	v_add_f32_e32 v66, v66, v71
	v_mov_b32_e32 v92, v51
	v_mov_b32_e32 v93, v55
	v_add_f32_e32 v62, v66, v62
	v_pk_fma_f32 v[64:65], v[92:93], v[92:93], v[64:65]
	v_add_f32_e32 v62, v62, v63
	v_add_f32_e32 v62, v62, v64
	v_add_f32_e32 v62, v62, v65
	ds_bpermute_b32 v63, v18, v62
	s_waitcnt lgkmcnt(0)
	v_add_f32_e32 v62, v62, v63
	ds_bpermute_b32 v63, v19, v62
	s_waitcnt lgkmcnt(0)
	v_add_f32_e32 v62, v62, v63
	ds_bpermute_b32 v63, v20, v62
	s_waitcnt lgkmcnt(0)
	v_add_f32_e32 v62, v62, v63
	ds_bpermute_b32 v63, v21, v62
	s_waitcnt lgkmcnt(0)
	v_add_f32_e32 v62, v62, v63
	ds_bpermute_b32 v63, v22, v62
	s_waitcnt lgkmcnt(0)
	v_add_f32_e32 v62, v62, v63
	ds_bpermute_b32 v63, v23, v62
	s_waitcnt lgkmcnt(0)
	v_add_f32_e32 v62, v62, v63
	v_fmamk_f32 v62, v62, 0x3a000000, v1
	v_mul_f32_e32 v63, 0x4b800000, v62
	v_cmp_gt_f32_e32 vcc, s5, v62
	s_nop 1
	v_cndmask_b32_e32 v62, v62, v63, vcc
	v_rsq_f32_e32 v62, v62
	s_nop 0
	v_mul_f32_e32 v63, 0x45800000, v62
	v_cndmask_b32_e32 v62, v62, v63, vcc
	v_pk_mul_f32 v[24:25], v[24:25], v[62:63] op_sel_hi:[1,0]
	v_pk_mul_f32 v[26:27], v[26:27], v[62:63] op_sel_hi:[1,0]
	v_pk_mul_f32 v[24:25], v[100:101], v[24:25]
	v_pk_mul_f32 v[26:27], v[102:103], v[26:27]
	global_store_dwordx4 v[60:61], v[24:27], off
	s_nop 0
	v_pk_mul_f32 v[28:29], v[28:29], v[62:63] op_sel_hi:[1,0]
	v_pk_mul_f32 v[30:31], v[30:31], v[62:63] op_sel_hi:[1,0]
	v_pk_mul_f32 v[24:25], v[104:105], v[28:29]
	v_pk_mul_f32 v[26:27], v[106:107], v[30:31]
	global_store_dwordx4 v[60:61], v[24:27], off offset:1024
	s_nop 0
	v_pk_mul_f32 v[28:29], v[32:33], v[62:63] op_sel_hi:[1,0]
	v_pk_mul_f32 v[30:31], v[34:35], v[62:63] op_sel_hi:[1,0]
	v_pk_mul_f32 v[32:33], v[42:43], v[62:63] op_sel_hi:[1,0]
	v_pk_mul_f32 v[24:25], v[28:29], v[108:109]
	v_pk_mul_f32 v[26:27], v[30:31], v[110:111]
	global_store_dwordx4 v[60:61], v[24:27], off offset:2048
	s_nop 0
	v_pk_mul_f32 v[28:29], v[36:37], v[62:63] op_sel_hi:[1,0]
	v_pk_mul_f32 v[30:31], v[38:39], v[62:63] op_sel_hi:[1,0]
	v_pk_mul_f32 v[24:25], v[28:29], v[112:113]
	v_pk_mul_f32 v[26:27], v[30:31], v[114:115]
	global_store_dwordx4 v[60:61], v[24:27], off offset:3072
	s_nop 0
	v_add_co_u32_e32 v28, vcc, s4, v60
	v_pk_mul_f32 v[30:31], v[40:41], v[62:63] op_sel_hi:[1,0]
	s_nop 0
	v_addc_co_u32_e32 v29, vcc, 0, v61, vcc
	v_cmp_lt_i32_e32 vcc, s6, v0
	s_or_b64 s[2:3], vcc, s[2:3]
	v_pk_mul_f32 v[24:25], v[30:31], v[116:117]
	v_pk_mul_f32 v[26:27], v[32:33], v[118:119]
	global_store_dwordx4 v[28:29], v[24:27], off
	s_nop 0
	v_pk_mul_f32 v[30:31], v[44:45], v[62:63] op_sel_hi:[1,0]
	v_pk_mul_f32 v[32:33], v[46:47], v[62:63] op_sel_hi:[1,0]
	v_pk_mul_f32 v[24:25], v[30:31], v[120:121]
	v_pk_mul_f32 v[26:27], v[32:33], v[122:123]
	global_store_dwordx4 v[28:29], v[24:27], off offset:1024
	s_nop 0
	v_pk_mul_f32 v[30:31], v[48:49], v[62:63] op_sel_hi:[1,0]
	v_pk_mul_f32 v[32:33], v[50:51], v[62:63] op_sel_hi:[1,0]
	v_pk_mul_f32 v[24:25], v[30:31], v[124:125]
	v_pk_mul_f32 v[26:27], v[32:33], v[126:127]
	global_store_dwordx4 v[28:29], v[24:27], off offset:2048
	s_nop 0
	v_pk_mul_f32 v[30:31], v[52:53], v[62:63] op_sel_hi:[1,0]
	v_pk_mul_f32 v[32:33], v[54:55], v[62:63] op_sel_hi:[1,0]
	v_pk_mul_f32 v[24:25], v[30:31], v[128:129]
	v_pk_mul_f32 v[26:27], v[32:33], v[130:131]
	global_store_dwordx4 v[28:29], v[24:27], off offset:3072
	s_nop 0
	s_andn2_b64 exec, exec, s[2:3]
	s_cbranch_execnz .LBB0_1125
